# defer the w_o_a/w_o_b/w_out, w_ff1, w_ff2 transposes from P0 into the idle tails of the P1 / P3 / P4 GEMM phases (CUs without a unit in the last round), grid 256 only
# speedup vs baseline: 1.0109x; 1.0109x over previous
.LBB0_5:
	s_mov_b32 s99, 0
	s_or_b64 exec, exec, s[4:5]
	s_load_dwordx16 s[68:83], s[0:1], 0x40
	s_load_dwordx16 s[36:51], s[0:1], 0x80
	s_cmp_lt_i32 s30, 1
	s_cselect_b64 s[0:1], -1, 0
	s_cmp_gt_i32 s31, 0
	s_cselect_b64 s[4:5], -1, 0
	s_and_b64 s[0:1], s[0:1], s[4:5]
	s_andn2_b64 vcc, exec, s[0:1]
	s_cbranch_vccnz .LBB0_54
	s_movk_i32 s98, 0x3b7f
	s_cmpk_lg_i32 s22, 0x100
	s_cbranch_scc1 .Ltc_entry
	s_movk_i32 s98, 0x137f
.Ltc_entry:
	s_cmp_gt_i32 s2, s98
	s_cbranch_scc1 .LBB0_33
	v_lshlrev_b32_e32 v2, 1, v194
	v_and_b32_e32 v2, 62, v2
	v_mul_u32_u24_e32 v8, 0x104, v2
	v_lshlrev_b32_e32 v2, 1, v2
	v_mov_b32_e32 v3, 0
	v_lshrrev_b32_e32 v24, 5, v194
	v_lshl_add_u64 v[4:5], s[28:29], 0, v[2:3]
	s_mov_b64 s[6:7], 0x5700000
	v_lshl_add_u64 v[6:7], v[4:5], 0, s[6:7]
	v_lshlrev_b32_e32 v2, 2, v24
	s_mov_b64 s[6:7], 0x3700000
	v_add3_u32 v25, 0, v8, v2
	v_lshl_add_u64 v[8:9], v[4:5], 0, s[6:7]
	s_mov_b64 s[6:7], 0x2f00000
	v_lshrrev_b32_e32 v1, 6, v194
	v_and_b32_e32 v16, 63, v194
	v_lshl_add_u64 v[10:11], v[4:5], 0, s[6:7]
	s_mov_b64 s[6:7], 0x2b00000
	v_lshl_add_u32 v29, v16, 2, 0
	v_mul_u32_u24_e32 v30, 0x104, v1
	v_lshl_add_u64 v[12:13], v[4:5], 0, s[6:7]
	s_mov_b64 s[6:7], 0x2700000
	s_mov_b32 s5, 0
	v_add_u32_e32 v17, 8, v1
	v_or_b32_e32 v18, 16, v1
	v_add_u32_e32 v19, 24, v1
	v_or_b32_e32 v20, 32, v1
	v_add_u32_e32 v21, 40, v1
	v_or_b32_e32 v22, 48, v1
	v_add_u32_e32 v23, 56, v1
	v_add_u32_e32 v26, 16, v24
	v_or_b32_e32 v27, 32, v24
	v_add_u32_e32 v28, 48, v24
	v_lshl_add_u64 v[14:15], v[4:5], 0, s[6:7]
	s_lshl_b32 s3, s2, 6
	s_lshl_b32 s8, s22, 6
	s_lshl_b32 s9, s2, 1
	s_lshl_b32 s10, s22, 1
	s_lshl_b32 s11, s2, 2
	s_lshl_b32 s12, s22, 2
	v_add_u32_e32 v29, v29, v30
	s_movk_i32 s13, 0x1650
	s_movk_i32 s14, 0x2650
	s_mov_b32 s15, s2
	s_branch .LBB0_10

.LBB0_9:
	s_add_i32 s15, s15, s22
	s_add_i32 s3, s3, s8
	s_add_i32 s9, s9, s10
	s_add_i32 s11, s11, s12
	s_cmp_gt_i32 s15, s98
	s_waitcnt lgkmcnt(0)
	s_cbranch_scc1 .LBB0_33

.LBB0_33:
	s_cmp_eq_u32 s99, 0
	s_cbranch_scc1 .Ltc_cont
	s_cmp_eq_u32 s99, 1
	s_cbranch_scc1 .Ldef_1_ret
	s_cmp_eq_u32 s99, 2
	s_cbranch_scc1 .Ltramp_ret2
	s_branch .Ltramp_ret3

.LBB0_367:
	s_waitcnt vmcnt(0)
	v_readlane_b32 s10, v242, 4
	v_readlane_b32 s11, v242, 5
	s_barrier
	s_cmpk_lg_i32 s22, 0x100
	s_cbranch_scc1 .Ldef_1_skip
	s_cmpk_lt_u32 s2, 14
	s_cbranch_scc1 .Ldef_1_skip
	v_readlane_b32 s4, v242, 0
	v_readlane_b32 s5, v242, 1
	s_sub_u32 s4, s4, 0xe0
	s_subb_u32 s5, s5, 0
	v_writelane_b32 v255, s42, 0
	v_writelane_b32 v255, s43, 1
	v_writelane_b32 v255, s44, 2
	v_writelane_b32 v255, s45, 3
	v_writelane_b32 v255, s46, 4
	v_writelane_b32 v255, s47, 5
	s_load_dwordx2 s[42:43], s[4:5], 0x98
	s_load_dwordx2 s[44:45], s[4:5], 0xa0
	s_load_dwordx2 s[46:47], s[4:5], 0xa8
	s_waitcnt lgkmcnt(0)
	s_mov_b32 s100, s2
	s_mov_b32 s101, s22
	s_sub_i32 s2, s2, 14
	s_addk_i32 s2, 4992
	s_movk_i32 s22, 242
	s_movk_i32 s98, 7039
	s_mov_b32 s99, 1
	s_branch .Ltc_entry
.Ldef_1_ret:
	s_mov_b32 s2, s100
	s_mov_b32 s22, s101
	s_mov_b32 s99, 0
	s_nop 0
	v_readlane_b32 s42, v255, 0
	v_readlane_b32 s43, v255, 1
	v_readlane_b32 s44, v255, 2
	v_readlane_b32 s45, v255, 3
	v_readlane_b32 s46, v255, 4
	v_readlane_b32 s47, v255, 5
	v_readlane_b32 s10, v242, 4
	v_readlane_b32 s11, v242, 5
.Ldef_1_skip:
.LBB0_368:
	s_cmp_gt_i32 s31, 2
	s_cselect_b64 s[4:5], -1, 0
	s_and_b64 s[0:1], s[10:11], s[4:5]
	s_andn2_b64 vcc, exec, s[0:1]
	s_cbranch_vccnz .LBB0_422
	s_getreg_b32 s3, hwreg(HW_REG_XCC_ID, 0, 4)
	s_waitcnt vmcnt(0)
	s_waitcnt vmcnt(0) lgkmcnt(0)
	s_barrier
	s_mov_b64 s[0:1], exec
	v_readlane_b32 s6, v242, 2
	v_readlane_b32 s7, v242, 3
	s_and_b64 s[6:7], s[0:1], s[6:7]
	s_mov_b64 exec, s[6:7]
	s_cbranch_execz .LBB0_421
	s_add_i32 s6, 0, 0x23fc0
	v_mov_b32_e32 v0, s6
	s_waitcnt vmcnt(0) expcnt(0) lgkmcnt(0)
	ds_read_b32 v2, v0
	s_add_i32 s6, 0, 0x23fc4
	v_mov_b32_e32 v0, s6
	ds_read_b32 v0, v0
	s_and_b32 s3, s3, 15
	s_waitcnt lgkmcnt(1)
	v_cmp_ne_u32_e32 vcc, 0, v2
	s_cbranch_vccnz .LBB0_385
	v_readlane_b32 s6, v242, 0
	v_readlane_b32 s7, v242, 1
	s_load_dwordx2 s[10:11], s[6:7], 0x4
	s_add_u32 s6, s28, 0x1d418200
	s_addc_u32 s7, s29, 0
	s_add_u32 s8, s28, 0x1d418400
	s_addc_u32 s9, s29, 0
	s_waitcnt lgkmcnt(0)
	s_mul_i32 s23, s10, s22
	s_add_u32 s10, s28, 0x1d418500
	s_mul_i32 s23, s23, s11
	s_addc_u32 s11, s29, 0
	s_add_u32 s12, s28, 0x1d418600
	s_addc_u32 s13, s29, 0
	s_add_u32 s14, s28, 0x1d418700
	s_addc_u32 s15, s29, 0
	s_add_u32 s16, s28, 0x1d418800
	s_addc_u32 s17, s29, 0
	s_add_u32 s18, s28, 0x1d418900
	s_addc_u32 s19, s29, 0
	s_add_u32 s20, s28, 0x1d418a00
	s_addc_u32 s21, s29, 0
	s_add_u32 s24, s28, 0x1d418b00
	s_addc_u32 s25, s29, 0
	s_add_u32 s34, s28, 0x1d418c00
	s_addc_u32 s35, s29, 0
	s_add_u32 s38, s28, 0x1d418d00
	s_addc_u32 s39, s29, 0
	s_add_u32 s40, s28, 0x1d418e00
	s_addc_u32 s41, s29, 0
	s_add_u32 s42, s28, 0x1d418f00
	s_addc_u32 s43, s29, 0
	s_add_u32 s44, s28, 0x1d419000
	s_addc_u32 s45, s29, 0
	s_add_u32 s46, s28, 0x1d419100
	s_addc_u32 s47, s29, 0
	s_add_u32 s50, s28, 0x1d419200
	s_addc_u32 s51, s29, 0
	s_add_u32 s56, s28, 0x1d419300
	s_addc_u32 s57, s29, 0
	s_mov_b32 s33, 1
	v_mov_b32_e32 v16, 0
	s_branch .LBB0_373

.LBB0_532:
	v_mov_b32_e32 v129, v194
	v_readfirstlane_b32 s83, v194
	v_and_b32_e32 v180, 31, v194
	v_bfe_u32 v131, v194, 5, 1
	v_and_b32_e32 v243, 63, v194
	s_ashr_i32 s84, s83, 6
	s_lshl_b32 s0, s84, 5
	v_or_b32_e32 v130, s0, v180
	v_lshlrev_b32_e32 v243, 2, v243
	s_lshl_b32 s0, s2, 17
	s_lshl_b32 s1, s84, 8
	s_add_u32 s0, s0, s1
	s_add_u32 s8, s28, s0
	s_addc_u32 s9, s29, 0
	s_lshl_b32 s21, s84, 12
	s_cmp_lg_u32 s82, 0
	s_cbranch_scc1 .Lix_reload
	v_bfe_u32 v0, v194, 2, 1
	v_lshrrev_b32_e32 v1, 1, v194
	v_and_b32_e32 v1, 12, v1
	v_and_b32_e32 v228, 3, v194
	v_or_b32_e32 v1, v1, v228
	v_add_u32_e32 v0, s34, v0
	v_lshlrev_b32_e32 v0, 11, v0
	v_lshl_add_u32 v0, v1, 7, v0
	v_lshl_add_u32 v0, v131, 4, v0
	v_add_u32_e32 v1, 0x1000, v0
	global_load_dwordx4 v[70:73], v0, s[36:37]
	global_load_dwordx4 v[74:77], v0, s[36:37] offset:32
	global_load_dwordx4 v[78:81], v0, s[36:37] offset:64
	global_load_dwordx4 v[82:85], v0, s[36:37] offset:96
	global_load_dwordx4 v[86:89], v1, s[36:37]
	global_load_dwordx4 v[90:93], v1, s[36:37] offset:32
	global_load_dwordx4 v[94:97], v1, s[36:37] offset:64
	global_load_dwordx4 v[98:101], v1, s[36:37] offset:96
	v_add_u32_e32 v228, s34, v131
	v_lshlrev_b32_e32 v228, 6, v228
	global_load_dwordx4 v[22:25], v228, s[38:39]
	global_load_dwordx4 v[26:29], v228, s[38:39] offset:16
	global_load_dwordx4 v[30:33], v228, s[38:39] offset:32
	global_load_dwordx4 v[34:37], v228, s[38:39] offset:48
	global_load_dwordx2 v[244:245], v228, s[38:39] offset:128
	global_load_dwordx2 v[246:247], v228, s[38:39] offset:136
	global_load_dwordx2 v[248:249], v228, s[38:39] offset:144
	global_load_dwordx2 v[250:251], v228, s[38:39] offset:152
	global_load_dwordx2 v[252:253], v228, s[38:39] offset:160
	global_load_dwordx2 v[254:255], v228, s[38:39] offset:168
	global_load_dwordx2 v[200:201], v228, s[38:39] offset:176
	global_load_dwordx2 v[202:203], v228, s[38:39] offset:184
	v_lshrrev_b32_e32 v0, 2, v243
	v_lshrrev_b32_e32 v1, 3, v0
	v_lshrrev_b32_e32 v228, 4, v0
	v_and_b32_e32 v229, 7, v0
	v_xor_b32_e32 v228, v229, v228
	v_xor_b32_e32 v229, 4, v228
	s_lshl_b32 s0, s84, 12
	v_lshl_add_u32 v1, v1, 7, s0
	v_lshl_add_u32 v102, v228, 4, v1
	v_lshl_add_u32 v110, v229, 4, v1
	v_add_u32_e32 v110, 0x400, v110
	v_add_u32_e32 v112, 0x800, v102
	v_add_u32_e32 v193, 0x800, v110
	v_lshlrev_b32_e32 v0, 7, v130
	v_bfe_u32 v1, v180, 1, 3
	v_or_b32_e32 v228, 0, v131
	v_xor_b32_e32 v228, v228, v1
	v_lshl_add_u32 v5, v228, 4, v0
	v_or_b32_e32 v228, 2, v131
	v_xor_b32_e32 v228, v228, v1
	v_lshl_add_u32 v52, v228, 4, v0
	v_or_b32_e32 v228, 4, v131
	v_xor_b32_e32 v228, v228, v1
	v_lshl_add_u32 v55, v228, 4, v0
	v_or_b32_e32 v228, 6, v131
	v_xor_b32_e32 v228, v228, v1
	v_lshl_add_u32 v56, v228, 4, v0
	s_mov_b32 s6, s14
	s_mov_b32 s7, s15
	s_add_i32 s10, s0, 10496
	s_sub_i32 s11, s35, s84
	s_add_i32 m0, s10, 0
	s_nop 0
	global_load_lds_dwordx4 v102, s[6:7]
	s_add_i32 m0, s10, 1024
	s_nop 0
	global_load_lds_dwordx4 v110, s[6:7]
	s_add_i32 m0, s10, 2048
	s_nop 0
	global_load_lds_dwordx4 v112, s[6:7]
	s_add_i32 m0, s10, 3072
	s_nop 0
	global_load_lds_dwordx4 v193, s[6:7]
	s_add_u32 s6, s6, 0x8000
	s_addc_u32 s7, s7, 0
	s_add_i32 m0, s10, 32768
	s_nop 0
	global_load_lds_dwordx4 v102, s[6:7]
	s_add_i32 m0, s10, 33792
	s_nop 0
	global_load_lds_dwordx4 v110, s[6:7]
	s_add_i32 m0, s10, 34816
	s_nop 0
	global_load_lds_dwordx4 v112, s[6:7]
	s_add_i32 m0, s10, 35840
	s_nop 0
	global_load_lds_dwordx4 v193, s[6:7]
	s_add_u32 s6, s6, 0x8000
	s_addc_u32 s7, s7, 0
	s_add_i32 m0, s10, 65536
	s_nop 0
	global_load_lds_dwordx4 v102, s[6:7]
	s_add_i32 m0, s10, 66560
	s_nop 0
	global_load_lds_dwordx4 v110, s[6:7]
	s_add_i32 m0, s10, 67584
	s_nop 0
	global_load_lds_dwordx4 v112, s[6:7]
	s_add_i32 m0, s10, 68608
	s_nop 0
	global_load_lds_dwordx4 v193, s[6:7]
	s_add_u32 s6, s6, 0x8000
	s_addc_u32 s7, s7, 0
	s_waitcnt vmcnt(8)
	ds_read_b128 v[38:41], v5 offset:10496
	ds_read_b128 v[42:45], v52 offset:10496
	ds_read_b128 v[46:49], v55 offset:10496
	ds_read_b128 v[196:199], v56 offset:10496
	s_waitcnt lgkmcnt(3)
	v_mfma_f32_32x32x16_bf16 v[212:227], v[70:73], v[38:41], 0
	s_add_i32 m0, s10, 98304
	s_nop 0
	global_load_lds_dwordx4 v102, s[6:7]
	s_waitcnt lgkmcnt(2)
	v_mfma_f32_32x32x16_bf16 v[212:227], v[74:77], v[42:45], v[212:227]
	s_add_i32 m0, s10, 99328
	s_nop 0
	global_load_lds_dwordx4 v110, s[6:7]
	s_waitcnt lgkmcnt(1)
	v_mfma_f32_32x32x16_bf16 v[212:227], v[78:81], v[46:49], v[212:227]
	s_add_i32 m0, s10, 100352
	s_nop 0
	global_load_lds_dwordx4 v112, s[6:7]
	s_waitcnt lgkmcnt(0)
	v_mfma_f32_32x32x16_bf16 v[212:227], v[82:85], v[196:199], v[212:227]
	s_add_i32 m0, s10, 101376
	s_nop 0
	global_load_lds_dwordx4 v193, s[6:7]
	s_add_u32 s6, s6, 0x8000
	s_addc_u32 s7, s7, 0
	v_mfma_f32_32x32x16_bf16 v[6:21], v[86:89], v[38:41], 0
	s_nop 7
	s_nop 2
	v_max_f32_e32 v108, 0, v212
	v_max_f32_e32 v109, 0, v213
	v_pk_mul_f32 v[0:1], v[22:23], v[108:109]
	v_max_f32_e32 v210, 0, v214
	v_max_f32_e32 v211, 0, v215
	v_pk_fma_f32 v[0:1], v[24:25], v[210:211], v[0:1]
	v_max_f32_e32 v108, 0, v216
	v_max_f32_e32 v109, 0, v217
	v_pk_fma_f32 v[0:1], v[26:27], v[108:109], v[0:1]
	v_mfma_f32_32x32x16_bf16 v[6:21], v[90:93], v[42:45], v[6:21]
	v_max_f32_e32 v210, 0, v218
	v_max_f32_e32 v211, 0, v219
	v_pk_fma_f32 v[0:1], v[28:29], v[210:211], v[0:1]
	v_max_f32_e32 v108, 0, v220
	v_max_f32_e32 v109, 0, v221
	v_pk_fma_f32 v[0:1], v[30:31], v[108:109], v[0:1]
	v_max_f32_e32 v210, 0, v222
	v_max_f32_e32 v211, 0, v223
	v_pk_fma_f32 v[0:1], v[32:33], v[210:211], v[0:1]
	v_mfma_f32_32x32x16_bf16 v[6:21], v[94:97], v[46:49], v[6:21]
	v_max_f32_e32 v108, 0, v224
	v_max_f32_e32 v109, 0, v225
	v_pk_fma_f32 v[0:1], v[34:35], v[108:109], v[0:1]
	v_max_f32_e32 v210, 0, v226
	v_max_f32_e32 v211, 0, v227
	v_pk_fma_f32 v[0:1], v[36:37], v[210:211], v[0:1]
	v_add_f32_e32 v0, v0, v1
	v_ashrrev_i32_e32 v1, 31, v0
	v_mfma_f32_32x32x16_bf16 v[6:21], v[98:101], v[196:199], v[6:21]
	s_waitcnt vmcnt(8)
	ds_read_b128 v[38:41], v5 offset:43264
	ds_read_b128 v[42:45], v52 offset:43264
	ds_read_b128 v[46:49], v55 offset:43264
	ds_read_b128 v[196:199], v56 offset:43264
	v_or_b32_e32 v1, 0x80000000, v1
	s_cmpk_gt_i32 s11, 0
	s_cselect_b64 vcc, -1, 0
	v_xor_b32_e32 v0, v1, v0
	v_cndmask_b32_e32 v133, v123, v0, vcc
	s_nop 3
	s_waitcnt lgkmcnt(3)
	v_mfma_f32_32x32x16_bf16 v[212:227], v[70:73], v[38:41], 0
	v_max_f32_e32 v108, 0, v6
	v_max_f32_e32 v109, 0, v7
	v_pk_mul_f32 v[50:51], v[244:245], v[108:109]
	v_max_f32_e32 v210, 0, v8
	v_max_f32_e32 v211, 0, v9
	v_pk_fma_f32 v[50:51], v[246:247], v[210:211], v[50:51]
	v_max_f32_e32 v108, 0, v10
	v_max_f32_e32 v109, 0, v11
	v_pk_fma_f32 v[50:51], v[248:249], v[108:109], v[50:51]
	s_waitcnt lgkmcnt(2)
	v_mfma_f32_32x32x16_bf16 v[212:227], v[74:77], v[42:45], v[212:227]
	v_max_f32_e32 v210, 0, v12
	v_max_f32_e32 v211, 0, v13
	v_pk_fma_f32 v[50:51], v[250:251], v[210:211], v[50:51]
	v_max_f32_e32 v108, 0, v14
	v_max_f32_e32 v109, 0, v15
	v_pk_fma_f32 v[50:51], v[252:253], v[108:109], v[50:51]
	v_max_f32_e32 v210, 0, v16
	v_max_f32_e32 v211, 0, v17
	v_pk_fma_f32 v[50:51], v[254:255], v[210:211], v[50:51]
	s_waitcnt lgkmcnt(1)
	v_mfma_f32_32x32x16_bf16 v[212:227], v[78:81], v[46:49], v[212:227]
	v_max_f32_e32 v108, 0, v18
	v_max_f32_e32 v109, 0, v19
	v_pk_fma_f32 v[50:51], v[200:201], v[108:109], v[50:51]
	v_max_f32_e32 v210, 0, v20
	v_max_f32_e32 v211, 0, v21
	v_pk_fma_f32 v[50:51], v[202:203], v[210:211], v[50:51]
	v_add_f32_e32 v50, v50, v51
	v_ashrrev_i32_e32 v51, 31, v50
	s_waitcnt lgkmcnt(0)
	v_mfma_f32_32x32x16_bf16 v[212:227], v[82:85], v[196:199], v[212:227]
	v_or_b32_e32 v51, 0x80000000, v51
	s_cmpk_gt_i32 s11, 0
	s_cselect_b64 vcc, -1, 0
	v_xor_b32_e32 v50, v51, v50
	v_cndmask_b32_e32 v50, v123, v50, vcc
	global_store_dword v243, v50, s[8:9]
	v_mfma_f32_32x32x16_bf16 v[6:21], v[86:89], v[38:41], 0
	s_add_i32 m0, s10, 0
	s_nop 0
	global_load_lds_dwordx4 v102, s[6:7]
	s_add_i32 m0, s10, 1024
	s_nop 0
	global_load_lds_dwordx4 v110, s[6:7]
	s_add_i32 m0, s10, 2048
	s_nop 0
	global_load_lds_dwordx4 v112, s[6:7]
	s_add_i32 m0, s10, 3072
	s_nop 0
	global_load_lds_dwordx4 v193, s[6:7]
	s_add_u32 s6, s6, 0x8000
	s_addc_u32 s7, s7, 0
	v_max_f32_e32 v108, 0, v212
	v_max_f32_e32 v109, 0, v213
	v_pk_mul_f32 v[0:1], v[22:23], v[108:109]
	v_max_f32_e32 v210, 0, v214
	v_max_f32_e32 v211, 0, v215
	v_pk_fma_f32 v[0:1], v[24:25], v[210:211], v[0:1]
	v_max_f32_e32 v108, 0, v216
	v_max_f32_e32 v109, 0, v217
	v_pk_fma_f32 v[0:1], v[26:27], v[108:109], v[0:1]
	v_mfma_f32_32x32x16_bf16 v[6:21], v[90:93], v[42:45], v[6:21]
	v_max_f32_e32 v210, 0, v218
	v_max_f32_e32 v211, 0, v219
	v_pk_fma_f32 v[0:1], v[28:29], v[210:211], v[0:1]
	v_max_f32_e32 v108, 0, v220
	v_max_f32_e32 v109, 0, v221
	v_pk_fma_f32 v[0:1], v[30:31], v[108:109], v[0:1]
	v_max_f32_e32 v210, 0, v222
	v_max_f32_e32 v211, 0, v223
	v_pk_fma_f32 v[0:1], v[32:33], v[210:211], v[0:1]
	v_mfma_f32_32x32x16_bf16 v[6:21], v[94:97], v[46:49], v[6:21]
	v_max_f32_e32 v108, 0, v224
	v_max_f32_e32 v109, 0, v225
	v_pk_fma_f32 v[0:1], v[34:35], v[108:109], v[0:1]
	v_max_f32_e32 v210, 0, v226
	v_max_f32_e32 v211, 0, v227
	v_pk_fma_f32 v[0:1], v[36:37], v[210:211], v[0:1]
	v_add_f32_e32 v0, v0, v1
	v_ashrrev_i32_e32 v1, 31, v0
	v_mfma_f32_32x32x16_bf16 v[6:21], v[98:101], v[196:199], v[6:21]
	s_waitcnt vmcnt(9)
	v_add_u32_e32 v228, 0x10000, v5
	ds_read_b128 v[38:41], v228 offset:10496
	v_add_u32_e32 v228, 0x10000, v52
	ds_read_b128 v[42:45], v228 offset:10496
	v_add_u32_e32 v228, 0x10000, v55
	ds_read_b128 v[46:49], v228 offset:10496
	v_add_u32_e32 v228, 0x10000, v56
	ds_read_b128 v[196:199], v228 offset:10496
	v_or_b32_e32 v1, 0x80000000, v1
	s_cmpk_gt_i32 s11, 8
	s_cselect_b64 vcc, -1, 0
	v_xor_b32_e32 v0, v1, v0
	v_cndmask_b32_e32 v132, v123, v0, vcc
	s_nop 3
	s_waitcnt lgkmcnt(3)
	v_mfma_f32_32x32x16_bf16 v[212:227], v[70:73], v[38:41], 0
	v_max_f32_e32 v108, 0, v6
	v_max_f32_e32 v109, 0, v7
	v_pk_mul_f32 v[50:51], v[244:245], v[108:109]
	v_max_f32_e32 v210, 0, v8
	v_max_f32_e32 v211, 0, v9
	v_pk_fma_f32 v[50:51], v[246:247], v[210:211], v[50:51]
	v_max_f32_e32 v108, 0, v10
	v_max_f32_e32 v109, 0, v11
	v_pk_fma_f32 v[50:51], v[248:249], v[108:109], v[50:51]
	s_waitcnt lgkmcnt(2)
	v_mfma_f32_32x32x16_bf16 v[212:227], v[74:77], v[42:45], v[212:227]
	v_max_f32_e32 v210, 0, v12
	v_max_f32_e32 v211, 0, v13
	v_pk_fma_f32 v[50:51], v[250:251], v[210:211], v[50:51]
	v_max_f32_e32 v108, 0, v14
	v_max_f32_e32 v109, 0, v15
	v_pk_fma_f32 v[50:51], v[252:253], v[108:109], v[50:51]
	v_max_f32_e32 v210, 0, v16
	v_max_f32_e32 v211, 0, v17
	v_pk_fma_f32 v[50:51], v[254:255], v[210:211], v[50:51]
	s_waitcnt lgkmcnt(1)
	v_mfma_f32_32x32x16_bf16 v[212:227], v[78:81], v[46:49], v[212:227]
	v_max_f32_e32 v108, 0, v18
	v_max_f32_e32 v109, 0, v19
	v_pk_fma_f32 v[50:51], v[200:201], v[108:109], v[50:51]
	v_max_f32_e32 v210, 0, v20
	v_max_f32_e32 v211, 0, v21
	v_pk_fma_f32 v[50:51], v[202:203], v[210:211], v[50:51]
	v_add_f32_e32 v50, v50, v51
	v_ashrrev_i32_e32 v51, 31, v50
	s_waitcnt lgkmcnt(0)
	v_mfma_f32_32x32x16_bf16 v[212:227], v[82:85], v[196:199], v[212:227]
	v_or_b32_e32 v51, 0x80000000, v51
	s_cmpk_gt_i32 s11, 8
	s_cselect_b64 vcc, -1, 0
	v_xor_b32_e32 v50, v51, v50
	v_cndmask_b32_e32 v50, v123, v50, vcc
	global_store_dword v243, v50, s[8:9] offset:2048
	s_add_u32 s8, s8, 0x1000
	s_addc_u32 s9, s9, 0
	v_mfma_f32_32x32x16_bf16 v[6:21], v[86:89], v[38:41], 0
	s_add_i32 m0, s10, 32768
	s_nop 0
	global_load_lds_dwordx4 v102, s[6:7]
	s_add_i32 m0, s10, 33792
	s_nop 0
	global_load_lds_dwordx4 v110, s[6:7]
	s_add_i32 m0, s10, 34816
	s_nop 0
	global_load_lds_dwordx4 v112, s[6:7]
	s_add_i32 m0, s10, 35840
	s_nop 0
	global_load_lds_dwordx4 v193, s[6:7]
	s_add_u32 s6, s6, 0x8000
	s_addc_u32 s7, s7, 0
	v_max_f32_e32 v108, 0, v212
	v_max_f32_e32 v109, 0, v213
	v_pk_mul_f32 v[0:1], v[22:23], v[108:109]
	v_max_f32_e32 v210, 0, v214
	v_max_f32_e32 v211, 0, v215
	v_pk_fma_f32 v[0:1], v[24:25], v[210:211], v[0:1]
	v_max_f32_e32 v108, 0, v216
	v_max_f32_e32 v109, 0, v217
	v_pk_fma_f32 v[0:1], v[26:27], v[108:109], v[0:1]
	v_mfma_f32_32x32x16_bf16 v[6:21], v[90:93], v[42:45], v[6:21]
	v_max_f32_e32 v210, 0, v218
	v_max_f32_e32 v211, 0, v219
	v_pk_fma_f32 v[0:1], v[28:29], v[210:211], v[0:1]
	v_max_f32_e32 v108, 0, v220
	v_max_f32_e32 v109, 0, v221
	v_pk_fma_f32 v[0:1], v[30:31], v[108:109], v[0:1]
	v_max_f32_e32 v210, 0, v222
	v_max_f32_e32 v211, 0, v223
	v_pk_fma_f32 v[0:1], v[32:33], v[210:211], v[0:1]
	v_mfma_f32_32x32x16_bf16 v[6:21], v[94:97], v[46:49], v[6:21]
	v_max_f32_e32 v108, 0, v224
	v_max_f32_e32 v109, 0, v225
	v_pk_fma_f32 v[0:1], v[34:35], v[108:109], v[0:1]
	v_max_f32_e32 v210, 0, v226
	v_max_f32_e32 v211, 0, v227
	v_pk_fma_f32 v[0:1], v[36:37], v[210:211], v[0:1]
	v_add_f32_e32 v0, v0, v1
	v_ashrrev_i32_e32 v1, 31, v0
	v_mfma_f32_32x32x16_bf16 v[6:21], v[98:101], v[196:199], v[6:21]
	s_waitcnt vmcnt(10)
	v_add_u32_e32 v228, 0x10000, v5
	ds_read_b128 v[38:41], v228 offset:43264
	v_add_u32_e32 v228, 0x10000, v52
	ds_read_b128 v[42:45], v228 offset:43264
	v_add_u32_e32 v228, 0x10000, v55
	ds_read_b128 v[46:49], v228 offset:43264
	v_add_u32_e32 v228, 0x10000, v56
	ds_read_b128 v[196:199], v228 offset:43264
	v_or_b32_e32 v1, 0x80000000, v1
	s_cmpk_gt_i32 s11, 16
	s_cselect_b64 vcc, -1, 0
	v_xor_b32_e32 v0, v1, v0
	v_cndmask_b32_e32 v135, v123, v0, vcc
	s_nop 3
	s_waitcnt lgkmcnt(3)
	v_mfma_f32_32x32x16_bf16 v[212:227], v[70:73], v[38:41], 0
	v_max_f32_e32 v108, 0, v6
	v_max_f32_e32 v109, 0, v7
	v_pk_mul_f32 v[50:51], v[244:245], v[108:109]
	v_max_f32_e32 v210, 0, v8
	v_max_f32_e32 v211, 0, v9
	v_pk_fma_f32 v[50:51], v[246:247], v[210:211], v[50:51]
	v_max_f32_e32 v108, 0, v10
	v_max_f32_e32 v109, 0, v11
	v_pk_fma_f32 v[50:51], v[248:249], v[108:109], v[50:51]
	s_waitcnt lgkmcnt(2)
	v_mfma_f32_32x32x16_bf16 v[212:227], v[74:77], v[42:45], v[212:227]
	v_max_f32_e32 v210, 0, v12
	v_max_f32_e32 v211, 0, v13
	v_pk_fma_f32 v[50:51], v[250:251], v[210:211], v[50:51]
	v_max_f32_e32 v108, 0, v14
	v_max_f32_e32 v109, 0, v15
	v_pk_fma_f32 v[50:51], v[252:253], v[108:109], v[50:51]
	v_max_f32_e32 v210, 0, v16
	v_max_f32_e32 v211, 0, v17
	v_pk_fma_f32 v[50:51], v[254:255], v[210:211], v[50:51]
	s_waitcnt lgkmcnt(1)
	v_mfma_f32_32x32x16_bf16 v[212:227], v[78:81], v[46:49], v[212:227]
	v_max_f32_e32 v108, 0, v18
	v_max_f32_e32 v109, 0, v19
	v_pk_fma_f32 v[50:51], v[200:201], v[108:109], v[50:51]
	v_max_f32_e32 v210, 0, v20
	v_max_f32_e32 v211, 0, v21
	v_pk_fma_f32 v[50:51], v[202:203], v[210:211], v[50:51]
	v_add_f32_e32 v50, v50, v51
	v_ashrrev_i32_e32 v51, 31, v50
	s_waitcnt lgkmcnt(0)
	v_mfma_f32_32x32x16_bf16 v[212:227], v[82:85], v[196:199], v[212:227]
	v_or_b32_e32 v51, 0x80000000, v51
	s_cmpk_gt_i32 s11, 16
	s_cselect_b64 vcc, -1, 0
	v_xor_b32_e32 v50, v51, v50
	v_cndmask_b32_e32 v50, v123, v50, vcc
	global_store_dword v243, v50, s[8:9]
	v_mfma_f32_32x32x16_bf16 v[6:21], v[86:89], v[38:41], 0
	s_add_i32 m0, s10, 65536
	s_nop 0
	global_load_lds_dwordx4 v102, s[6:7]
	s_add_i32 m0, s10, 66560
	s_nop 0
	global_load_lds_dwordx4 v110, s[6:7]
	s_add_i32 m0, s10, 67584
	s_nop 0
	global_load_lds_dwordx4 v112, s[6:7]
	s_add_i32 m0, s10, 68608
	s_nop 0
	global_load_lds_dwordx4 v193, s[6:7]
	s_add_u32 s6, s6, 0x8000
	s_addc_u32 s7, s7, 0
	v_max_f32_e32 v108, 0, v212
	v_max_f32_e32 v109, 0, v213
	v_pk_mul_f32 v[0:1], v[22:23], v[108:109]
	v_max_f32_e32 v210, 0, v214
	v_max_f32_e32 v211, 0, v215
	v_pk_fma_f32 v[0:1], v[24:25], v[210:211], v[0:1]
	v_max_f32_e32 v108, 0, v216
	v_max_f32_e32 v109, 0, v217
	v_pk_fma_f32 v[0:1], v[26:27], v[108:109], v[0:1]
	v_mfma_f32_32x32x16_bf16 v[6:21], v[90:93], v[42:45], v[6:21]
	v_max_f32_e32 v210, 0, v218
	v_max_f32_e32 v211, 0, v219
	v_pk_fma_f32 v[0:1], v[28:29], v[210:211], v[0:1]
	v_max_f32_e32 v108, 0, v220
	v_max_f32_e32 v109, 0, v221
	v_pk_fma_f32 v[0:1], v[30:31], v[108:109], v[0:1]
	v_max_f32_e32 v210, 0, v222
	v_max_f32_e32 v211, 0, v223
	v_pk_fma_f32 v[0:1], v[32:33], v[210:211], v[0:1]
	v_mfma_f32_32x32x16_bf16 v[6:21], v[94:97], v[46:49], v[6:21]
	v_max_f32_e32 v108, 0, v224
	v_max_f32_e32 v109, 0, v225
	v_pk_fma_f32 v[0:1], v[34:35], v[108:109], v[0:1]
	v_max_f32_e32 v210, 0, v226
	v_max_f32_e32 v211, 0, v227
	v_pk_fma_f32 v[0:1], v[36:37], v[210:211], v[0:1]
	v_add_f32_e32 v0, v0, v1
	v_ashrrev_i32_e32 v1, 31, v0
	v_mfma_f32_32x32x16_bf16 v[6:21], v[98:101], v[196:199], v[6:21]
	s_waitcnt vmcnt(10)
	ds_read_b128 v[38:41], v5 offset:10496
	ds_read_b128 v[42:45], v52 offset:10496
	ds_read_b128 v[46:49], v55 offset:10496
	ds_read_b128 v[196:199], v56 offset:10496
	v_or_b32_e32 v1, 0x80000000, v1
	s_cmpk_gt_i32 s11, 24
	s_cselect_b64 vcc, -1, 0
	v_xor_b32_e32 v0, v1, v0
	v_cndmask_b32_e32 v134, v123, v0, vcc
	s_nop 3
	s_waitcnt lgkmcnt(3)
	v_mfma_f32_32x32x16_bf16 v[212:227], v[70:73], v[38:41], 0
	v_max_f32_e32 v108, 0, v6
	v_max_f32_e32 v109, 0, v7
	v_pk_mul_f32 v[50:51], v[244:245], v[108:109]
	v_max_f32_e32 v210, 0, v8
	v_max_f32_e32 v211, 0, v9
	v_pk_fma_f32 v[50:51], v[246:247], v[210:211], v[50:51]
	v_max_f32_e32 v108, 0, v10
	v_max_f32_e32 v109, 0, v11
	v_pk_fma_f32 v[50:51], v[248:249], v[108:109], v[50:51]
	s_waitcnt lgkmcnt(2)
	v_mfma_f32_32x32x16_bf16 v[212:227], v[74:77], v[42:45], v[212:227]
	v_max_f32_e32 v210, 0, v12
	v_max_f32_e32 v211, 0, v13
	v_pk_fma_f32 v[50:51], v[250:251], v[210:211], v[50:51]
	v_max_f32_e32 v108, 0, v14
	v_max_f32_e32 v109, 0, v15
	v_pk_fma_f32 v[50:51], v[252:253], v[108:109], v[50:51]
	v_max_f32_e32 v210, 0, v16
	v_max_f32_e32 v211, 0, v17
	v_pk_fma_f32 v[50:51], v[254:255], v[210:211], v[50:51]
	s_waitcnt lgkmcnt(1)
	v_mfma_f32_32x32x16_bf16 v[212:227], v[78:81], v[46:49], v[212:227]
	v_max_f32_e32 v108, 0, v18
	v_max_f32_e32 v109, 0, v19
	v_pk_fma_f32 v[50:51], v[200:201], v[108:109], v[50:51]
	v_max_f32_e32 v210, 0, v20
	v_max_f32_e32 v211, 0, v21
	v_pk_fma_f32 v[50:51], v[202:203], v[210:211], v[50:51]
	v_add_f32_e32 v50, v50, v51
	v_ashrrev_i32_e32 v51, 31, v50
	s_waitcnt lgkmcnt(0)
	v_mfma_f32_32x32x16_bf16 v[212:227], v[82:85], v[196:199], v[212:227]
	v_or_b32_e32 v51, 0x80000000, v51
	s_cmpk_gt_i32 s11, 24
	s_cselect_b64 vcc, -1, 0
	v_xor_b32_e32 v50, v51, v50
	v_cndmask_b32_e32 v50, v123, v50, vcc
	global_store_dword v243, v50, s[8:9] offset:2048
	s_add_u32 s8, s8, 0x1000
	s_addc_u32 s9, s9, 0
	v_mfma_f32_32x32x16_bf16 v[6:21], v[86:89], v[38:41], 0
	s_add_i32 m0, s10, 98304
	s_nop 0
	global_load_lds_dwordx4 v102, s[6:7]
	s_add_i32 m0, s10, 99328
	s_nop 0
	global_load_lds_dwordx4 v110, s[6:7]
	s_add_i32 m0, s10, 100352
	s_nop 0
	global_load_lds_dwordx4 v112, s[6:7]
	s_add_i32 m0, s10, 101376
	s_nop 0
	global_load_lds_dwordx4 v193, s[6:7]
	s_add_u32 s6, s6, 0x8000
	s_addc_u32 s7, s7, 0
	v_max_f32_e32 v108, 0, v212
	v_max_f32_e32 v109, 0, v213
	v_pk_mul_f32 v[0:1], v[22:23], v[108:109]
	v_max_f32_e32 v210, 0, v214
	v_max_f32_e32 v211, 0, v215
	v_pk_fma_f32 v[0:1], v[24:25], v[210:211], v[0:1]
	v_max_f32_e32 v108, 0, v216
	v_max_f32_e32 v109, 0, v217
	v_pk_fma_f32 v[0:1], v[26:27], v[108:109], v[0:1]
	v_mfma_f32_32x32x16_bf16 v[6:21], v[90:93], v[42:45], v[6:21]
	v_max_f32_e32 v210, 0, v218
	v_max_f32_e32 v211, 0, v219
	v_pk_fma_f32 v[0:1], v[28:29], v[210:211], v[0:1]
	v_max_f32_e32 v108, 0, v220
	v_max_f32_e32 v109, 0, v221
	v_pk_fma_f32 v[0:1], v[30:31], v[108:109], v[0:1]
	v_max_f32_e32 v210, 0, v222
	v_max_f32_e32 v211, 0, v223
	v_pk_fma_f32 v[0:1], v[32:33], v[210:211], v[0:1]
	v_mfma_f32_32x32x16_bf16 v[6:21], v[94:97], v[46:49], v[6:21]
	v_max_f32_e32 v108, 0, v224
	v_max_f32_e32 v109, 0, v225
	v_pk_fma_f32 v[0:1], v[34:35], v[108:109], v[0:1]
	v_max_f32_e32 v210, 0, v226
	v_max_f32_e32 v211, 0, v227
	v_pk_fma_f32 v[0:1], v[36:37], v[210:211], v[0:1]
	v_add_f32_e32 v0, v0, v1
	v_ashrrev_i32_e32 v1, 31, v0
	v_mfma_f32_32x32x16_bf16 v[6:21], v[98:101], v[196:199], v[6:21]
	s_waitcnt vmcnt(10)
	ds_read_b128 v[38:41], v5 offset:43264
	ds_read_b128 v[42:45], v52 offset:43264
	ds_read_b128 v[46:49], v55 offset:43264
	ds_read_b128 v[196:199], v56 offset:43264
	v_or_b32_e32 v1, 0x80000000, v1
	s_cmpk_gt_i32 s11, 32
	s_cselect_b64 vcc, -1, 0
	v_xor_b32_e32 v0, v1, v0
	v_cndmask_b32_e32 v138, v123, v0, vcc
	s_nop 3
	s_waitcnt lgkmcnt(3)
	v_mfma_f32_32x32x16_bf16 v[212:227], v[70:73], v[38:41], 0
	v_max_f32_e32 v108, 0, v6
	v_max_f32_e32 v109, 0, v7
	v_pk_mul_f32 v[50:51], v[244:245], v[108:109]
	v_max_f32_e32 v210, 0, v8
	v_max_f32_e32 v211, 0, v9
	v_pk_fma_f32 v[50:51], v[246:247], v[210:211], v[50:51]
	v_max_f32_e32 v108, 0, v10
	v_max_f32_e32 v109, 0, v11
	v_pk_fma_f32 v[50:51], v[248:249], v[108:109], v[50:51]
	s_waitcnt lgkmcnt(2)
	v_mfma_f32_32x32x16_bf16 v[212:227], v[74:77], v[42:45], v[212:227]
	v_max_f32_e32 v210, 0, v12
	v_max_f32_e32 v211, 0, v13
	v_pk_fma_f32 v[50:51], v[250:251], v[210:211], v[50:51]
	v_max_f32_e32 v108, 0, v14
	v_max_f32_e32 v109, 0, v15
	v_pk_fma_f32 v[50:51], v[252:253], v[108:109], v[50:51]
	v_max_f32_e32 v210, 0, v16
	v_max_f32_e32 v211, 0, v17
	v_pk_fma_f32 v[50:51], v[254:255], v[210:211], v[50:51]
	s_waitcnt lgkmcnt(1)
	v_mfma_f32_32x32x16_bf16 v[212:227], v[78:81], v[46:49], v[212:227]
	v_max_f32_e32 v108, 0, v18
	v_max_f32_e32 v109, 0, v19
	v_pk_fma_f32 v[50:51], v[200:201], v[108:109], v[50:51]
	v_max_f32_e32 v210, 0, v20
	v_max_f32_e32 v211, 0, v21
	v_pk_fma_f32 v[50:51], v[202:203], v[210:211], v[50:51]
	v_add_f32_e32 v50, v50, v51
	v_ashrrev_i32_e32 v51, 31, v50
	s_waitcnt lgkmcnt(0)
	v_mfma_f32_32x32x16_bf16 v[212:227], v[82:85], v[196:199], v[212:227]
	v_or_b32_e32 v51, 0x80000000, v51
	s_cmpk_gt_i32 s11, 32
	s_cselect_b64 vcc, -1, 0
	v_xor_b32_e32 v50, v51, v50
	v_cndmask_b32_e32 v50, v123, v50, vcc
	global_store_dword v243, v50, s[8:9]
	v_mfma_f32_32x32x16_bf16 v[6:21], v[86:89], v[38:41], 0
	s_add_i32 m0, s10, 0
	s_nop 0
	global_load_lds_dwordx4 v102, s[6:7]
	s_add_i32 m0, s10, 1024
	s_nop 0
	global_load_lds_dwordx4 v110, s[6:7]
	s_add_i32 m0, s10, 2048
	s_nop 0
	global_load_lds_dwordx4 v112, s[6:7]
	s_add_i32 m0, s10, 3072
	s_nop 0
	global_load_lds_dwordx4 v193, s[6:7]
	s_add_u32 s6, s6, 0x8000
	s_addc_u32 s7, s7, 0
	v_max_f32_e32 v108, 0, v212
	v_max_f32_e32 v109, 0, v213
	v_pk_mul_f32 v[0:1], v[22:23], v[108:109]
	v_max_f32_e32 v210, 0, v214
	v_max_f32_e32 v211, 0, v215
	v_pk_fma_f32 v[0:1], v[24:25], v[210:211], v[0:1]
	v_max_f32_e32 v108, 0, v216
	v_max_f32_e32 v109, 0, v217
	v_pk_fma_f32 v[0:1], v[26:27], v[108:109], v[0:1]
	v_mfma_f32_32x32x16_bf16 v[6:21], v[90:93], v[42:45], v[6:21]
	v_max_f32_e32 v210, 0, v218
	v_max_f32_e32 v211, 0, v219
	v_pk_fma_f32 v[0:1], v[28:29], v[210:211], v[0:1]
	v_max_f32_e32 v108, 0, v220
	v_max_f32_e32 v109, 0, v221
	v_pk_fma_f32 v[0:1], v[30:31], v[108:109], v[0:1]
	v_max_f32_e32 v210, 0, v222
	v_max_f32_e32 v211, 0, v223
	v_pk_fma_f32 v[0:1], v[32:33], v[210:211], v[0:1]
	v_mfma_f32_32x32x16_bf16 v[6:21], v[94:97], v[46:49], v[6:21]
	v_max_f32_e32 v108, 0, v224
	v_max_f32_e32 v109, 0, v225
	v_pk_fma_f32 v[0:1], v[34:35], v[108:109], v[0:1]
	v_max_f32_e32 v210, 0, v226
	v_max_f32_e32 v211, 0, v227
	v_pk_fma_f32 v[0:1], v[36:37], v[210:211], v[0:1]
	v_add_f32_e32 v0, v0, v1
	v_ashrrev_i32_e32 v1, 31, v0
	v_mfma_f32_32x32x16_bf16 v[6:21], v[98:101], v[196:199], v[6:21]
	s_waitcnt vmcnt(10)
	v_add_u32_e32 v228, 0x10000, v5
	ds_read_b128 v[38:41], v228 offset:10496
	v_add_u32_e32 v228, 0x10000, v52
	ds_read_b128 v[42:45], v228 offset:10496
	v_add_u32_e32 v228, 0x10000, v55
	ds_read_b128 v[46:49], v228 offset:10496
	v_add_u32_e32 v228, 0x10000, v56
	ds_read_b128 v[196:199], v228 offset:10496
	v_or_b32_e32 v1, 0x80000000, v1
	s_cmpk_gt_i32 s11, 40
	s_cselect_b64 vcc, -1, 0
	v_xor_b32_e32 v0, v1, v0
	v_cndmask_b32_e32 v137, v123, v0, vcc
	s_nop 3
	s_waitcnt lgkmcnt(3)
	v_mfma_f32_32x32x16_bf16 v[212:227], v[70:73], v[38:41], 0
	v_max_f32_e32 v108, 0, v6
	v_max_f32_e32 v109, 0, v7
	v_pk_mul_f32 v[50:51], v[244:245], v[108:109]
	v_max_f32_e32 v210, 0, v8
	v_max_f32_e32 v211, 0, v9
	v_pk_fma_f32 v[50:51], v[246:247], v[210:211], v[50:51]
	v_max_f32_e32 v108, 0, v10
	v_max_f32_e32 v109, 0, v11
	v_pk_fma_f32 v[50:51], v[248:249], v[108:109], v[50:51]
	s_waitcnt lgkmcnt(2)
	v_mfma_f32_32x32x16_bf16 v[212:227], v[74:77], v[42:45], v[212:227]
	v_max_f32_e32 v210, 0, v12
	v_max_f32_e32 v211, 0, v13
	v_pk_fma_f32 v[50:51], v[250:251], v[210:211], v[50:51]
	v_max_f32_e32 v108, 0, v14
	v_max_f32_e32 v109, 0, v15
	v_pk_fma_f32 v[50:51], v[252:253], v[108:109], v[50:51]
	v_max_f32_e32 v210, 0, v16
	v_max_f32_e32 v211, 0, v17
	v_pk_fma_f32 v[50:51], v[254:255], v[210:211], v[50:51]
	s_waitcnt lgkmcnt(1)
	v_mfma_f32_32x32x16_bf16 v[212:227], v[78:81], v[46:49], v[212:227]
	v_max_f32_e32 v108, 0, v18
	v_max_f32_e32 v109, 0, v19
	v_pk_fma_f32 v[50:51], v[200:201], v[108:109], v[50:51]
	v_max_f32_e32 v210, 0, v20
	v_max_f32_e32 v211, 0, v21
	v_pk_fma_f32 v[50:51], v[202:203], v[210:211], v[50:51]
	v_add_f32_e32 v50, v50, v51
	v_ashrrev_i32_e32 v51, 31, v50
	s_waitcnt lgkmcnt(0)
	v_mfma_f32_32x32x16_bf16 v[212:227], v[82:85], v[196:199], v[212:227]
	v_or_b32_e32 v51, 0x80000000, v51
	s_cmpk_gt_i32 s11, 40
	s_cselect_b64 vcc, -1, 0
	v_xor_b32_e32 v50, v51, v50
	v_cndmask_b32_e32 v50, v123, v50, vcc
	global_store_dword v243, v50, s[8:9] offset:2048
	s_add_u32 s8, s8, 0x1000
	s_addc_u32 s9, s9, 0
	v_mfma_f32_32x32x16_bf16 v[6:21], v[86:89], v[38:41], 0
	s_add_i32 m0, s10, 32768
	s_nop 0
	global_load_lds_dwordx4 v102, s[6:7]
	s_add_i32 m0, s10, 33792
	s_nop 0
	global_load_lds_dwordx4 v110, s[6:7]
	s_add_i32 m0, s10, 34816
	s_nop 0
	global_load_lds_dwordx4 v112, s[6:7]
	s_add_i32 m0, s10, 35840
	s_nop 0
	global_load_lds_dwordx4 v193, s[6:7]
	s_add_u32 s6, s6, 0x8000
	s_addc_u32 s7, s7, 0
	v_max_f32_e32 v108, 0, v212
	v_max_f32_e32 v109, 0, v213
	v_pk_mul_f32 v[0:1], v[22:23], v[108:109]
	v_max_f32_e32 v210, 0, v214
	v_max_f32_e32 v211, 0, v215
	v_pk_fma_f32 v[0:1], v[24:25], v[210:211], v[0:1]
	v_max_f32_e32 v108, 0, v216
	v_max_f32_e32 v109, 0, v217
	v_pk_fma_f32 v[0:1], v[26:27], v[108:109], v[0:1]
	v_mfma_f32_32x32x16_bf16 v[6:21], v[90:93], v[42:45], v[6:21]
	v_max_f32_e32 v210, 0, v218
	v_max_f32_e32 v211, 0, v219
	v_pk_fma_f32 v[0:1], v[28:29], v[210:211], v[0:1]
	v_max_f32_e32 v108, 0, v220
	v_max_f32_e32 v109, 0, v221
	v_pk_fma_f32 v[0:1], v[30:31], v[108:109], v[0:1]
	v_max_f32_e32 v210, 0, v222
	v_max_f32_e32 v211, 0, v223
	v_pk_fma_f32 v[0:1], v[32:33], v[210:211], v[0:1]
	v_mfma_f32_32x32x16_bf16 v[6:21], v[94:97], v[46:49], v[6:21]
	v_max_f32_e32 v108, 0, v224
	v_max_f32_e32 v109, 0, v225
	v_pk_fma_f32 v[0:1], v[34:35], v[108:109], v[0:1]
	v_max_f32_e32 v210, 0, v226
	v_max_f32_e32 v211, 0, v227
	v_pk_fma_f32 v[0:1], v[36:37], v[210:211], v[0:1]
	v_add_f32_e32 v0, v0, v1
	v_ashrrev_i32_e32 v1, 31, v0
	v_mfma_f32_32x32x16_bf16 v[6:21], v[98:101], v[196:199], v[6:21]
	s_waitcnt vmcnt(10)
	v_add_u32_e32 v228, 0x10000, v5
	ds_read_b128 v[38:41], v228 offset:43264
	v_add_u32_e32 v228, 0x10000, v52
	ds_read_b128 v[42:45], v228 offset:43264
	v_add_u32_e32 v228, 0x10000, v55
	ds_read_b128 v[46:49], v228 offset:43264
	v_add_u32_e32 v228, 0x10000, v56
	ds_read_b128 v[196:199], v228 offset:43264
	v_or_b32_e32 v1, 0x80000000, v1
	s_cmpk_gt_i32 s11, 48
	s_cselect_b64 vcc, -1, 0
	v_xor_b32_e32 v0, v1, v0
	v_cndmask_b32_e32 v140, v123, v0, vcc
	s_nop 3
	s_waitcnt lgkmcnt(3)
	v_mfma_f32_32x32x16_bf16 v[212:227], v[70:73], v[38:41], 0
	v_max_f32_e32 v108, 0, v6
	v_max_f32_e32 v109, 0, v7
	v_pk_mul_f32 v[50:51], v[244:245], v[108:109]
	v_max_f32_e32 v210, 0, v8
	v_max_f32_e32 v211, 0, v9
	v_pk_fma_f32 v[50:51], v[246:247], v[210:211], v[50:51]
	v_max_f32_e32 v108, 0, v10
	v_max_f32_e32 v109, 0, v11
	v_pk_fma_f32 v[50:51], v[248:249], v[108:109], v[50:51]
	s_waitcnt lgkmcnt(2)
	v_mfma_f32_32x32x16_bf16 v[212:227], v[74:77], v[42:45], v[212:227]
	v_max_f32_e32 v210, 0, v12
	v_max_f32_e32 v211, 0, v13
	v_pk_fma_f32 v[50:51], v[250:251], v[210:211], v[50:51]
	v_max_f32_e32 v108, 0, v14
	v_max_f32_e32 v109, 0, v15
	v_pk_fma_f32 v[50:51], v[252:253], v[108:109], v[50:51]
	v_max_f32_e32 v210, 0, v16
	v_max_f32_e32 v211, 0, v17
	v_pk_fma_f32 v[50:51], v[254:255], v[210:211], v[50:51]
	s_waitcnt lgkmcnt(1)
	v_mfma_f32_32x32x16_bf16 v[212:227], v[78:81], v[46:49], v[212:227]
	v_max_f32_e32 v108, 0, v18
	v_max_f32_e32 v109, 0, v19
	v_pk_fma_f32 v[50:51], v[200:201], v[108:109], v[50:51]
	v_max_f32_e32 v210, 0, v20
	v_max_f32_e32 v211, 0, v21
	v_pk_fma_f32 v[50:51], v[202:203], v[210:211], v[50:51]
	v_add_f32_e32 v50, v50, v51
	v_ashrrev_i32_e32 v51, 31, v50
	s_waitcnt lgkmcnt(0)
	v_mfma_f32_32x32x16_bf16 v[212:227], v[82:85], v[196:199], v[212:227]
	v_or_b32_e32 v51, 0x80000000, v51
	s_cmpk_gt_i32 s11, 48
	s_cselect_b64 vcc, -1, 0
	v_xor_b32_e32 v50, v51, v50
	v_cndmask_b32_e32 v50, v123, v50, vcc
	global_store_dword v243, v50, s[8:9]
	v_mfma_f32_32x32x16_bf16 v[6:21], v[86:89], v[38:41], 0
	s_add_i32 m0, s10, 65536
	s_nop 0
	global_load_lds_dwordx4 v102, s[6:7]
	s_add_i32 m0, s10, 66560
	s_nop 0
	global_load_lds_dwordx4 v110, s[6:7]
	s_add_i32 m0, s10, 67584
	s_nop 0
	global_load_lds_dwordx4 v112, s[6:7]
	s_add_i32 m0, s10, 68608
	s_nop 0
	global_load_lds_dwordx4 v193, s[6:7]
	s_add_u32 s6, s6, 0x8000
	s_addc_u32 s7, s7, 0
	v_max_f32_e32 v108, 0, v212
	v_max_f32_e32 v109, 0, v213
	v_pk_mul_f32 v[0:1], v[22:23], v[108:109]
	v_max_f32_e32 v210, 0, v214
	v_max_f32_e32 v211, 0, v215
	v_pk_fma_f32 v[0:1], v[24:25], v[210:211], v[0:1]
	v_max_f32_e32 v108, 0, v216
	v_max_f32_e32 v109, 0, v217
	v_pk_fma_f32 v[0:1], v[26:27], v[108:109], v[0:1]
	v_mfma_f32_32x32x16_bf16 v[6:21], v[90:93], v[42:45], v[6:21]
	v_max_f32_e32 v210, 0, v218
	v_max_f32_e32 v211, 0, v219
	v_pk_fma_f32 v[0:1], v[28:29], v[210:211], v[0:1]
	v_max_f32_e32 v108, 0, v220
	v_max_f32_e32 v109, 0, v221
	v_pk_fma_f32 v[0:1], v[30:31], v[108:109], v[0:1]
	v_max_f32_e32 v210, 0, v222
	v_max_f32_e32 v211, 0, v223
	v_pk_fma_f32 v[0:1], v[32:33], v[210:211], v[0:1]
	v_mfma_f32_32x32x16_bf16 v[6:21], v[94:97], v[46:49], v[6:21]
	v_max_f32_e32 v108, 0, v224
	v_max_f32_e32 v109, 0, v225
	v_pk_fma_f32 v[0:1], v[34:35], v[108:109], v[0:1]
	v_max_f32_e32 v210, 0, v226
	v_max_f32_e32 v211, 0, v227
	v_pk_fma_f32 v[0:1], v[36:37], v[210:211], v[0:1]
	v_add_f32_e32 v0, v0, v1
	v_ashrrev_i32_e32 v1, 31, v0
	v_mfma_f32_32x32x16_bf16 v[6:21], v[98:101], v[196:199], v[6:21]
	s_waitcnt vmcnt(10)
	ds_read_b128 v[38:41], v5 offset:10496
	ds_read_b128 v[42:45], v52 offset:10496
	ds_read_b128 v[46:49], v55 offset:10496
	ds_read_b128 v[196:199], v56 offset:10496
	v_or_b32_e32 v1, 0x80000000, v1
	s_cmpk_gt_i32 s11, 56
	s_cselect_b64 vcc, -1, 0
	v_xor_b32_e32 v0, v1, v0
	v_cndmask_b32_e32 v139, v123, v0, vcc
	s_nop 3
	v_max_f32_e32 v108, 0, v6
	v_max_f32_e32 v109, 0, v7
	v_pk_mul_f32 v[50:51], v[244:245], v[108:109]
	v_max_f32_e32 v210, 0, v8
	v_max_f32_e32 v211, 0, v9
	v_pk_fma_f32 v[50:51], v[246:247], v[210:211], v[50:51]
	v_max_f32_e32 v108, 0, v10
	v_max_f32_e32 v109, 0, v11
	v_pk_fma_f32 v[50:51], v[248:249], v[108:109], v[50:51]
	v_max_f32_e32 v210, 0, v12
	v_max_f32_e32 v211, 0, v13
	v_pk_fma_f32 v[50:51], v[250:251], v[210:211], v[50:51]
	v_max_f32_e32 v108, 0, v14
	v_max_f32_e32 v109, 0, v15
	v_pk_fma_f32 v[50:51], v[252:253], v[108:109], v[50:51]
	v_max_f32_e32 v210, 0, v16
	v_max_f32_e32 v211, 0, v17
	v_pk_fma_f32 v[50:51], v[254:255], v[210:211], v[50:51]
	v_max_f32_e32 v108, 0, v18
	v_max_f32_e32 v109, 0, v19
	v_pk_fma_f32 v[50:51], v[200:201], v[108:109], v[50:51]
	v_max_f32_e32 v210, 0, v20
	v_max_f32_e32 v211, 0, v21
	v_pk_fma_f32 v[50:51], v[202:203], v[210:211], v[50:51]
	v_add_f32_e32 v50, v50, v51
	v_ashrrev_i32_e32 v51, 31, v50
	v_or_b32_e32 v51, 0x80000000, v51
	s_cmpk_gt_i32 s11, 56
	s_cselect_b64 vcc, -1, 0
	v_xor_b32_e32 v50, v51, v50
	v_cndmask_b32_e32 v50, v123, v50, vcc
	global_store_dword v243, v50, s[8:9] offset:2048
	s_add_u32 s8, s8, 0x1000
	s_addc_u32 s9, s9, 0
	s_cmpk_gt_i32 s81, 8
	s_cbranch_scc0 .Lix_fill_1
	s_waitcnt lgkmcnt(3)
	v_mfma_f32_32x32x16_bf16 v[212:227], v[70:73], v[38:41], 0
	s_add_i32 m0, s10, 98304
	s_nop 0
	global_load_lds_dwordx4 v102, s[6:7]
	s_waitcnt lgkmcnt(2)
	v_mfma_f32_32x32x16_bf16 v[212:227], v[74:77], v[42:45], v[212:227]
	s_add_i32 m0, s10, 99328
	s_nop 0
	global_load_lds_dwordx4 v110, s[6:7]
	s_waitcnt lgkmcnt(1)
	v_mfma_f32_32x32x16_bf16 v[212:227], v[78:81], v[46:49], v[212:227]
	s_add_i32 m0, s10, 100352
	s_nop 0
	global_load_lds_dwordx4 v112, s[6:7]
	s_waitcnt lgkmcnt(0)
	v_mfma_f32_32x32x16_bf16 v[212:227], v[82:85], v[196:199], v[212:227]
	s_add_i32 m0, s10, 101376
	s_nop 0
	global_load_lds_dwordx4 v193, s[6:7]
	s_add_u32 s6, s6, 0x8000
	s_addc_u32 s7, s7, 0
	v_mfma_f32_32x32x16_bf16 v[6:21], v[86:89], v[38:41], 0
	s_nop 7
	s_nop 2
	v_max_f32_e32 v108, 0, v212
	v_max_f32_e32 v109, 0, v213
	v_pk_mul_f32 v[0:1], v[22:23], v[108:109]
	v_max_f32_e32 v210, 0, v214
	v_max_f32_e32 v211, 0, v215
	v_pk_fma_f32 v[0:1], v[24:25], v[210:211], v[0:1]
	v_max_f32_e32 v108, 0, v216
	v_max_f32_e32 v109, 0, v217
	v_pk_fma_f32 v[0:1], v[26:27], v[108:109], v[0:1]
	v_mfma_f32_32x32x16_bf16 v[6:21], v[90:93], v[42:45], v[6:21]
	v_max_f32_e32 v210, 0, v218
	v_max_f32_e32 v211, 0, v219
	v_pk_fma_f32 v[0:1], v[28:29], v[210:211], v[0:1]
	v_max_f32_e32 v108, 0, v220
	v_max_f32_e32 v109, 0, v221
	v_pk_fma_f32 v[0:1], v[30:31], v[108:109], v[0:1]
	v_max_f32_e32 v210, 0, v222
	v_max_f32_e32 v211, 0, v223
	v_pk_fma_f32 v[0:1], v[32:33], v[210:211], v[0:1]
	v_mfma_f32_32x32x16_bf16 v[6:21], v[94:97], v[46:49], v[6:21]
	v_max_f32_e32 v108, 0, v224
	v_max_f32_e32 v109, 0, v225
	v_pk_fma_f32 v[0:1], v[34:35], v[108:109], v[0:1]
	v_max_f32_e32 v210, 0, v226
	v_max_f32_e32 v211, 0, v227
	v_pk_fma_f32 v[0:1], v[36:37], v[210:211], v[0:1]
	v_add_f32_e32 v0, v0, v1
	v_ashrrev_i32_e32 v1, 31, v0
	v_mfma_f32_32x32x16_bf16 v[6:21], v[98:101], v[196:199], v[6:21]
	s_waitcnt vmcnt(10)
	ds_read_b128 v[38:41], v5 offset:43264
	ds_read_b128 v[42:45], v52 offset:43264
	ds_read_b128 v[46:49], v55 offset:43264
	ds_read_b128 v[196:199], v56 offset:43264
	v_or_b32_e32 v1, 0x80000000, v1
	s_cmpk_gt_i32 s11, 64
	s_cselect_b64 vcc, -1, 0
	v_xor_b32_e32 v0, v1, v0
	v_cndmask_b32_e32 v142, v123, v0, vcc
	s_nop 3
	s_waitcnt lgkmcnt(3)
	v_mfma_f32_32x32x16_bf16 v[212:227], v[70:73], v[38:41], 0
	v_max_f32_e32 v108, 0, v6
	v_max_f32_e32 v109, 0, v7
	v_pk_mul_f32 v[50:51], v[244:245], v[108:109]
	v_max_f32_e32 v210, 0, v8
	v_max_f32_e32 v211, 0, v9
	v_pk_fma_f32 v[50:51], v[246:247], v[210:211], v[50:51]
	v_max_f32_e32 v108, 0, v10
	v_max_f32_e32 v109, 0, v11
	v_pk_fma_f32 v[50:51], v[248:249], v[108:109], v[50:51]
	s_waitcnt lgkmcnt(2)
	v_mfma_f32_32x32x16_bf16 v[212:227], v[74:77], v[42:45], v[212:227]
	v_max_f32_e32 v210, 0, v12
	v_max_f32_e32 v211, 0, v13
	v_pk_fma_f32 v[50:51], v[250:251], v[210:211], v[50:51]
	v_max_f32_e32 v108, 0, v14
	v_max_f32_e32 v109, 0, v15
	v_pk_fma_f32 v[50:51], v[252:253], v[108:109], v[50:51]
	v_max_f32_e32 v210, 0, v16
	v_max_f32_e32 v211, 0, v17
	v_pk_fma_f32 v[50:51], v[254:255], v[210:211], v[50:51]
	s_waitcnt lgkmcnt(1)
	v_mfma_f32_32x32x16_bf16 v[212:227], v[78:81], v[46:49], v[212:227]
	v_max_f32_e32 v108, 0, v18
	v_max_f32_e32 v109, 0, v19
	v_pk_fma_f32 v[50:51], v[200:201], v[108:109], v[50:51]
	v_max_f32_e32 v210, 0, v20
	v_max_f32_e32 v211, 0, v21
	v_pk_fma_f32 v[50:51], v[202:203], v[210:211], v[50:51]
	v_add_f32_e32 v50, v50, v51
	v_ashrrev_i32_e32 v51, 31, v50
	s_waitcnt lgkmcnt(0)
	v_mfma_f32_32x32x16_bf16 v[212:227], v[82:85], v[196:199], v[212:227]
	v_or_b32_e32 v51, 0x80000000, v51
	s_cmpk_gt_i32 s11, 64
	s_cselect_b64 vcc, -1, 0
	v_xor_b32_e32 v50, v51, v50
	v_cndmask_b32_e32 v50, v123, v50, vcc
	global_store_dword v243, v50, s[8:9]
	v_mfma_f32_32x32x16_bf16 v[6:21], v[86:89], v[38:41], 0
	s_add_i32 m0, s10, 0
	s_nop 0
	global_load_lds_dwordx4 v102, s[6:7]
	s_add_i32 m0, s10, 1024
	s_nop 0
	global_load_lds_dwordx4 v110, s[6:7]
	s_add_i32 m0, s10, 2048
	s_nop 0
	global_load_lds_dwordx4 v112, s[6:7]
	s_add_i32 m0, s10, 3072
	s_nop 0
	global_load_lds_dwordx4 v193, s[6:7]
	s_add_u32 s6, s6, 0x8000
	s_addc_u32 s7, s7, 0
	v_max_f32_e32 v108, 0, v212
	v_max_f32_e32 v109, 0, v213
	v_pk_mul_f32 v[0:1], v[22:23], v[108:109]
	v_max_f32_e32 v210, 0, v214
	v_max_f32_e32 v211, 0, v215
	v_pk_fma_f32 v[0:1], v[24:25], v[210:211], v[0:1]
	v_max_f32_e32 v108, 0, v216
	v_max_f32_e32 v109, 0, v217
	v_pk_fma_f32 v[0:1], v[26:27], v[108:109], v[0:1]
	v_mfma_f32_32x32x16_bf16 v[6:21], v[90:93], v[42:45], v[6:21]
	v_max_f32_e32 v210, 0, v218
	v_max_f32_e32 v211, 0, v219
	v_pk_fma_f32 v[0:1], v[28:29], v[210:211], v[0:1]
	v_max_f32_e32 v108, 0, v220
	v_max_f32_e32 v109, 0, v221
	v_pk_fma_f32 v[0:1], v[30:31], v[108:109], v[0:1]
	v_max_f32_e32 v210, 0, v222
	v_max_f32_e32 v211, 0, v223
	v_pk_fma_f32 v[0:1], v[32:33], v[210:211], v[0:1]
	v_mfma_f32_32x32x16_bf16 v[6:21], v[94:97], v[46:49], v[6:21]
	v_max_f32_e32 v108, 0, v224
	v_max_f32_e32 v109, 0, v225
	v_pk_fma_f32 v[0:1], v[34:35], v[108:109], v[0:1]
	v_max_f32_e32 v210, 0, v226
	v_max_f32_e32 v211, 0, v227
	v_pk_fma_f32 v[0:1], v[36:37], v[210:211], v[0:1]
	v_add_f32_e32 v0, v0, v1
	v_ashrrev_i32_e32 v1, 31, v0
	v_mfma_f32_32x32x16_bf16 v[6:21], v[98:101], v[196:199], v[6:21]
	s_waitcnt vmcnt(10)
	v_add_u32_e32 v228, 0x10000, v5
	ds_read_b128 v[38:41], v228 offset:10496
	v_add_u32_e32 v228, 0x10000, v52
	ds_read_b128 v[42:45], v228 offset:10496
	v_add_u32_e32 v228, 0x10000, v55
	ds_read_b128 v[46:49], v228 offset:10496
	v_add_u32_e32 v228, 0x10000, v56
	ds_read_b128 v[196:199], v228 offset:10496
	v_or_b32_e32 v1, 0x80000000, v1
	s_cmpk_gt_i32 s11, 72
	s_cselect_b64 vcc, -1, 0
	v_xor_b32_e32 v0, v1, v0
	v_cndmask_b32_e32 v141, v123, v0, vcc
	s_nop 3
	s_waitcnt lgkmcnt(3)
	v_mfma_f32_32x32x16_bf16 v[212:227], v[70:73], v[38:41], 0
	v_max_f32_e32 v108, 0, v6
	v_max_f32_e32 v109, 0, v7
	v_pk_mul_f32 v[50:51], v[244:245], v[108:109]
	v_max_f32_e32 v210, 0, v8
	v_max_f32_e32 v211, 0, v9
	v_pk_fma_f32 v[50:51], v[246:247], v[210:211], v[50:51]
	v_max_f32_e32 v108, 0, v10
	v_max_f32_e32 v109, 0, v11
	v_pk_fma_f32 v[50:51], v[248:249], v[108:109], v[50:51]
	s_waitcnt lgkmcnt(2)
	v_mfma_f32_32x32x16_bf16 v[212:227], v[74:77], v[42:45], v[212:227]
	v_max_f32_e32 v210, 0, v12
	v_max_f32_e32 v211, 0, v13
	v_pk_fma_f32 v[50:51], v[250:251], v[210:211], v[50:51]
	v_max_f32_e32 v108, 0, v14
	v_max_f32_e32 v109, 0, v15
	v_pk_fma_f32 v[50:51], v[252:253], v[108:109], v[50:51]
	v_max_f32_e32 v210, 0, v16
	v_max_f32_e32 v211, 0, v17
	v_pk_fma_f32 v[50:51], v[254:255], v[210:211], v[50:51]
	s_waitcnt lgkmcnt(1)
	v_mfma_f32_32x32x16_bf16 v[212:227], v[78:81], v[46:49], v[212:227]
	v_max_f32_e32 v108, 0, v18
	v_max_f32_e32 v109, 0, v19
	v_pk_fma_f32 v[50:51], v[200:201], v[108:109], v[50:51]
	v_max_f32_e32 v210, 0, v20
	v_max_f32_e32 v211, 0, v21
	v_pk_fma_f32 v[50:51], v[202:203], v[210:211], v[50:51]
	v_add_f32_e32 v50, v50, v51
	v_ashrrev_i32_e32 v51, 31, v50
	s_waitcnt lgkmcnt(0)
	v_mfma_f32_32x32x16_bf16 v[212:227], v[82:85], v[196:199], v[212:227]
	v_or_b32_e32 v51, 0x80000000, v51
	s_cmpk_gt_i32 s11, 72
	s_cselect_b64 vcc, -1, 0
	v_xor_b32_e32 v50, v51, v50
	v_cndmask_b32_e32 v50, v123, v50, vcc
	global_store_dword v243, v50, s[8:9] offset:2048
	s_add_u32 s8, s8, 0x1000
	s_addc_u32 s9, s9, 0
	v_mfma_f32_32x32x16_bf16 v[6:21], v[86:89], v[38:41], 0
	s_add_i32 m0, s10, 32768
	s_nop 0
	global_load_lds_dwordx4 v102, s[6:7]
	s_add_i32 m0, s10, 33792
	s_nop 0
	global_load_lds_dwordx4 v110, s[6:7]
	s_add_i32 m0, s10, 34816
	s_nop 0
	global_load_lds_dwordx4 v112, s[6:7]
	s_add_i32 m0, s10, 35840
	s_nop 0
	global_load_lds_dwordx4 v193, s[6:7]
	s_add_u32 s6, s6, 0x8000
	s_addc_u32 s7, s7, 0
	v_max_f32_e32 v108, 0, v212
	v_max_f32_e32 v109, 0, v213
	v_pk_mul_f32 v[0:1], v[22:23], v[108:109]
	v_max_f32_e32 v210, 0, v214
	v_max_f32_e32 v211, 0, v215
	v_pk_fma_f32 v[0:1], v[24:25], v[210:211], v[0:1]
	v_max_f32_e32 v108, 0, v216
	v_max_f32_e32 v109, 0, v217
	v_pk_fma_f32 v[0:1], v[26:27], v[108:109], v[0:1]
	v_mfma_f32_32x32x16_bf16 v[6:21], v[90:93], v[42:45], v[6:21]
	v_max_f32_e32 v210, 0, v218
	v_max_f32_e32 v211, 0, v219
	v_pk_fma_f32 v[0:1], v[28:29], v[210:211], v[0:1]
	v_max_f32_e32 v108, 0, v220
	v_max_f32_e32 v109, 0, v221
	v_pk_fma_f32 v[0:1], v[30:31], v[108:109], v[0:1]
	v_max_f32_e32 v210, 0, v222
	v_max_f32_e32 v211, 0, v223
	v_pk_fma_f32 v[0:1], v[32:33], v[210:211], v[0:1]
	v_mfma_f32_32x32x16_bf16 v[6:21], v[94:97], v[46:49], v[6:21]
	v_max_f32_e32 v108, 0, v224
	v_max_f32_e32 v109, 0, v225
	v_pk_fma_f32 v[0:1], v[34:35], v[108:109], v[0:1]
	v_max_f32_e32 v210, 0, v226
	v_max_f32_e32 v211, 0, v227
	v_pk_fma_f32 v[0:1], v[36:37], v[210:211], v[0:1]
	v_add_f32_e32 v0, v0, v1
	v_ashrrev_i32_e32 v1, 31, v0
	v_mfma_f32_32x32x16_bf16 v[6:21], v[98:101], v[196:199], v[6:21]
	s_waitcnt vmcnt(10)
	v_add_u32_e32 v228, 0x10000, v5
	ds_read_b128 v[38:41], v228 offset:43264
	v_add_u32_e32 v228, 0x10000, v52
	ds_read_b128 v[42:45], v228 offset:43264
	v_add_u32_e32 v228, 0x10000, v55
	ds_read_b128 v[46:49], v228 offset:43264
	v_add_u32_e32 v228, 0x10000, v56
	ds_read_b128 v[196:199], v228 offset:43264
	v_or_b32_e32 v1, 0x80000000, v1
	s_cmpk_gt_i32 s11, 80
	s_cselect_b64 vcc, -1, 0
	v_xor_b32_e32 v0, v1, v0
	v_cndmask_b32_e32 v144, v123, v0, vcc
	s_nop 3
	s_waitcnt lgkmcnt(3)
	v_mfma_f32_32x32x16_bf16 v[212:227], v[70:73], v[38:41], 0
	v_max_f32_e32 v108, 0, v6
	v_max_f32_e32 v109, 0, v7
	v_pk_mul_f32 v[50:51], v[244:245], v[108:109]
	v_max_f32_e32 v210, 0, v8
	v_max_f32_e32 v211, 0, v9
	v_pk_fma_f32 v[50:51], v[246:247], v[210:211], v[50:51]
	v_max_f32_e32 v108, 0, v10
	v_max_f32_e32 v109, 0, v11
	v_pk_fma_f32 v[50:51], v[248:249], v[108:109], v[50:51]
	s_waitcnt lgkmcnt(2)
	v_mfma_f32_32x32x16_bf16 v[212:227], v[74:77], v[42:45], v[212:227]
	v_max_f32_e32 v210, 0, v12
	v_max_f32_e32 v211, 0, v13
	v_pk_fma_f32 v[50:51], v[250:251], v[210:211], v[50:51]
	v_max_f32_e32 v108, 0, v14
	v_max_f32_e32 v109, 0, v15
	v_pk_fma_f32 v[50:51], v[252:253], v[108:109], v[50:51]
	v_max_f32_e32 v210, 0, v16
	v_max_f32_e32 v211, 0, v17
	v_pk_fma_f32 v[50:51], v[254:255], v[210:211], v[50:51]
	s_waitcnt lgkmcnt(1)
	v_mfma_f32_32x32x16_bf16 v[212:227], v[78:81], v[46:49], v[212:227]
	v_max_f32_e32 v108, 0, v18
	v_max_f32_e32 v109, 0, v19
	v_pk_fma_f32 v[50:51], v[200:201], v[108:109], v[50:51]
	v_max_f32_e32 v210, 0, v20
	v_max_f32_e32 v211, 0, v21
	v_pk_fma_f32 v[50:51], v[202:203], v[210:211], v[50:51]
	v_add_f32_e32 v50, v50, v51
	v_ashrrev_i32_e32 v51, 31, v50
	s_waitcnt lgkmcnt(0)
	v_mfma_f32_32x32x16_bf16 v[212:227], v[82:85], v[196:199], v[212:227]
	v_or_b32_e32 v51, 0x80000000, v51
	s_cmpk_gt_i32 s11, 80
	s_cselect_b64 vcc, -1, 0
	v_xor_b32_e32 v50, v51, v50
	v_cndmask_b32_e32 v50, v123, v50, vcc
	global_store_dword v243, v50, s[8:9]
	v_mfma_f32_32x32x16_bf16 v[6:21], v[86:89], v[38:41], 0
	s_add_i32 m0, s10, 65536
	s_nop 0
	global_load_lds_dwordx4 v102, s[6:7]
	s_add_i32 m0, s10, 66560
	s_nop 0
	global_load_lds_dwordx4 v110, s[6:7]
	s_add_i32 m0, s10, 67584
	s_nop 0
	global_load_lds_dwordx4 v112, s[6:7]
	s_add_i32 m0, s10, 68608
	s_nop 0
	global_load_lds_dwordx4 v193, s[6:7]
	s_add_u32 s6, s6, 0x8000
	s_addc_u32 s7, s7, 0
	v_max_f32_e32 v108, 0, v212
	v_max_f32_e32 v109, 0, v213
	v_pk_mul_f32 v[0:1], v[22:23], v[108:109]
	v_max_f32_e32 v210, 0, v214
	v_max_f32_e32 v211, 0, v215
	v_pk_fma_f32 v[0:1], v[24:25], v[210:211], v[0:1]
	v_max_f32_e32 v108, 0, v216
	v_max_f32_e32 v109, 0, v217
	v_pk_fma_f32 v[0:1], v[26:27], v[108:109], v[0:1]
	v_mfma_f32_32x32x16_bf16 v[6:21], v[90:93], v[42:45], v[6:21]
	v_max_f32_e32 v210, 0, v218
	v_max_f32_e32 v211, 0, v219
	v_pk_fma_f32 v[0:1], v[28:29], v[210:211], v[0:1]
	v_max_f32_e32 v108, 0, v220
	v_max_f32_e32 v109, 0, v221
	v_pk_fma_f32 v[0:1], v[30:31], v[108:109], v[0:1]
	v_max_f32_e32 v210, 0, v222
	v_max_f32_e32 v211, 0, v223
	v_pk_fma_f32 v[0:1], v[32:33], v[210:211], v[0:1]
	v_mfma_f32_32x32x16_bf16 v[6:21], v[94:97], v[46:49], v[6:21]
	v_max_f32_e32 v108, 0, v224
	v_max_f32_e32 v109, 0, v225
	v_pk_fma_f32 v[0:1], v[34:35], v[108:109], v[0:1]
	v_max_f32_e32 v210, 0, v226
	v_max_f32_e32 v211, 0, v227
	v_pk_fma_f32 v[0:1], v[36:37], v[210:211], v[0:1]
	v_add_f32_e32 v0, v0, v1
	v_ashrrev_i32_e32 v1, 31, v0
	v_mfma_f32_32x32x16_bf16 v[6:21], v[98:101], v[196:199], v[6:21]
	s_waitcnt vmcnt(10)
	ds_read_b128 v[38:41], v5 offset:10496
	ds_read_b128 v[42:45], v52 offset:10496
	ds_read_b128 v[46:49], v55 offset:10496
	ds_read_b128 v[196:199], v56 offset:10496
	v_or_b32_e32 v1, 0x80000000, v1
	s_cmpk_gt_i32 s11, 88
	s_cselect_b64 vcc, -1, 0
	v_xor_b32_e32 v0, v1, v0
	v_cndmask_b32_e32 v143, v123, v0, vcc
	s_nop 3
	s_waitcnt lgkmcnt(3)
	v_mfma_f32_32x32x16_bf16 v[212:227], v[70:73], v[38:41], 0
	v_max_f32_e32 v108, 0, v6
	v_max_f32_e32 v109, 0, v7
	v_pk_mul_f32 v[50:51], v[244:245], v[108:109]
	v_max_f32_e32 v210, 0, v8
	v_max_f32_e32 v211, 0, v9
	v_pk_fma_f32 v[50:51], v[246:247], v[210:211], v[50:51]
	v_max_f32_e32 v108, 0, v10
	v_max_f32_e32 v109, 0, v11
	v_pk_fma_f32 v[50:51], v[248:249], v[108:109], v[50:51]
	s_waitcnt lgkmcnt(2)
	v_mfma_f32_32x32x16_bf16 v[212:227], v[74:77], v[42:45], v[212:227]
	v_max_f32_e32 v210, 0, v12
	v_max_f32_e32 v211, 0, v13
	v_pk_fma_f32 v[50:51], v[250:251], v[210:211], v[50:51]
	v_max_f32_e32 v108, 0, v14
	v_max_f32_e32 v109, 0, v15
	v_pk_fma_f32 v[50:51], v[252:253], v[108:109], v[50:51]
	v_max_f32_e32 v210, 0, v16
	v_max_f32_e32 v211, 0, v17
	v_pk_fma_f32 v[50:51], v[254:255], v[210:211], v[50:51]
	s_waitcnt lgkmcnt(1)
	v_mfma_f32_32x32x16_bf16 v[212:227], v[78:81], v[46:49], v[212:227]
	v_max_f32_e32 v108, 0, v18
	v_max_f32_e32 v109, 0, v19
	v_pk_fma_f32 v[50:51], v[200:201], v[108:109], v[50:51]
	v_max_f32_e32 v210, 0, v20
	v_max_f32_e32 v211, 0, v21
	v_pk_fma_f32 v[50:51], v[202:203], v[210:211], v[50:51]
	v_add_f32_e32 v50, v50, v51
	v_ashrrev_i32_e32 v51, 31, v50
	s_waitcnt lgkmcnt(0)
	v_mfma_f32_32x32x16_bf16 v[212:227], v[82:85], v[196:199], v[212:227]
	v_or_b32_e32 v51, 0x80000000, v51
	s_cmpk_gt_i32 s11, 88
	s_cselect_b64 vcc, -1, 0
	v_xor_b32_e32 v50, v51, v50
	v_cndmask_b32_e32 v50, v123, v50, vcc
	global_store_dword v243, v50, s[8:9] offset:2048
	s_add_u32 s8, s8, 0x1000
	s_addc_u32 s9, s9, 0
	v_mfma_f32_32x32x16_bf16 v[6:21], v[86:89], v[38:41], 0
	s_add_i32 m0, s10, 98304
	s_nop 0
	global_load_lds_dwordx4 v102, s[6:7]
	s_add_i32 m0, s10, 99328
	s_nop 0
	global_load_lds_dwordx4 v110, s[6:7]
	s_add_i32 m0, s10, 100352
	s_nop 0
	global_load_lds_dwordx4 v112, s[6:7]
	s_add_i32 m0, s10, 101376
	s_nop 0
	global_load_lds_dwordx4 v193, s[6:7]
	s_add_u32 s6, s6, 0x8000
	s_addc_u32 s7, s7, 0
	v_max_f32_e32 v108, 0, v212
	v_max_f32_e32 v109, 0, v213
	v_pk_mul_f32 v[0:1], v[22:23], v[108:109]
	v_max_f32_e32 v210, 0, v214
	v_max_f32_e32 v211, 0, v215
	v_pk_fma_f32 v[0:1], v[24:25], v[210:211], v[0:1]
	v_max_f32_e32 v108, 0, v216
	v_max_f32_e32 v109, 0, v217
	v_pk_fma_f32 v[0:1], v[26:27], v[108:109], v[0:1]
	v_mfma_f32_32x32x16_bf16 v[6:21], v[90:93], v[42:45], v[6:21]
	v_max_f32_e32 v210, 0, v218
	v_max_f32_e32 v211, 0, v219
	v_pk_fma_f32 v[0:1], v[28:29], v[210:211], v[0:1]
	v_max_f32_e32 v108, 0, v220
	v_max_f32_e32 v109, 0, v221
	v_pk_fma_f32 v[0:1], v[30:31], v[108:109], v[0:1]
	v_max_f32_e32 v210, 0, v222
	v_max_f32_e32 v211, 0, v223
	v_pk_fma_f32 v[0:1], v[32:33], v[210:211], v[0:1]
	v_mfma_f32_32x32x16_bf16 v[6:21], v[94:97], v[46:49], v[6:21]
	v_max_f32_e32 v108, 0, v224
	v_max_f32_e32 v109, 0, v225
	v_pk_fma_f32 v[0:1], v[34:35], v[108:109], v[0:1]
	v_max_f32_e32 v210, 0, v226
	v_max_f32_e32 v211, 0, v227
	v_pk_fma_f32 v[0:1], v[36:37], v[210:211], v[0:1]
	v_add_f32_e32 v0, v0, v1
	v_ashrrev_i32_e32 v1, 31, v0
	v_mfma_f32_32x32x16_bf16 v[6:21], v[98:101], v[196:199], v[6:21]
	s_waitcnt vmcnt(10)
	ds_read_b128 v[38:41], v5 offset:43264
	ds_read_b128 v[42:45], v52 offset:43264
	ds_read_b128 v[46:49], v55 offset:43264
	ds_read_b128 v[196:199], v56 offset:43264
	v_or_b32_e32 v1, 0x80000000, v1
	s_cmpk_gt_i32 s11, 96
	s_cselect_b64 vcc, -1, 0
	v_xor_b32_e32 v0, v1, v0
	v_cndmask_b32_e32 v146, v123, v0, vcc
	s_nop 3
	s_waitcnt lgkmcnt(3)
	v_mfma_f32_32x32x16_bf16 v[212:227], v[70:73], v[38:41], 0
	v_max_f32_e32 v108, 0, v6
	v_max_f32_e32 v109, 0, v7
	v_pk_mul_f32 v[50:51], v[244:245], v[108:109]
	v_max_f32_e32 v210, 0, v8
	v_max_f32_e32 v211, 0, v9
	v_pk_fma_f32 v[50:51], v[246:247], v[210:211], v[50:51]
	v_max_f32_e32 v108, 0, v10
	v_max_f32_e32 v109, 0, v11
	v_pk_fma_f32 v[50:51], v[248:249], v[108:109], v[50:51]
	s_waitcnt lgkmcnt(2)
	v_mfma_f32_32x32x16_bf16 v[212:227], v[74:77], v[42:45], v[212:227]
	v_max_f32_e32 v210, 0, v12
	v_max_f32_e32 v211, 0, v13
	v_pk_fma_f32 v[50:51], v[250:251], v[210:211], v[50:51]
	v_max_f32_e32 v108, 0, v14
	v_max_f32_e32 v109, 0, v15
	v_pk_fma_f32 v[50:51], v[252:253], v[108:109], v[50:51]
	v_max_f32_e32 v210, 0, v16
	v_max_f32_e32 v211, 0, v17
	v_pk_fma_f32 v[50:51], v[254:255], v[210:211], v[50:51]
	s_waitcnt lgkmcnt(1)
	v_mfma_f32_32x32x16_bf16 v[212:227], v[78:81], v[46:49], v[212:227]
	v_max_f32_e32 v108, 0, v18
	v_max_f32_e32 v109, 0, v19
	v_pk_fma_f32 v[50:51], v[200:201], v[108:109], v[50:51]
	v_max_f32_e32 v210, 0, v20
	v_max_f32_e32 v211, 0, v21
	v_pk_fma_f32 v[50:51], v[202:203], v[210:211], v[50:51]
	v_add_f32_e32 v50, v50, v51
	v_ashrrev_i32_e32 v51, 31, v50
	s_waitcnt lgkmcnt(0)
	v_mfma_f32_32x32x16_bf16 v[212:227], v[82:85], v[196:199], v[212:227]
	v_or_b32_e32 v51, 0x80000000, v51
	s_cmpk_gt_i32 s11, 96
	s_cselect_b64 vcc, -1, 0
	v_xor_b32_e32 v50, v51, v50
	v_cndmask_b32_e32 v50, v123, v50, vcc
	global_store_dword v243, v50, s[8:9]
	v_mfma_f32_32x32x16_bf16 v[6:21], v[86:89], v[38:41], 0
	s_add_i32 m0, s10, 0
	s_nop 0
	global_load_lds_dwordx4 v102, s[6:7]
	s_add_i32 m0, s10, 1024
	s_nop 0
	global_load_lds_dwordx4 v110, s[6:7]
	s_add_i32 m0, s10, 2048
	s_nop 0
	global_load_lds_dwordx4 v112, s[6:7]
	s_add_i32 m0, s10, 3072
	s_nop 0
	global_load_lds_dwordx4 v193, s[6:7]
	s_add_u32 s6, s6, 0x8000
	s_addc_u32 s7, s7, 0
	v_max_f32_e32 v108, 0, v212
	v_max_f32_e32 v109, 0, v213
	v_pk_mul_f32 v[0:1], v[22:23], v[108:109]
	v_max_f32_e32 v210, 0, v214
	v_max_f32_e32 v211, 0, v215
	v_pk_fma_f32 v[0:1], v[24:25], v[210:211], v[0:1]
	v_max_f32_e32 v108, 0, v216
	v_max_f32_e32 v109, 0, v217
	v_pk_fma_f32 v[0:1], v[26:27], v[108:109], v[0:1]
	v_mfma_f32_32x32x16_bf16 v[6:21], v[90:93], v[42:45], v[6:21]
	v_max_f32_e32 v210, 0, v218
	v_max_f32_e32 v211, 0, v219
	v_pk_fma_f32 v[0:1], v[28:29], v[210:211], v[0:1]
	v_max_f32_e32 v108, 0, v220
	v_max_f32_e32 v109, 0, v221
	v_pk_fma_f32 v[0:1], v[30:31], v[108:109], v[0:1]
	v_max_f32_e32 v210, 0, v222
	v_max_f32_e32 v211, 0, v223
	v_pk_fma_f32 v[0:1], v[32:33], v[210:211], v[0:1]
	v_mfma_f32_32x32x16_bf16 v[6:21], v[94:97], v[46:49], v[6:21]
	v_max_f32_e32 v108, 0, v224
	v_max_f32_e32 v109, 0, v225
	v_pk_fma_f32 v[0:1], v[34:35], v[108:109], v[0:1]
	v_max_f32_e32 v210, 0, v226
	v_max_f32_e32 v211, 0, v227
	v_pk_fma_f32 v[0:1], v[36:37], v[210:211], v[0:1]
	v_add_f32_e32 v0, v0, v1
	v_ashrrev_i32_e32 v1, 31, v0
	v_mfma_f32_32x32x16_bf16 v[6:21], v[98:101], v[196:199], v[6:21]
	s_waitcnt vmcnt(10)
	v_add_u32_e32 v228, 0x10000, v5
	ds_read_b128 v[38:41], v228 offset:10496
	v_add_u32_e32 v228, 0x10000, v52
	ds_read_b128 v[42:45], v228 offset:10496
	v_add_u32_e32 v228, 0x10000, v55
	ds_read_b128 v[46:49], v228 offset:10496
	v_add_u32_e32 v228, 0x10000, v56
	ds_read_b128 v[196:199], v228 offset:10496
	v_or_b32_e32 v1, 0x80000000, v1
	s_cmpk_gt_i32 s11, 104
	s_cselect_b64 vcc, -1, 0
	v_xor_b32_e32 v0, v1, v0
	v_cndmask_b32_e32 v145, v123, v0, vcc
	s_nop 3
	s_waitcnt lgkmcnt(3)
	v_mfma_f32_32x32x16_bf16 v[212:227], v[70:73], v[38:41], 0
	v_max_f32_e32 v108, 0, v6
	v_max_f32_e32 v109, 0, v7
	v_pk_mul_f32 v[50:51], v[244:245], v[108:109]
	v_max_f32_e32 v210, 0, v8
	v_max_f32_e32 v211, 0, v9
	v_pk_fma_f32 v[50:51], v[246:247], v[210:211], v[50:51]
	v_max_f32_e32 v108, 0, v10
	v_max_f32_e32 v109, 0, v11
	v_pk_fma_f32 v[50:51], v[248:249], v[108:109], v[50:51]
	s_waitcnt lgkmcnt(2)
	v_mfma_f32_32x32x16_bf16 v[212:227], v[74:77], v[42:45], v[212:227]
	v_max_f32_e32 v210, 0, v12
	v_max_f32_e32 v211, 0, v13
	v_pk_fma_f32 v[50:51], v[250:251], v[210:211], v[50:51]
	v_max_f32_e32 v108, 0, v14
	v_max_f32_e32 v109, 0, v15
	v_pk_fma_f32 v[50:51], v[252:253], v[108:109], v[50:51]
	v_max_f32_e32 v210, 0, v16
	v_max_f32_e32 v211, 0, v17
	v_pk_fma_f32 v[50:51], v[254:255], v[210:211], v[50:51]
	s_waitcnt lgkmcnt(1)
	v_mfma_f32_32x32x16_bf16 v[212:227], v[78:81], v[46:49], v[212:227]
	v_max_f32_e32 v108, 0, v18
	v_max_f32_e32 v109, 0, v19
	v_pk_fma_f32 v[50:51], v[200:201], v[108:109], v[50:51]
	v_max_f32_e32 v210, 0, v20
	v_max_f32_e32 v211, 0, v21
	v_pk_fma_f32 v[50:51], v[202:203], v[210:211], v[50:51]
	v_add_f32_e32 v50, v50, v51
	v_ashrrev_i32_e32 v51, 31, v50
	s_waitcnt lgkmcnt(0)
	v_mfma_f32_32x32x16_bf16 v[212:227], v[82:85], v[196:199], v[212:227]
	v_or_b32_e32 v51, 0x80000000, v51
	s_cmpk_gt_i32 s11, 104
	s_cselect_b64 vcc, -1, 0
	v_xor_b32_e32 v50, v51, v50
	v_cndmask_b32_e32 v50, v123, v50, vcc
	global_store_dword v243, v50, s[8:9] offset:2048
	s_add_u32 s8, s8, 0x1000
	s_addc_u32 s9, s9, 0
	v_mfma_f32_32x32x16_bf16 v[6:21], v[86:89], v[38:41], 0
	s_add_i32 m0, s10, 32768
	s_nop 0
	global_load_lds_dwordx4 v102, s[6:7]
	s_add_i32 m0, s10, 33792
	s_nop 0
	global_load_lds_dwordx4 v110, s[6:7]
	s_add_i32 m0, s10, 34816
	s_nop 0
	global_load_lds_dwordx4 v112, s[6:7]
	s_add_i32 m0, s10, 35840
	s_nop 0
	global_load_lds_dwordx4 v193, s[6:7]
	s_add_u32 s6, s6, 0x8000
	s_addc_u32 s7, s7, 0
	v_max_f32_e32 v108, 0, v212
	v_max_f32_e32 v109, 0, v213
	v_pk_mul_f32 v[0:1], v[22:23], v[108:109]
	v_max_f32_e32 v210, 0, v214
	v_max_f32_e32 v211, 0, v215
	v_pk_fma_f32 v[0:1], v[24:25], v[210:211], v[0:1]
	v_max_f32_e32 v108, 0, v216
	v_max_f32_e32 v109, 0, v217
	v_pk_fma_f32 v[0:1], v[26:27], v[108:109], v[0:1]
	v_mfma_f32_32x32x16_bf16 v[6:21], v[90:93], v[42:45], v[6:21]
	v_max_f32_e32 v210, 0, v218
	v_max_f32_e32 v211, 0, v219
	v_pk_fma_f32 v[0:1], v[28:29], v[210:211], v[0:1]
	v_max_f32_e32 v108, 0, v220
	v_max_f32_e32 v109, 0, v221
	v_pk_fma_f32 v[0:1], v[30:31], v[108:109], v[0:1]
	v_max_f32_e32 v210, 0, v222
	v_max_f32_e32 v211, 0, v223
	v_pk_fma_f32 v[0:1], v[32:33], v[210:211], v[0:1]
	v_mfma_f32_32x32x16_bf16 v[6:21], v[94:97], v[46:49], v[6:21]
	v_max_f32_e32 v108, 0, v224
	v_max_f32_e32 v109, 0, v225
	v_pk_fma_f32 v[0:1], v[34:35], v[108:109], v[0:1]
	v_max_f32_e32 v210, 0, v226
	v_max_f32_e32 v211, 0, v227
	v_pk_fma_f32 v[0:1], v[36:37], v[210:211], v[0:1]
	v_add_f32_e32 v0, v0, v1
	v_ashrrev_i32_e32 v1, 31, v0
	v_mfma_f32_32x32x16_bf16 v[6:21], v[98:101], v[196:199], v[6:21]
	s_waitcnt vmcnt(10)
	v_add_u32_e32 v228, 0x10000, v5
	ds_read_b128 v[38:41], v228 offset:43264
	v_add_u32_e32 v228, 0x10000, v52
	ds_read_b128 v[42:45], v228 offset:43264
	v_add_u32_e32 v228, 0x10000, v55
	ds_read_b128 v[46:49], v228 offset:43264
	v_add_u32_e32 v228, 0x10000, v56
	ds_read_b128 v[196:199], v228 offset:43264
	v_or_b32_e32 v1, 0x80000000, v1
	s_cmpk_gt_i32 s11, 112
	s_cselect_b64 vcc, -1, 0
	v_xor_b32_e32 v0, v1, v0
	v_cndmask_b32_e32 v147, v123, v0, vcc
	s_nop 3
	s_waitcnt lgkmcnt(3)
	v_mfma_f32_32x32x16_bf16 v[212:227], v[70:73], v[38:41], 0
	v_max_f32_e32 v108, 0, v6
	v_max_f32_e32 v109, 0, v7
	v_pk_mul_f32 v[50:51], v[244:245], v[108:109]
	v_max_f32_e32 v210, 0, v8
	v_max_f32_e32 v211, 0, v9
	v_pk_fma_f32 v[50:51], v[246:247], v[210:211], v[50:51]
	v_max_f32_e32 v108, 0, v10
	v_max_f32_e32 v109, 0, v11
	v_pk_fma_f32 v[50:51], v[248:249], v[108:109], v[50:51]
	s_waitcnt lgkmcnt(2)
	v_mfma_f32_32x32x16_bf16 v[212:227], v[74:77], v[42:45], v[212:227]
	v_max_f32_e32 v210, 0, v12
	v_max_f32_e32 v211, 0, v13
	v_pk_fma_f32 v[50:51], v[250:251], v[210:211], v[50:51]
	v_max_f32_e32 v108, 0, v14
	v_max_f32_e32 v109, 0, v15
	v_pk_fma_f32 v[50:51], v[252:253], v[108:109], v[50:51]
	v_max_f32_e32 v210, 0, v16
	v_max_f32_e32 v211, 0, v17
	v_pk_fma_f32 v[50:51], v[254:255], v[210:211], v[50:51]
	s_waitcnt lgkmcnt(1)
	v_mfma_f32_32x32x16_bf16 v[212:227], v[78:81], v[46:49], v[212:227]
	v_max_f32_e32 v108, 0, v18
	v_max_f32_e32 v109, 0, v19
	v_pk_fma_f32 v[50:51], v[200:201], v[108:109], v[50:51]
	v_max_f32_e32 v210, 0, v20
	v_max_f32_e32 v211, 0, v21
	v_pk_fma_f32 v[50:51], v[202:203], v[210:211], v[50:51]
	v_add_f32_e32 v50, v50, v51
	v_ashrrev_i32_e32 v51, 31, v50
	s_waitcnt lgkmcnt(0)
	v_mfma_f32_32x32x16_bf16 v[212:227], v[82:85], v[196:199], v[212:227]
	v_or_b32_e32 v51, 0x80000000, v51
	s_cmpk_gt_i32 s11, 112
	s_cselect_b64 vcc, -1, 0
	v_xor_b32_e32 v50, v51, v50
	v_cndmask_b32_e32 v50, v123, v50, vcc
	global_store_dword v243, v50, s[8:9]
	v_mfma_f32_32x32x16_bf16 v[6:21], v[86:89], v[38:41], 0
	s_add_i32 m0, s10, 65536
	s_nop 0
	global_load_lds_dwordx4 v102, s[6:7]
	s_add_i32 m0, s10, 66560
	s_nop 0
	global_load_lds_dwordx4 v110, s[6:7]
	s_add_i32 m0, s10, 67584
	s_nop 0
	global_load_lds_dwordx4 v112, s[6:7]
	s_add_i32 m0, s10, 68608
	s_nop 0
	global_load_lds_dwordx4 v193, s[6:7]
	s_add_u32 s6, s6, 0x8000
	s_addc_u32 s7, s7, 0
	v_max_f32_e32 v108, 0, v212
	v_max_f32_e32 v109, 0, v213
	v_pk_mul_f32 v[0:1], v[22:23], v[108:109]
	v_max_f32_e32 v210, 0, v214
	v_max_f32_e32 v211, 0, v215
	v_pk_fma_f32 v[0:1], v[24:25], v[210:211], v[0:1]
	v_max_f32_e32 v108, 0, v216
	v_max_f32_e32 v109, 0, v217
	v_pk_fma_f32 v[0:1], v[26:27], v[108:109], v[0:1]
	v_mfma_f32_32x32x16_bf16 v[6:21], v[90:93], v[42:45], v[6:21]
	v_max_f32_e32 v210, 0, v218
	v_max_f32_e32 v211, 0, v219
	v_pk_fma_f32 v[0:1], v[28:29], v[210:211], v[0:1]
	v_max_f32_e32 v108, 0, v220
	v_max_f32_e32 v109, 0, v221
	v_pk_fma_f32 v[0:1], v[30:31], v[108:109], v[0:1]
	v_max_f32_e32 v210, 0, v222
	v_max_f32_e32 v211, 0, v223
	v_pk_fma_f32 v[0:1], v[32:33], v[210:211], v[0:1]
	v_mfma_f32_32x32x16_bf16 v[6:21], v[94:97], v[46:49], v[6:21]
	v_max_f32_e32 v108, 0, v224
	v_max_f32_e32 v109, 0, v225
	v_pk_fma_f32 v[0:1], v[34:35], v[108:109], v[0:1]
	v_max_f32_e32 v210, 0, v226
	v_max_f32_e32 v211, 0, v227
	v_pk_fma_f32 v[0:1], v[36:37], v[210:211], v[0:1]
	v_add_f32_e32 v0, v0, v1
	v_ashrrev_i32_e32 v1, 31, v0
	v_mfma_f32_32x32x16_bf16 v[6:21], v[98:101], v[196:199], v[6:21]
	s_waitcnt vmcnt(10)
	ds_read_b128 v[38:41], v5 offset:10496
	ds_read_b128 v[42:45], v52 offset:10496
	ds_read_b128 v[46:49], v55 offset:10496
	ds_read_b128 v[196:199], v56 offset:10496
	v_or_b32_e32 v1, 0x80000000, v1
	s_cmpk_gt_i32 s11, 120
	s_cselect_b64 vcc, -1, 0
	v_xor_b32_e32 v0, v1, v0
	v_cndmask_b32_e32 v136, v123, v0, vcc
	s_nop 3
	v_max_f32_e32 v108, 0, v6
	v_max_f32_e32 v109, 0, v7
	v_pk_mul_f32 v[50:51], v[244:245], v[108:109]
	v_max_f32_e32 v210, 0, v8
	v_max_f32_e32 v211, 0, v9
	v_pk_fma_f32 v[50:51], v[246:247], v[210:211], v[50:51]
	v_max_f32_e32 v108, 0, v10
	v_max_f32_e32 v109, 0, v11
	v_pk_fma_f32 v[50:51], v[248:249], v[108:109], v[50:51]
	v_max_f32_e32 v210, 0, v12
	v_max_f32_e32 v211, 0, v13
	v_pk_fma_f32 v[50:51], v[250:251], v[210:211], v[50:51]
	v_max_f32_e32 v108, 0, v14
	v_max_f32_e32 v109, 0, v15
	v_pk_fma_f32 v[50:51], v[252:253], v[108:109], v[50:51]
	v_max_f32_e32 v210, 0, v16
	v_max_f32_e32 v211, 0, v17
	v_pk_fma_f32 v[50:51], v[254:255], v[210:211], v[50:51]
	v_max_f32_e32 v108, 0, v18
	v_max_f32_e32 v109, 0, v19
	v_pk_fma_f32 v[50:51], v[200:201], v[108:109], v[50:51]
	v_max_f32_e32 v210, 0, v20
	v_max_f32_e32 v211, 0, v21
	v_pk_fma_f32 v[50:51], v[202:203], v[210:211], v[50:51]
	v_add_f32_e32 v50, v50, v51
	v_ashrrev_i32_e32 v51, 31, v50
	v_or_b32_e32 v51, 0x80000000, v51
	s_cmpk_gt_i32 s11, 120
	s_cselect_b64 vcc, -1, 0
	v_xor_b32_e32 v50, v51, v50
	v_cndmask_b32_e32 v50, v123, v50, vcc
	global_store_dword v243, v50, s[8:9] offset:2048
	s_add_u32 s8, s8, 0x1000
	s_addc_u32 s9, s9, 0
	s_cmpk_gt_i32 s81, 16
	s_cbranch_scc0 .Lix_fill_2
	s_waitcnt lgkmcnt(3)
	v_mfma_f32_32x32x16_bf16 v[212:227], v[70:73], v[38:41], 0
	s_add_i32 m0, s10, 98304
	s_nop 0
	global_load_lds_dwordx4 v102, s[6:7]
	s_waitcnt lgkmcnt(2)
	v_mfma_f32_32x32x16_bf16 v[212:227], v[74:77], v[42:45], v[212:227]
	s_add_i32 m0, s10, 99328
	s_nop 0
	global_load_lds_dwordx4 v110, s[6:7]
	s_waitcnt lgkmcnt(1)
	v_mfma_f32_32x32x16_bf16 v[212:227], v[78:81], v[46:49], v[212:227]
	s_add_i32 m0, s10, 100352
	s_nop 0
	global_load_lds_dwordx4 v112, s[6:7]
	s_waitcnt lgkmcnt(0)
	v_mfma_f32_32x32x16_bf16 v[212:227], v[82:85], v[196:199], v[212:227]
	s_add_i32 m0, s10, 101376
	s_nop 0
	global_load_lds_dwordx4 v193, s[6:7]
	s_add_u32 s6, s6, 0x8000
	s_addc_u32 s7, s7, 0
	v_mfma_f32_32x32x16_bf16 v[6:21], v[86:89], v[38:41], 0
	s_nop 7
	s_nop 2
	v_max_f32_e32 v108, 0, v212
	v_max_f32_e32 v109, 0, v213
	v_pk_mul_f32 v[0:1], v[22:23], v[108:109]
	v_max_f32_e32 v210, 0, v214
	v_max_f32_e32 v211, 0, v215
	v_pk_fma_f32 v[0:1], v[24:25], v[210:211], v[0:1]
	v_max_f32_e32 v108, 0, v216
	v_max_f32_e32 v109, 0, v217
	v_pk_fma_f32 v[0:1], v[26:27], v[108:109], v[0:1]
	v_mfma_f32_32x32x16_bf16 v[6:21], v[90:93], v[42:45], v[6:21]
	v_max_f32_e32 v210, 0, v218
	v_max_f32_e32 v211, 0, v219
	v_pk_fma_f32 v[0:1], v[28:29], v[210:211], v[0:1]
	v_max_f32_e32 v108, 0, v220
	v_max_f32_e32 v109, 0, v221
	v_pk_fma_f32 v[0:1], v[30:31], v[108:109], v[0:1]
	v_max_f32_e32 v210, 0, v222
	v_max_f32_e32 v211, 0, v223
	v_pk_fma_f32 v[0:1], v[32:33], v[210:211], v[0:1]
	v_mfma_f32_32x32x16_bf16 v[6:21], v[94:97], v[46:49], v[6:21]
	v_max_f32_e32 v108, 0, v224
	v_max_f32_e32 v109, 0, v225
	v_pk_fma_f32 v[0:1], v[34:35], v[108:109], v[0:1]
	v_max_f32_e32 v210, 0, v226
	v_max_f32_e32 v211, 0, v227
	v_pk_fma_f32 v[0:1], v[36:37], v[210:211], v[0:1]
	v_add_f32_e32 v0, v0, v1
	v_ashrrev_i32_e32 v1, 31, v0
	v_mfma_f32_32x32x16_bf16 v[6:21], v[98:101], v[196:199], v[6:21]
	s_waitcnt vmcnt(10)
	ds_read_b128 v[38:41], v5 offset:43264
	ds_read_b128 v[42:45], v52 offset:43264
	ds_read_b128 v[46:49], v55 offset:43264
	ds_read_b128 v[196:199], v56 offset:43264
	v_or_b32_e32 v1, 0x80000000, v1
	s_cmpk_gt_i32 s11, 128
	s_cselect_b64 vcc, -1, 0
	v_xor_b32_e32 v0, v1, v0
	v_cndmask_b32_e32 v149, v123, v0, vcc
	s_nop 3
	s_waitcnt lgkmcnt(3)
	v_mfma_f32_32x32x16_bf16 v[212:227], v[70:73], v[38:41], 0
	v_max_f32_e32 v108, 0, v6
	v_max_f32_e32 v109, 0, v7
	v_pk_mul_f32 v[50:51], v[244:245], v[108:109]
	v_max_f32_e32 v210, 0, v8
	v_max_f32_e32 v211, 0, v9
	v_pk_fma_f32 v[50:51], v[246:247], v[210:211], v[50:51]
	v_max_f32_e32 v108, 0, v10
	v_max_f32_e32 v109, 0, v11
	v_pk_fma_f32 v[50:51], v[248:249], v[108:109], v[50:51]
	s_waitcnt lgkmcnt(2)
	v_mfma_f32_32x32x16_bf16 v[212:227], v[74:77], v[42:45], v[212:227]
	v_max_f32_e32 v210, 0, v12
	v_max_f32_e32 v211, 0, v13
	v_pk_fma_f32 v[50:51], v[250:251], v[210:211], v[50:51]
	v_max_f32_e32 v108, 0, v14
	v_max_f32_e32 v109, 0, v15
	v_pk_fma_f32 v[50:51], v[252:253], v[108:109], v[50:51]
	v_max_f32_e32 v210, 0, v16
	v_max_f32_e32 v211, 0, v17
	v_pk_fma_f32 v[50:51], v[254:255], v[210:211], v[50:51]
	s_waitcnt lgkmcnt(1)
	v_mfma_f32_32x32x16_bf16 v[212:227], v[78:81], v[46:49], v[212:227]
	v_max_f32_e32 v108, 0, v18
	v_max_f32_e32 v109, 0, v19
	v_pk_fma_f32 v[50:51], v[200:201], v[108:109], v[50:51]
	v_max_f32_e32 v210, 0, v20
	v_max_f32_e32 v211, 0, v21
	v_pk_fma_f32 v[50:51], v[202:203], v[210:211], v[50:51]
	v_add_f32_e32 v50, v50, v51
	v_ashrrev_i32_e32 v51, 31, v50
	s_waitcnt lgkmcnt(0)
	v_mfma_f32_32x32x16_bf16 v[212:227], v[82:85], v[196:199], v[212:227]
	v_or_b32_e32 v51, 0x80000000, v51
	s_cmpk_gt_i32 s11, 128
	s_cselect_b64 vcc, -1, 0
	v_xor_b32_e32 v50, v51, v50
	v_cndmask_b32_e32 v50, v123, v50, vcc
	global_store_dword v243, v50, s[8:9]
	v_mfma_f32_32x32x16_bf16 v[6:21], v[86:89], v[38:41], 0
	s_add_i32 m0, s10, 0
	s_nop 0
	global_load_lds_dwordx4 v102, s[6:7]
	s_add_i32 m0, s10, 1024
	s_nop 0
	global_load_lds_dwordx4 v110, s[6:7]
	s_add_i32 m0, s10, 2048
	s_nop 0
	global_load_lds_dwordx4 v112, s[6:7]
	s_add_i32 m0, s10, 3072
	s_nop 0
	global_load_lds_dwordx4 v193, s[6:7]
	s_add_u32 s6, s6, 0x8000
	s_addc_u32 s7, s7, 0
	v_max_f32_e32 v108, 0, v212
	v_max_f32_e32 v109, 0, v213
	v_pk_mul_f32 v[0:1], v[22:23], v[108:109]
	v_max_f32_e32 v210, 0, v214
	v_max_f32_e32 v211, 0, v215
	v_pk_fma_f32 v[0:1], v[24:25], v[210:211], v[0:1]
	v_max_f32_e32 v108, 0, v216
	v_max_f32_e32 v109, 0, v217
	v_pk_fma_f32 v[0:1], v[26:27], v[108:109], v[0:1]
	v_mfma_f32_32x32x16_bf16 v[6:21], v[90:93], v[42:45], v[6:21]
	v_max_f32_e32 v210, 0, v218
	v_max_f32_e32 v211, 0, v219
	v_pk_fma_f32 v[0:1], v[28:29], v[210:211], v[0:1]
	v_max_f32_e32 v108, 0, v220
	v_max_f32_e32 v109, 0, v221
	v_pk_fma_f32 v[0:1], v[30:31], v[108:109], v[0:1]
	v_max_f32_e32 v210, 0, v222
	v_max_f32_e32 v211, 0, v223
	v_pk_fma_f32 v[0:1], v[32:33], v[210:211], v[0:1]
	v_mfma_f32_32x32x16_bf16 v[6:21], v[94:97], v[46:49], v[6:21]
	v_max_f32_e32 v108, 0, v224
	v_max_f32_e32 v109, 0, v225
	v_pk_fma_f32 v[0:1], v[34:35], v[108:109], v[0:1]
	v_max_f32_e32 v210, 0, v226
	v_max_f32_e32 v211, 0, v227
	v_pk_fma_f32 v[0:1], v[36:37], v[210:211], v[0:1]
	v_add_f32_e32 v0, v0, v1
	v_ashrrev_i32_e32 v1, 31, v0
	v_mfma_f32_32x32x16_bf16 v[6:21], v[98:101], v[196:199], v[6:21]
	s_waitcnt vmcnt(10)
	v_add_u32_e32 v228, 0x10000, v5
	ds_read_b128 v[38:41], v228 offset:10496
	v_add_u32_e32 v228, 0x10000, v52
	ds_read_b128 v[42:45], v228 offset:10496
	v_add_u32_e32 v228, 0x10000, v55
	ds_read_b128 v[46:49], v228 offset:10496
	v_add_u32_e32 v228, 0x10000, v56
	ds_read_b128 v[196:199], v228 offset:10496
	v_or_b32_e32 v1, 0x80000000, v1
	s_cmpk_gt_i32 s11, 136
	s_cselect_b64 vcc, -1, 0
	v_xor_b32_e32 v0, v1, v0
	v_cndmask_b32_e32 v148, v123, v0, vcc
	s_nop 3
	s_waitcnt lgkmcnt(3)
	v_mfma_f32_32x32x16_bf16 v[212:227], v[70:73], v[38:41], 0
	v_max_f32_e32 v108, 0, v6
	v_max_f32_e32 v109, 0, v7
	v_pk_mul_f32 v[50:51], v[244:245], v[108:109]
	v_max_f32_e32 v210, 0, v8
	v_max_f32_e32 v211, 0, v9
	v_pk_fma_f32 v[50:51], v[246:247], v[210:211], v[50:51]
	v_max_f32_e32 v108, 0, v10
	v_max_f32_e32 v109, 0, v11
	v_pk_fma_f32 v[50:51], v[248:249], v[108:109], v[50:51]
	s_waitcnt lgkmcnt(2)
	v_mfma_f32_32x32x16_bf16 v[212:227], v[74:77], v[42:45], v[212:227]
	v_max_f32_e32 v210, 0, v12
	v_max_f32_e32 v211, 0, v13
	v_pk_fma_f32 v[50:51], v[250:251], v[210:211], v[50:51]
	v_max_f32_e32 v108, 0, v14
	v_max_f32_e32 v109, 0, v15
	v_pk_fma_f32 v[50:51], v[252:253], v[108:109], v[50:51]
	v_max_f32_e32 v210, 0, v16
	v_max_f32_e32 v211, 0, v17
	v_pk_fma_f32 v[50:51], v[254:255], v[210:211], v[50:51]
	s_waitcnt lgkmcnt(1)
	v_mfma_f32_32x32x16_bf16 v[212:227], v[78:81], v[46:49], v[212:227]
	v_max_f32_e32 v108, 0, v18
	v_max_f32_e32 v109, 0, v19
	v_pk_fma_f32 v[50:51], v[200:201], v[108:109], v[50:51]
	v_max_f32_e32 v210, 0, v20
	v_max_f32_e32 v211, 0, v21
	v_pk_fma_f32 v[50:51], v[202:203], v[210:211], v[50:51]
	v_add_f32_e32 v50, v50, v51
	v_ashrrev_i32_e32 v51, 31, v50
	s_waitcnt lgkmcnt(0)
	v_mfma_f32_32x32x16_bf16 v[212:227], v[82:85], v[196:199], v[212:227]
	v_or_b32_e32 v51, 0x80000000, v51
	s_cmpk_gt_i32 s11, 136
	s_cselect_b64 vcc, -1, 0
	v_xor_b32_e32 v50, v51, v50
	v_cndmask_b32_e32 v50, v123, v50, vcc
	global_store_dword v243, v50, s[8:9] offset:2048
	s_add_u32 s8, s8, 0x1000
	s_addc_u32 s9, s9, 0
	v_mfma_f32_32x32x16_bf16 v[6:21], v[86:89], v[38:41], 0
	s_add_i32 m0, s10, 32768
	s_nop 0
	global_load_lds_dwordx4 v102, s[6:7]
	s_add_i32 m0, s10, 33792
	s_nop 0
	global_load_lds_dwordx4 v110, s[6:7]
	s_add_i32 m0, s10, 34816
	s_nop 0
	global_load_lds_dwordx4 v112, s[6:7]
	s_add_i32 m0, s10, 35840
	s_nop 0
	global_load_lds_dwordx4 v193, s[6:7]
	s_add_u32 s6, s6, 0x8000
	s_addc_u32 s7, s7, 0
	v_max_f32_e32 v108, 0, v212
	v_max_f32_e32 v109, 0, v213
	v_pk_mul_f32 v[0:1], v[22:23], v[108:109]
	v_max_f32_e32 v210, 0, v214
	v_max_f32_e32 v211, 0, v215
	v_pk_fma_f32 v[0:1], v[24:25], v[210:211], v[0:1]
	v_max_f32_e32 v108, 0, v216
	v_max_f32_e32 v109, 0, v217
	v_pk_fma_f32 v[0:1], v[26:27], v[108:109], v[0:1]
	v_mfma_f32_32x32x16_bf16 v[6:21], v[90:93], v[42:45], v[6:21]
	v_max_f32_e32 v210, 0, v218
	v_max_f32_e32 v211, 0, v219
	v_pk_fma_f32 v[0:1], v[28:29], v[210:211], v[0:1]
	v_max_f32_e32 v108, 0, v220
	v_max_f32_e32 v109, 0, v221
	v_pk_fma_f32 v[0:1], v[30:31], v[108:109], v[0:1]
	v_max_f32_e32 v210, 0, v222
	v_max_f32_e32 v211, 0, v223
	v_pk_fma_f32 v[0:1], v[32:33], v[210:211], v[0:1]
	v_mfma_f32_32x32x16_bf16 v[6:21], v[94:97], v[46:49], v[6:21]
	v_max_f32_e32 v108, 0, v224
	v_max_f32_e32 v109, 0, v225
	v_pk_fma_f32 v[0:1], v[34:35], v[108:109], v[0:1]
	v_max_f32_e32 v210, 0, v226
	v_max_f32_e32 v211, 0, v227
	v_pk_fma_f32 v[0:1], v[36:37], v[210:211], v[0:1]
	v_add_f32_e32 v0, v0, v1
	v_ashrrev_i32_e32 v1, 31, v0
	v_mfma_f32_32x32x16_bf16 v[6:21], v[98:101], v[196:199], v[6:21]
	s_waitcnt vmcnt(10)
	v_add_u32_e32 v228, 0x10000, v5
	ds_read_b128 v[38:41], v228 offset:43264
	v_add_u32_e32 v228, 0x10000, v52
	ds_read_b128 v[42:45], v228 offset:43264
	v_add_u32_e32 v228, 0x10000, v55
	ds_read_b128 v[46:49], v228 offset:43264
	v_add_u32_e32 v228, 0x10000, v56
	ds_read_b128 v[196:199], v228 offset:43264
	v_or_b32_e32 v1, 0x80000000, v1
	s_cmpk_gt_i32 s11, 144
	s_cselect_b64 vcc, -1, 0
	v_xor_b32_e32 v0, v1, v0
	v_cndmask_b32_e32 v151, v123, v0, vcc
	s_nop 3
	s_waitcnt lgkmcnt(3)
	v_mfma_f32_32x32x16_bf16 v[212:227], v[70:73], v[38:41], 0
	v_max_f32_e32 v108, 0, v6
	v_max_f32_e32 v109, 0, v7
	v_pk_mul_f32 v[50:51], v[244:245], v[108:109]
	v_max_f32_e32 v210, 0, v8
	v_max_f32_e32 v211, 0, v9
	v_pk_fma_f32 v[50:51], v[246:247], v[210:211], v[50:51]
	v_max_f32_e32 v108, 0, v10
	v_max_f32_e32 v109, 0, v11
	v_pk_fma_f32 v[50:51], v[248:249], v[108:109], v[50:51]
	s_waitcnt lgkmcnt(2)
	v_mfma_f32_32x32x16_bf16 v[212:227], v[74:77], v[42:45], v[212:227]
	v_max_f32_e32 v210, 0, v12
	v_max_f32_e32 v211, 0, v13
	v_pk_fma_f32 v[50:51], v[250:251], v[210:211], v[50:51]
	v_max_f32_e32 v108, 0, v14
	v_max_f32_e32 v109, 0, v15
	v_pk_fma_f32 v[50:51], v[252:253], v[108:109], v[50:51]
	v_max_f32_e32 v210, 0, v16
	v_max_f32_e32 v211, 0, v17
	v_pk_fma_f32 v[50:51], v[254:255], v[210:211], v[50:51]
	s_waitcnt lgkmcnt(1)
	v_mfma_f32_32x32x16_bf16 v[212:227], v[78:81], v[46:49], v[212:227]
	v_max_f32_e32 v108, 0, v18
	v_max_f32_e32 v109, 0, v19
	v_pk_fma_f32 v[50:51], v[200:201], v[108:109], v[50:51]
	v_max_f32_e32 v210, 0, v20
	v_max_f32_e32 v211, 0, v21
	v_pk_fma_f32 v[50:51], v[202:203], v[210:211], v[50:51]
	v_add_f32_e32 v50, v50, v51
	v_ashrrev_i32_e32 v51, 31, v50
	s_waitcnt lgkmcnt(0)
	v_mfma_f32_32x32x16_bf16 v[212:227], v[82:85], v[196:199], v[212:227]
	v_or_b32_e32 v51, 0x80000000, v51
	s_cmpk_gt_i32 s11, 144
	s_cselect_b64 vcc, -1, 0
	v_xor_b32_e32 v50, v51, v50
	v_cndmask_b32_e32 v50, v123, v50, vcc
	global_store_dword v243, v50, s[8:9]
	v_mfma_f32_32x32x16_bf16 v[6:21], v[86:89], v[38:41], 0
	s_add_i32 m0, s10, 65536
	s_nop 0
	global_load_lds_dwordx4 v102, s[6:7]
	s_add_i32 m0, s10, 66560
	s_nop 0
	global_load_lds_dwordx4 v110, s[6:7]
	s_add_i32 m0, s10, 67584
	s_nop 0
	global_load_lds_dwordx4 v112, s[6:7]
	s_add_i32 m0, s10, 68608
	s_nop 0
	global_load_lds_dwordx4 v193, s[6:7]
	s_add_u32 s6, s6, 0x8000
	s_addc_u32 s7, s7, 0
	v_max_f32_e32 v108, 0, v212
	v_max_f32_e32 v109, 0, v213
	v_pk_mul_f32 v[0:1], v[22:23], v[108:109]
	v_max_f32_e32 v210, 0, v214
	v_max_f32_e32 v211, 0, v215
	v_pk_fma_f32 v[0:1], v[24:25], v[210:211], v[0:1]
	v_max_f32_e32 v108, 0, v216
	v_max_f32_e32 v109, 0, v217
	v_pk_fma_f32 v[0:1], v[26:27], v[108:109], v[0:1]
	v_mfma_f32_32x32x16_bf16 v[6:21], v[90:93], v[42:45], v[6:21]
	v_max_f32_e32 v210, 0, v218
	v_max_f32_e32 v211, 0, v219
	v_pk_fma_f32 v[0:1], v[28:29], v[210:211], v[0:1]
	v_max_f32_e32 v108, 0, v220
	v_max_f32_e32 v109, 0, v221
	v_pk_fma_f32 v[0:1], v[30:31], v[108:109], v[0:1]
	v_max_f32_e32 v210, 0, v222
	v_max_f32_e32 v211, 0, v223
	v_pk_fma_f32 v[0:1], v[32:33], v[210:211], v[0:1]
	v_mfma_f32_32x32x16_bf16 v[6:21], v[94:97], v[46:49], v[6:21]
	v_max_f32_e32 v108, 0, v224
	v_max_f32_e32 v109, 0, v225
	v_pk_fma_f32 v[0:1], v[34:35], v[108:109], v[0:1]
	v_max_f32_e32 v210, 0, v226
	v_max_f32_e32 v211, 0, v227
	v_pk_fma_f32 v[0:1], v[36:37], v[210:211], v[0:1]
	v_add_f32_e32 v0, v0, v1
	v_ashrrev_i32_e32 v1, 31, v0
	v_mfma_f32_32x32x16_bf16 v[6:21], v[98:101], v[196:199], v[6:21]
	s_waitcnt vmcnt(10)
	ds_read_b128 v[38:41], v5 offset:10496
	ds_read_b128 v[42:45], v52 offset:10496
	ds_read_b128 v[46:49], v55 offset:10496
	ds_read_b128 v[196:199], v56 offset:10496
	v_or_b32_e32 v1, 0x80000000, v1
	s_cmpk_gt_i32 s11, 152
	s_cselect_b64 vcc, -1, 0
	v_xor_b32_e32 v0, v1, v0
	v_cndmask_b32_e32 v150, v123, v0, vcc
	s_nop 3
	s_waitcnt lgkmcnt(3)
	v_mfma_f32_32x32x16_bf16 v[212:227], v[70:73], v[38:41], 0
	v_max_f32_e32 v108, 0, v6
	v_max_f32_e32 v109, 0, v7
	v_pk_mul_f32 v[50:51], v[244:245], v[108:109]
	v_max_f32_e32 v210, 0, v8
	v_max_f32_e32 v211, 0, v9
	v_pk_fma_f32 v[50:51], v[246:247], v[210:211], v[50:51]
	v_max_f32_e32 v108, 0, v10
	v_max_f32_e32 v109, 0, v11
	v_pk_fma_f32 v[50:51], v[248:249], v[108:109], v[50:51]
	s_waitcnt lgkmcnt(2)
	v_mfma_f32_32x32x16_bf16 v[212:227], v[74:77], v[42:45], v[212:227]
	v_max_f32_e32 v210, 0, v12
	v_max_f32_e32 v211, 0, v13
	v_pk_fma_f32 v[50:51], v[250:251], v[210:211], v[50:51]
	v_max_f32_e32 v108, 0, v14
	v_max_f32_e32 v109, 0, v15
	v_pk_fma_f32 v[50:51], v[252:253], v[108:109], v[50:51]
	v_max_f32_e32 v210, 0, v16
	v_max_f32_e32 v211, 0, v17
	v_pk_fma_f32 v[50:51], v[254:255], v[210:211], v[50:51]
	s_waitcnt lgkmcnt(1)
	v_mfma_f32_32x32x16_bf16 v[212:227], v[78:81], v[46:49], v[212:227]
	v_max_f32_e32 v108, 0, v18
	v_max_f32_e32 v109, 0, v19
	v_pk_fma_f32 v[50:51], v[200:201], v[108:109], v[50:51]
	v_max_f32_e32 v210, 0, v20
	v_max_f32_e32 v211, 0, v21
	v_pk_fma_f32 v[50:51], v[202:203], v[210:211], v[50:51]
	v_add_f32_e32 v50, v50, v51
	v_ashrrev_i32_e32 v51, 31, v50
	s_waitcnt lgkmcnt(0)
	v_mfma_f32_32x32x16_bf16 v[212:227], v[82:85], v[196:199], v[212:227]
	v_or_b32_e32 v51, 0x80000000, v51
	s_cmpk_gt_i32 s11, 152
	s_cselect_b64 vcc, -1, 0
	v_xor_b32_e32 v50, v51, v50
	v_cndmask_b32_e32 v50, v123, v50, vcc
	global_store_dword v243, v50, s[8:9] offset:2048
	s_add_u32 s8, s8, 0x1000
	s_addc_u32 s9, s9, 0
	v_mfma_f32_32x32x16_bf16 v[6:21], v[86:89], v[38:41], 0
	s_add_i32 m0, s10, 98304
	s_nop 0
	global_load_lds_dwordx4 v102, s[6:7]
	s_add_i32 m0, s10, 99328
	s_nop 0
	global_load_lds_dwordx4 v110, s[6:7]
	s_add_i32 m0, s10, 100352
	s_nop 0
	global_load_lds_dwordx4 v112, s[6:7]
	s_add_i32 m0, s10, 101376
	s_nop 0
	global_load_lds_dwordx4 v193, s[6:7]
	s_add_u32 s6, s6, 0x8000
	s_addc_u32 s7, s7, 0
	v_max_f32_e32 v108, 0, v212
	v_max_f32_e32 v109, 0, v213
	v_pk_mul_f32 v[0:1], v[22:23], v[108:109]
	v_max_f32_e32 v210, 0, v214
	v_max_f32_e32 v211, 0, v215
	v_pk_fma_f32 v[0:1], v[24:25], v[210:211], v[0:1]
	v_max_f32_e32 v108, 0, v216
	v_max_f32_e32 v109, 0, v217
	v_pk_fma_f32 v[0:1], v[26:27], v[108:109], v[0:1]
	v_mfma_f32_32x32x16_bf16 v[6:21], v[90:93], v[42:45], v[6:21]
	v_max_f32_e32 v210, 0, v218
	v_max_f32_e32 v211, 0, v219
	v_pk_fma_f32 v[0:1], v[28:29], v[210:211], v[0:1]
	v_max_f32_e32 v108, 0, v220
	v_max_f32_e32 v109, 0, v221
	v_pk_fma_f32 v[0:1], v[30:31], v[108:109], v[0:1]
	v_max_f32_e32 v210, 0, v222
	v_max_f32_e32 v211, 0, v223
	v_pk_fma_f32 v[0:1], v[32:33], v[210:211], v[0:1]
	v_mfma_f32_32x32x16_bf16 v[6:21], v[94:97], v[46:49], v[6:21]
	v_max_f32_e32 v108, 0, v224
	v_max_f32_e32 v109, 0, v225
	v_pk_fma_f32 v[0:1], v[34:35], v[108:109], v[0:1]
	v_max_f32_e32 v210, 0, v226
	v_max_f32_e32 v211, 0, v227
	v_pk_fma_f32 v[0:1], v[36:37], v[210:211], v[0:1]
	v_add_f32_e32 v0, v0, v1
	v_ashrrev_i32_e32 v1, 31, v0
	v_mfma_f32_32x32x16_bf16 v[6:21], v[98:101], v[196:199], v[6:21]
	s_waitcnt vmcnt(10)
	ds_read_b128 v[38:41], v5 offset:43264
	ds_read_b128 v[42:45], v52 offset:43264
	ds_read_b128 v[46:49], v55 offset:43264
	ds_read_b128 v[196:199], v56 offset:43264
	v_or_b32_e32 v1, 0x80000000, v1
	s_cmpk_gt_i32 s11, 160
	s_cselect_b64 vcc, -1, 0
	v_xor_b32_e32 v0, v1, v0
	v_cndmask_b32_e32 v154, v123, v0, vcc
	s_nop 3
	s_waitcnt lgkmcnt(3)
	v_mfma_f32_32x32x16_bf16 v[212:227], v[70:73], v[38:41], 0
	v_max_f32_e32 v108, 0, v6
	v_max_f32_e32 v109, 0, v7
	v_pk_mul_f32 v[50:51], v[244:245], v[108:109]
	v_max_f32_e32 v210, 0, v8
	v_max_f32_e32 v211, 0, v9
	v_pk_fma_f32 v[50:51], v[246:247], v[210:211], v[50:51]
	v_max_f32_e32 v108, 0, v10
	v_max_f32_e32 v109, 0, v11
	v_pk_fma_f32 v[50:51], v[248:249], v[108:109], v[50:51]
	s_waitcnt lgkmcnt(2)
	v_mfma_f32_32x32x16_bf16 v[212:227], v[74:77], v[42:45], v[212:227]
	v_max_f32_e32 v210, 0, v12
	v_max_f32_e32 v211, 0, v13
	v_pk_fma_f32 v[50:51], v[250:251], v[210:211], v[50:51]
	v_max_f32_e32 v108, 0, v14
	v_max_f32_e32 v109, 0, v15
	v_pk_fma_f32 v[50:51], v[252:253], v[108:109], v[50:51]
	v_max_f32_e32 v210, 0, v16
	v_max_f32_e32 v211, 0, v17
	v_pk_fma_f32 v[50:51], v[254:255], v[210:211], v[50:51]
	s_waitcnt lgkmcnt(1)
	v_mfma_f32_32x32x16_bf16 v[212:227], v[78:81], v[46:49], v[212:227]
	v_max_f32_e32 v108, 0, v18
	v_max_f32_e32 v109, 0, v19
	v_pk_fma_f32 v[50:51], v[200:201], v[108:109], v[50:51]
	v_max_f32_e32 v210, 0, v20
	v_max_f32_e32 v211, 0, v21
	v_pk_fma_f32 v[50:51], v[202:203], v[210:211], v[50:51]
	v_add_f32_e32 v50, v50, v51
	v_ashrrev_i32_e32 v51, 31, v50
	s_waitcnt lgkmcnt(0)
	v_mfma_f32_32x32x16_bf16 v[212:227], v[82:85], v[196:199], v[212:227]
	v_or_b32_e32 v51, 0x80000000, v51
	s_cmpk_gt_i32 s11, 160
	s_cselect_b64 vcc, -1, 0
	v_xor_b32_e32 v50, v51, v50
	v_cndmask_b32_e32 v50, v123, v50, vcc
	global_store_dword v243, v50, s[8:9]
	v_mfma_f32_32x32x16_bf16 v[6:21], v[86:89], v[38:41], 0
	s_add_i32 m0, s10, 0
	s_nop 0
	global_load_lds_dwordx4 v102, s[6:7]
	s_add_i32 m0, s10, 1024
	s_nop 0
	global_load_lds_dwordx4 v110, s[6:7]
	s_add_i32 m0, s10, 2048
	s_nop 0
	global_load_lds_dwordx4 v112, s[6:7]
	s_add_i32 m0, s10, 3072
	s_nop 0
	global_load_lds_dwordx4 v193, s[6:7]
	s_add_u32 s6, s6, 0x8000
	s_addc_u32 s7, s7, 0
	v_max_f32_e32 v108, 0, v212
	v_max_f32_e32 v109, 0, v213
	v_pk_mul_f32 v[0:1], v[22:23], v[108:109]
	v_max_f32_e32 v210, 0, v214
	v_max_f32_e32 v211, 0, v215
	v_pk_fma_f32 v[0:1], v[24:25], v[210:211], v[0:1]
	v_max_f32_e32 v108, 0, v216
	v_max_f32_e32 v109, 0, v217
	v_pk_fma_f32 v[0:1], v[26:27], v[108:109], v[0:1]
	v_mfma_f32_32x32x16_bf16 v[6:21], v[90:93], v[42:45], v[6:21]
	v_max_f32_e32 v210, 0, v218
	v_max_f32_e32 v211, 0, v219
	v_pk_fma_f32 v[0:1], v[28:29], v[210:211], v[0:1]
	v_max_f32_e32 v108, 0, v220
	v_max_f32_e32 v109, 0, v221
	v_pk_fma_f32 v[0:1], v[30:31], v[108:109], v[0:1]
	v_max_f32_e32 v210, 0, v222
	v_max_f32_e32 v211, 0, v223
	v_pk_fma_f32 v[0:1], v[32:33], v[210:211], v[0:1]
	v_mfma_f32_32x32x16_bf16 v[6:21], v[94:97], v[46:49], v[6:21]
	v_max_f32_e32 v108, 0, v224
	v_max_f32_e32 v109, 0, v225
	v_pk_fma_f32 v[0:1], v[34:35], v[108:109], v[0:1]
	v_max_f32_e32 v210, 0, v226
	v_max_f32_e32 v211, 0, v227
	v_pk_fma_f32 v[0:1], v[36:37], v[210:211], v[0:1]
	v_add_f32_e32 v0, v0, v1
	v_ashrrev_i32_e32 v1, 31, v0
	v_mfma_f32_32x32x16_bf16 v[6:21], v[98:101], v[196:199], v[6:21]
	s_waitcnt vmcnt(10)
	v_add_u32_e32 v228, 0x10000, v5
	ds_read_b128 v[38:41], v228 offset:10496
	v_add_u32_e32 v228, 0x10000, v52
	ds_read_b128 v[42:45], v228 offset:10496
	v_add_u32_e32 v228, 0x10000, v55
	ds_read_b128 v[46:49], v228 offset:10496
	v_add_u32_e32 v228, 0x10000, v56
	ds_read_b128 v[196:199], v228 offset:10496
	v_or_b32_e32 v1, 0x80000000, v1
	s_cmpk_gt_i32 s11, 168
	s_cselect_b64 vcc, -1, 0
	v_xor_b32_e32 v0, v1, v0
	v_cndmask_b32_e32 v153, v123, v0, vcc
	s_nop 3
	s_waitcnt lgkmcnt(3)
	v_mfma_f32_32x32x16_bf16 v[212:227], v[70:73], v[38:41], 0
	v_max_f32_e32 v108, 0, v6
	v_max_f32_e32 v109, 0, v7
	v_pk_mul_f32 v[50:51], v[244:245], v[108:109]
	v_max_f32_e32 v210, 0, v8
	v_max_f32_e32 v211, 0, v9
	v_pk_fma_f32 v[50:51], v[246:247], v[210:211], v[50:51]
	v_max_f32_e32 v108, 0, v10
	v_max_f32_e32 v109, 0, v11
	v_pk_fma_f32 v[50:51], v[248:249], v[108:109], v[50:51]
	s_waitcnt lgkmcnt(2)
	v_mfma_f32_32x32x16_bf16 v[212:227], v[74:77], v[42:45], v[212:227]
	v_max_f32_e32 v210, 0, v12
	v_max_f32_e32 v211, 0, v13
	v_pk_fma_f32 v[50:51], v[250:251], v[210:211], v[50:51]
	v_max_f32_e32 v108, 0, v14
	v_max_f32_e32 v109, 0, v15
	v_pk_fma_f32 v[50:51], v[252:253], v[108:109], v[50:51]
	v_max_f32_e32 v210, 0, v16
	v_max_f32_e32 v211, 0, v17
	v_pk_fma_f32 v[50:51], v[254:255], v[210:211], v[50:51]
	s_waitcnt lgkmcnt(1)
	v_mfma_f32_32x32x16_bf16 v[212:227], v[78:81], v[46:49], v[212:227]
	v_max_f32_e32 v108, 0, v18
	v_max_f32_e32 v109, 0, v19
	v_pk_fma_f32 v[50:51], v[200:201], v[108:109], v[50:51]
	v_max_f32_e32 v210, 0, v20
	v_max_f32_e32 v211, 0, v21
	v_pk_fma_f32 v[50:51], v[202:203], v[210:211], v[50:51]
	v_add_f32_e32 v50, v50, v51
	v_ashrrev_i32_e32 v51, 31, v50
	s_waitcnt lgkmcnt(0)
	v_mfma_f32_32x32x16_bf16 v[212:227], v[82:85], v[196:199], v[212:227]
	v_or_b32_e32 v51, 0x80000000, v51
	s_cmpk_gt_i32 s11, 168
	s_cselect_b64 vcc, -1, 0
	v_xor_b32_e32 v50, v51, v50
	v_cndmask_b32_e32 v50, v123, v50, vcc
	global_store_dword v243, v50, s[8:9] offset:2048
	s_add_u32 s8, s8, 0x1000
	s_addc_u32 s9, s9, 0
	v_mfma_f32_32x32x16_bf16 v[6:21], v[86:89], v[38:41], 0
	s_add_i32 m0, s10, 32768
	s_nop 0
	global_load_lds_dwordx4 v102, s[6:7]
	s_add_i32 m0, s10, 33792
	s_nop 0
	global_load_lds_dwordx4 v110, s[6:7]
	s_add_i32 m0, s10, 34816
	s_nop 0
	global_load_lds_dwordx4 v112, s[6:7]
	s_add_i32 m0, s10, 35840
	s_nop 0
	global_load_lds_dwordx4 v193, s[6:7]
	s_add_u32 s6, s6, 0x8000
	s_addc_u32 s7, s7, 0
	v_max_f32_e32 v108, 0, v212
	v_max_f32_e32 v109, 0, v213
	v_pk_mul_f32 v[0:1], v[22:23], v[108:109]
	v_max_f32_e32 v210, 0, v214
	v_max_f32_e32 v211, 0, v215
	v_pk_fma_f32 v[0:1], v[24:25], v[210:211], v[0:1]
	v_max_f32_e32 v108, 0, v216
	v_max_f32_e32 v109, 0, v217
	v_pk_fma_f32 v[0:1], v[26:27], v[108:109], v[0:1]
	v_mfma_f32_32x32x16_bf16 v[6:21], v[90:93], v[42:45], v[6:21]
	v_max_f32_e32 v210, 0, v218
	v_max_f32_e32 v211, 0, v219
	v_pk_fma_f32 v[0:1], v[28:29], v[210:211], v[0:1]
	v_max_f32_e32 v108, 0, v220
	v_max_f32_e32 v109, 0, v221
	v_pk_fma_f32 v[0:1], v[30:31], v[108:109], v[0:1]
	v_max_f32_e32 v210, 0, v222
	v_max_f32_e32 v211, 0, v223
	v_pk_fma_f32 v[0:1], v[32:33], v[210:211], v[0:1]
	v_mfma_f32_32x32x16_bf16 v[6:21], v[94:97], v[46:49], v[6:21]
	v_max_f32_e32 v108, 0, v224
	v_max_f32_e32 v109, 0, v225
	v_pk_fma_f32 v[0:1], v[34:35], v[108:109], v[0:1]
	v_max_f32_e32 v210, 0, v226
	v_max_f32_e32 v211, 0, v227
	v_pk_fma_f32 v[0:1], v[36:37], v[210:211], v[0:1]
	v_add_f32_e32 v0, v0, v1
	v_ashrrev_i32_e32 v1, 31, v0
	v_mfma_f32_32x32x16_bf16 v[6:21], v[98:101], v[196:199], v[6:21]
	s_waitcnt vmcnt(10)
	v_add_u32_e32 v228, 0x10000, v5
	ds_read_b128 v[38:41], v228 offset:43264
	v_add_u32_e32 v228, 0x10000, v52
	ds_read_b128 v[42:45], v228 offset:43264
	v_add_u32_e32 v228, 0x10000, v55
	ds_read_b128 v[46:49], v228 offset:43264
	v_add_u32_e32 v228, 0x10000, v56
	ds_read_b128 v[196:199], v228 offset:43264
	v_or_b32_e32 v1, 0x80000000, v1
	s_cmpk_gt_i32 s11, 176
	s_cselect_b64 vcc, -1, 0
	v_xor_b32_e32 v0, v1, v0
	v_cndmask_b32_e32 v156, v123, v0, vcc
	s_nop 3
	s_waitcnt lgkmcnt(3)
	v_mfma_f32_32x32x16_bf16 v[212:227], v[70:73], v[38:41], 0
	v_max_f32_e32 v108, 0, v6
	v_max_f32_e32 v109, 0, v7
	v_pk_mul_f32 v[50:51], v[244:245], v[108:109]
	v_max_f32_e32 v210, 0, v8
	v_max_f32_e32 v211, 0, v9
	v_pk_fma_f32 v[50:51], v[246:247], v[210:211], v[50:51]
	v_max_f32_e32 v108, 0, v10
	v_max_f32_e32 v109, 0, v11
	v_pk_fma_f32 v[50:51], v[248:249], v[108:109], v[50:51]
	s_waitcnt lgkmcnt(2)
	v_mfma_f32_32x32x16_bf16 v[212:227], v[74:77], v[42:45], v[212:227]
	v_max_f32_e32 v210, 0, v12
	v_max_f32_e32 v211, 0, v13
	v_pk_fma_f32 v[50:51], v[250:251], v[210:211], v[50:51]
	v_max_f32_e32 v108, 0, v14
	v_max_f32_e32 v109, 0, v15
	v_pk_fma_f32 v[50:51], v[252:253], v[108:109], v[50:51]
	v_max_f32_e32 v210, 0, v16
	v_max_f32_e32 v211, 0, v17
	v_pk_fma_f32 v[50:51], v[254:255], v[210:211], v[50:51]
	s_waitcnt lgkmcnt(1)
	v_mfma_f32_32x32x16_bf16 v[212:227], v[78:81], v[46:49], v[212:227]
	v_max_f32_e32 v108, 0, v18
	v_max_f32_e32 v109, 0, v19
	v_pk_fma_f32 v[50:51], v[200:201], v[108:109], v[50:51]
	v_max_f32_e32 v210, 0, v20
	v_max_f32_e32 v211, 0, v21
	v_pk_fma_f32 v[50:51], v[202:203], v[210:211], v[50:51]
	v_add_f32_e32 v50, v50, v51
	v_ashrrev_i32_e32 v51, 31, v50
	s_waitcnt lgkmcnt(0)
	v_mfma_f32_32x32x16_bf16 v[212:227], v[82:85], v[196:199], v[212:227]
	v_or_b32_e32 v51, 0x80000000, v51
	s_cmpk_gt_i32 s11, 176
	s_cselect_b64 vcc, -1, 0
	v_xor_b32_e32 v50, v51, v50
	v_cndmask_b32_e32 v50, v123, v50, vcc
	global_store_dword v243, v50, s[8:9]
	v_mfma_f32_32x32x16_bf16 v[6:21], v[86:89], v[38:41], 0
	s_add_i32 m0, s10, 65536
	s_nop 0
	global_load_lds_dwordx4 v102, s[6:7]
	s_add_i32 m0, s10, 66560
	s_nop 0
	global_load_lds_dwordx4 v110, s[6:7]
	s_add_i32 m0, s10, 67584
	s_nop 0
	global_load_lds_dwordx4 v112, s[6:7]
	s_add_i32 m0, s10, 68608
	s_nop 0
	global_load_lds_dwordx4 v193, s[6:7]
	s_add_u32 s6, s6, 0x8000
	s_addc_u32 s7, s7, 0
	v_max_f32_e32 v108, 0, v212
	v_max_f32_e32 v109, 0, v213
	v_pk_mul_f32 v[0:1], v[22:23], v[108:109]
	v_max_f32_e32 v210, 0, v214
	v_max_f32_e32 v211, 0, v215
	v_pk_fma_f32 v[0:1], v[24:25], v[210:211], v[0:1]
	v_max_f32_e32 v108, 0, v216
	v_max_f32_e32 v109, 0, v217
	v_pk_fma_f32 v[0:1], v[26:27], v[108:109], v[0:1]
	v_mfma_f32_32x32x16_bf16 v[6:21], v[90:93], v[42:45], v[6:21]
	v_max_f32_e32 v210, 0, v218
	v_max_f32_e32 v211, 0, v219
	v_pk_fma_f32 v[0:1], v[28:29], v[210:211], v[0:1]
	v_max_f32_e32 v108, 0, v220
	v_max_f32_e32 v109, 0, v221
	v_pk_fma_f32 v[0:1], v[30:31], v[108:109], v[0:1]
	v_max_f32_e32 v210, 0, v222
	v_max_f32_e32 v211, 0, v223
	v_pk_fma_f32 v[0:1], v[32:33], v[210:211], v[0:1]
	v_mfma_f32_32x32x16_bf16 v[6:21], v[94:97], v[46:49], v[6:21]
	v_max_f32_e32 v108, 0, v224
	v_max_f32_e32 v109, 0, v225
	v_pk_fma_f32 v[0:1], v[34:35], v[108:109], v[0:1]
	v_max_f32_e32 v210, 0, v226
	v_max_f32_e32 v211, 0, v227
	v_pk_fma_f32 v[0:1], v[36:37], v[210:211], v[0:1]
	v_add_f32_e32 v0, v0, v1
	v_ashrrev_i32_e32 v1, 31, v0
	v_mfma_f32_32x32x16_bf16 v[6:21], v[98:101], v[196:199], v[6:21]
	s_waitcnt vmcnt(10)
	ds_read_b128 v[38:41], v5 offset:10496
	ds_read_b128 v[42:45], v52 offset:10496
	ds_read_b128 v[46:49], v55 offset:10496
	ds_read_b128 v[196:199], v56 offset:10496
	v_or_b32_e32 v1, 0x80000000, v1
	s_cmpk_gt_i32 s11, 184
	s_cselect_b64 vcc, -1, 0
	v_xor_b32_e32 v0, v1, v0
	v_cndmask_b32_e32 v155, v123, v0, vcc
	s_nop 3
	v_max_f32_e32 v108, 0, v6
	v_max_f32_e32 v109, 0, v7
	v_pk_mul_f32 v[50:51], v[244:245], v[108:109]
	v_max_f32_e32 v210, 0, v8
	v_max_f32_e32 v211, 0, v9
	v_pk_fma_f32 v[50:51], v[246:247], v[210:211], v[50:51]
	v_max_f32_e32 v108, 0, v10
	v_max_f32_e32 v109, 0, v11
	v_pk_fma_f32 v[50:51], v[248:249], v[108:109], v[50:51]
	v_max_f32_e32 v210, 0, v12
	v_max_f32_e32 v211, 0, v13
	v_pk_fma_f32 v[50:51], v[250:251], v[210:211], v[50:51]
	v_max_f32_e32 v108, 0, v14
	v_max_f32_e32 v109, 0, v15
	v_pk_fma_f32 v[50:51], v[252:253], v[108:109], v[50:51]
	v_max_f32_e32 v210, 0, v16
	v_max_f32_e32 v211, 0, v17
	v_pk_fma_f32 v[50:51], v[254:255], v[210:211], v[50:51]
	v_max_f32_e32 v108, 0, v18
	v_max_f32_e32 v109, 0, v19
	v_pk_fma_f32 v[50:51], v[200:201], v[108:109], v[50:51]
	v_max_f32_e32 v210, 0, v20
	v_max_f32_e32 v211, 0, v21
	v_pk_fma_f32 v[50:51], v[202:203], v[210:211], v[50:51]
	v_add_f32_e32 v50, v50, v51
	v_ashrrev_i32_e32 v51, 31, v50
	v_or_b32_e32 v51, 0x80000000, v51
	s_cmpk_gt_i32 s11, 184
	s_cselect_b64 vcc, -1, 0
	v_xor_b32_e32 v50, v51, v50
	v_cndmask_b32_e32 v50, v123, v50, vcc
	global_store_dword v243, v50, s[8:9] offset:2048
	s_add_u32 s8, s8, 0x1000
	s_addc_u32 s9, s9, 0
	s_cmpk_gt_i32 s81, 24
	s_cbranch_scc0 .Lix_fill_3
	s_waitcnt lgkmcnt(3)
	v_mfma_f32_32x32x16_bf16 v[212:227], v[70:73], v[38:41], 0
	s_add_i32 m0, s10, 98304
	s_nop 0
	global_load_lds_dwordx4 v102, s[6:7]
	s_waitcnt lgkmcnt(2)
	v_mfma_f32_32x32x16_bf16 v[212:227], v[74:77], v[42:45], v[212:227]
	s_add_i32 m0, s10, 99328
	s_nop 0
	global_load_lds_dwordx4 v110, s[6:7]
	s_waitcnt lgkmcnt(1)
	v_mfma_f32_32x32x16_bf16 v[212:227], v[78:81], v[46:49], v[212:227]
	s_add_i32 m0, s10, 100352
	s_nop 0
	global_load_lds_dwordx4 v112, s[6:7]
	s_waitcnt lgkmcnt(0)
	v_mfma_f32_32x32x16_bf16 v[212:227], v[82:85], v[196:199], v[212:227]
	s_add_i32 m0, s10, 101376
	s_nop 0
	global_load_lds_dwordx4 v193, s[6:7]
	s_add_u32 s6, s6, 0x8000
	s_addc_u32 s7, s7, 0
	v_mfma_f32_32x32x16_bf16 v[6:21], v[86:89], v[38:41], 0
	s_nop 7
	s_nop 2
	v_max_f32_e32 v108, 0, v212
	v_max_f32_e32 v109, 0, v213
	v_pk_mul_f32 v[0:1], v[22:23], v[108:109]
	v_max_f32_e32 v210, 0, v214
	v_max_f32_e32 v211, 0, v215
	v_pk_fma_f32 v[0:1], v[24:25], v[210:211], v[0:1]
	v_max_f32_e32 v108, 0, v216
	v_max_f32_e32 v109, 0, v217
	v_pk_fma_f32 v[0:1], v[26:27], v[108:109], v[0:1]
	v_mfma_f32_32x32x16_bf16 v[6:21], v[90:93], v[42:45], v[6:21]
	v_max_f32_e32 v210, 0, v218
	v_max_f32_e32 v211, 0, v219
	v_pk_fma_f32 v[0:1], v[28:29], v[210:211], v[0:1]
	v_max_f32_e32 v108, 0, v220
	v_max_f32_e32 v109, 0, v221
	v_pk_fma_f32 v[0:1], v[30:31], v[108:109], v[0:1]
	v_max_f32_e32 v210, 0, v222
	v_max_f32_e32 v211, 0, v223
	v_pk_fma_f32 v[0:1], v[32:33], v[210:211], v[0:1]
	v_mfma_f32_32x32x16_bf16 v[6:21], v[94:97], v[46:49], v[6:21]
	v_max_f32_e32 v108, 0, v224
	v_max_f32_e32 v109, 0, v225
	v_pk_fma_f32 v[0:1], v[34:35], v[108:109], v[0:1]
	v_max_f32_e32 v210, 0, v226
	v_max_f32_e32 v211, 0, v227
	v_pk_fma_f32 v[0:1], v[36:37], v[210:211], v[0:1]
	v_add_f32_e32 v0, v0, v1
	v_ashrrev_i32_e32 v1, 31, v0
	v_mfma_f32_32x32x16_bf16 v[6:21], v[98:101], v[196:199], v[6:21]
	s_waitcnt vmcnt(10)
	ds_read_b128 v[38:41], v5 offset:43264
	ds_read_b128 v[42:45], v52 offset:43264
	ds_read_b128 v[46:49], v55 offset:43264
	ds_read_b128 v[196:199], v56 offset:43264
	v_or_b32_e32 v1, 0x80000000, v1
	s_cmpk_gt_i32 s11, 192
	s_cselect_b64 vcc, -1, 0
	v_xor_b32_e32 v0, v1, v0
	v_cndmask_b32_e32 v158, v123, v0, vcc
	s_nop 3
	s_waitcnt lgkmcnt(3)
	v_mfma_f32_32x32x16_bf16 v[212:227], v[70:73], v[38:41], 0
	v_max_f32_e32 v108, 0, v6
	v_max_f32_e32 v109, 0, v7
	v_pk_mul_f32 v[50:51], v[244:245], v[108:109]
	v_max_f32_e32 v210, 0, v8
	v_max_f32_e32 v211, 0, v9
	v_pk_fma_f32 v[50:51], v[246:247], v[210:211], v[50:51]
	v_max_f32_e32 v108, 0, v10
	v_max_f32_e32 v109, 0, v11
	v_pk_fma_f32 v[50:51], v[248:249], v[108:109], v[50:51]
	s_waitcnt lgkmcnt(2)
	v_mfma_f32_32x32x16_bf16 v[212:227], v[74:77], v[42:45], v[212:227]
	v_max_f32_e32 v210, 0, v12
	v_max_f32_e32 v211, 0, v13
	v_pk_fma_f32 v[50:51], v[250:251], v[210:211], v[50:51]
	v_max_f32_e32 v108, 0, v14
	v_max_f32_e32 v109, 0, v15
	v_pk_fma_f32 v[50:51], v[252:253], v[108:109], v[50:51]
	v_max_f32_e32 v210, 0, v16
	v_max_f32_e32 v211, 0, v17
	v_pk_fma_f32 v[50:51], v[254:255], v[210:211], v[50:51]
	s_waitcnt lgkmcnt(1)
	v_mfma_f32_32x32x16_bf16 v[212:227], v[78:81], v[46:49], v[212:227]
	v_max_f32_e32 v108, 0, v18
	v_max_f32_e32 v109, 0, v19
	v_pk_fma_f32 v[50:51], v[200:201], v[108:109], v[50:51]
	v_max_f32_e32 v210, 0, v20
	v_max_f32_e32 v211, 0, v21
	v_pk_fma_f32 v[50:51], v[202:203], v[210:211], v[50:51]
	v_add_f32_e32 v50, v50, v51
	v_ashrrev_i32_e32 v51, 31, v50
	s_waitcnt lgkmcnt(0)
	v_mfma_f32_32x32x16_bf16 v[212:227], v[82:85], v[196:199], v[212:227]
	v_or_b32_e32 v51, 0x80000000, v51
	s_cmpk_gt_i32 s11, 192
	s_cselect_b64 vcc, -1, 0
	v_xor_b32_e32 v50, v51, v50
	v_cndmask_b32_e32 v50, v123, v50, vcc
	global_store_dword v243, v50, s[8:9]
	v_mfma_f32_32x32x16_bf16 v[6:21], v[86:89], v[38:41], 0
	s_add_i32 m0, s10, 0
	s_nop 0
	global_load_lds_dwordx4 v102, s[6:7]
	s_add_i32 m0, s10, 1024
	s_nop 0
	global_load_lds_dwordx4 v110, s[6:7]
	s_add_i32 m0, s10, 2048
	s_nop 0
	global_load_lds_dwordx4 v112, s[6:7]
	s_add_i32 m0, s10, 3072
	s_nop 0
	global_load_lds_dwordx4 v193, s[6:7]
	s_add_u32 s6, s6, 0x8000
	s_addc_u32 s7, s7, 0
	v_max_f32_e32 v108, 0, v212
	v_max_f32_e32 v109, 0, v213
	v_pk_mul_f32 v[0:1], v[22:23], v[108:109]
	v_max_f32_e32 v210, 0, v214
	v_max_f32_e32 v211, 0, v215
	v_pk_fma_f32 v[0:1], v[24:25], v[210:211], v[0:1]
	v_max_f32_e32 v108, 0, v216
	v_max_f32_e32 v109, 0, v217
	v_pk_fma_f32 v[0:1], v[26:27], v[108:109], v[0:1]
	v_mfma_f32_32x32x16_bf16 v[6:21], v[90:93], v[42:45], v[6:21]
	v_max_f32_e32 v210, 0, v218
	v_max_f32_e32 v211, 0, v219
	v_pk_fma_f32 v[0:1], v[28:29], v[210:211], v[0:1]
	v_max_f32_e32 v108, 0, v220
	v_max_f32_e32 v109, 0, v221
	v_pk_fma_f32 v[0:1], v[30:31], v[108:109], v[0:1]
	v_max_f32_e32 v210, 0, v222
	v_max_f32_e32 v211, 0, v223
	v_pk_fma_f32 v[0:1], v[32:33], v[210:211], v[0:1]
	v_mfma_f32_32x32x16_bf16 v[6:21], v[94:97], v[46:49], v[6:21]
	v_max_f32_e32 v108, 0, v224
	v_max_f32_e32 v109, 0, v225
	v_pk_fma_f32 v[0:1], v[34:35], v[108:109], v[0:1]
	v_max_f32_e32 v210, 0, v226
	v_max_f32_e32 v211, 0, v227
	v_pk_fma_f32 v[0:1], v[36:37], v[210:211], v[0:1]
	v_add_f32_e32 v0, v0, v1
	v_ashrrev_i32_e32 v1, 31, v0
	v_mfma_f32_32x32x16_bf16 v[6:21], v[98:101], v[196:199], v[6:21]
	s_waitcnt vmcnt(10)
	v_add_u32_e32 v228, 0x10000, v5
	ds_read_b128 v[38:41], v228 offset:10496
	v_add_u32_e32 v228, 0x10000, v52
	ds_read_b128 v[42:45], v228 offset:10496
	v_add_u32_e32 v228, 0x10000, v55
	ds_read_b128 v[46:49], v228 offset:10496
	v_add_u32_e32 v228, 0x10000, v56
	ds_read_b128 v[196:199], v228 offset:10496
	v_or_b32_e32 v1, 0x80000000, v1
	s_cmpk_gt_i32 s11, 200
	s_cselect_b64 vcc, -1, 0
	v_xor_b32_e32 v0, v1, v0
	v_cndmask_b32_e32 v157, v123, v0, vcc
	s_nop 3
	s_waitcnt lgkmcnt(3)
	v_mfma_f32_32x32x16_bf16 v[212:227], v[70:73], v[38:41], 0
	v_max_f32_e32 v108, 0, v6
	v_max_f32_e32 v109, 0, v7
	v_pk_mul_f32 v[50:51], v[244:245], v[108:109]
	v_max_f32_e32 v210, 0, v8
	v_max_f32_e32 v211, 0, v9
	v_pk_fma_f32 v[50:51], v[246:247], v[210:211], v[50:51]
	v_max_f32_e32 v108, 0, v10
	v_max_f32_e32 v109, 0, v11
	v_pk_fma_f32 v[50:51], v[248:249], v[108:109], v[50:51]
	s_waitcnt lgkmcnt(2)
	v_mfma_f32_32x32x16_bf16 v[212:227], v[74:77], v[42:45], v[212:227]
	v_max_f32_e32 v210, 0, v12
	v_max_f32_e32 v211, 0, v13
	v_pk_fma_f32 v[50:51], v[250:251], v[210:211], v[50:51]
	v_max_f32_e32 v108, 0, v14
	v_max_f32_e32 v109, 0, v15
	v_pk_fma_f32 v[50:51], v[252:253], v[108:109], v[50:51]
	v_max_f32_e32 v210, 0, v16
	v_max_f32_e32 v211, 0, v17
	v_pk_fma_f32 v[50:51], v[254:255], v[210:211], v[50:51]
	s_waitcnt lgkmcnt(1)
	v_mfma_f32_32x32x16_bf16 v[212:227], v[78:81], v[46:49], v[212:227]
	v_max_f32_e32 v108, 0, v18
	v_max_f32_e32 v109, 0, v19
	v_pk_fma_f32 v[50:51], v[200:201], v[108:109], v[50:51]
	v_max_f32_e32 v210, 0, v20
	v_max_f32_e32 v211, 0, v21
	v_pk_fma_f32 v[50:51], v[202:203], v[210:211], v[50:51]
	v_add_f32_e32 v50, v50, v51
	v_ashrrev_i32_e32 v51, 31, v50
	s_waitcnt lgkmcnt(0)
	v_mfma_f32_32x32x16_bf16 v[212:227], v[82:85], v[196:199], v[212:227]
	v_or_b32_e32 v51, 0x80000000, v51
	s_cmpk_gt_i32 s11, 200
	s_cselect_b64 vcc, -1, 0
	v_xor_b32_e32 v50, v51, v50
	v_cndmask_b32_e32 v50, v123, v50, vcc
	global_store_dword v243, v50, s[8:9] offset:2048
	s_add_u32 s8, s8, 0x1000
	s_addc_u32 s9, s9, 0
	v_mfma_f32_32x32x16_bf16 v[6:21], v[86:89], v[38:41], 0
	s_add_i32 m0, s10, 32768
	s_nop 0
	global_load_lds_dwordx4 v102, s[6:7]
	s_add_i32 m0, s10, 33792
	s_nop 0
	global_load_lds_dwordx4 v110, s[6:7]
	s_add_i32 m0, s10, 34816
	s_nop 0
	global_load_lds_dwordx4 v112, s[6:7]
	s_add_i32 m0, s10, 35840
	s_nop 0
	global_load_lds_dwordx4 v193, s[6:7]
	s_add_u32 s6, s6, 0x8000
	s_addc_u32 s7, s7, 0
	v_max_f32_e32 v108, 0, v212
	v_max_f32_e32 v109, 0, v213
	v_pk_mul_f32 v[0:1], v[22:23], v[108:109]
	v_max_f32_e32 v210, 0, v214
	v_max_f32_e32 v211, 0, v215
	v_pk_fma_f32 v[0:1], v[24:25], v[210:211], v[0:1]
	v_max_f32_e32 v108, 0, v216
	v_max_f32_e32 v109, 0, v217
	v_pk_fma_f32 v[0:1], v[26:27], v[108:109], v[0:1]
	v_mfma_f32_32x32x16_bf16 v[6:21], v[90:93], v[42:45], v[6:21]
	v_max_f32_e32 v210, 0, v218
	v_max_f32_e32 v211, 0, v219
	v_pk_fma_f32 v[0:1], v[28:29], v[210:211], v[0:1]
	v_max_f32_e32 v108, 0, v220
	v_max_f32_e32 v109, 0, v221
	v_pk_fma_f32 v[0:1], v[30:31], v[108:109], v[0:1]
	v_max_f32_e32 v210, 0, v222
	v_max_f32_e32 v211, 0, v223
	v_pk_fma_f32 v[0:1], v[32:33], v[210:211], v[0:1]
	v_mfma_f32_32x32x16_bf16 v[6:21], v[94:97], v[46:49], v[6:21]
	v_max_f32_e32 v108, 0, v224
	v_max_f32_e32 v109, 0, v225
	v_pk_fma_f32 v[0:1], v[34:35], v[108:109], v[0:1]
	v_max_f32_e32 v210, 0, v226
	v_max_f32_e32 v211, 0, v227
	v_pk_fma_f32 v[0:1], v[36:37], v[210:211], v[0:1]
	v_add_f32_e32 v0, v0, v1
	v_ashrrev_i32_e32 v1, 31, v0
	v_mfma_f32_32x32x16_bf16 v[6:21], v[98:101], v[196:199], v[6:21]
	s_waitcnt vmcnt(10)
	v_add_u32_e32 v228, 0x10000, v5
	ds_read_b128 v[38:41], v228 offset:43264
	v_add_u32_e32 v228, 0x10000, v52
	ds_read_b128 v[42:45], v228 offset:43264
	v_add_u32_e32 v228, 0x10000, v55
	ds_read_b128 v[46:49], v228 offset:43264
	v_add_u32_e32 v228, 0x10000, v56
	ds_read_b128 v[196:199], v228 offset:43264
	v_or_b32_e32 v1, 0x80000000, v1
	s_cmpk_gt_i32 s11, 208
	s_cselect_b64 vcc, -1, 0
	v_xor_b32_e32 v0, v1, v0
	v_cndmask_b32_e32 v160, v123, v0, vcc
	s_nop 3
	s_waitcnt lgkmcnt(3)
	v_mfma_f32_32x32x16_bf16 v[212:227], v[70:73], v[38:41], 0
	v_max_f32_e32 v108, 0, v6
	v_max_f32_e32 v109, 0, v7
	v_pk_mul_f32 v[50:51], v[244:245], v[108:109]
	v_max_f32_e32 v210, 0, v8
	v_max_f32_e32 v211, 0, v9
	v_pk_fma_f32 v[50:51], v[246:247], v[210:211], v[50:51]
	v_max_f32_e32 v108, 0, v10
	v_max_f32_e32 v109, 0, v11
	v_pk_fma_f32 v[50:51], v[248:249], v[108:109], v[50:51]
	s_waitcnt lgkmcnt(2)
	v_mfma_f32_32x32x16_bf16 v[212:227], v[74:77], v[42:45], v[212:227]
	v_max_f32_e32 v210, 0, v12
	v_max_f32_e32 v211, 0, v13
	v_pk_fma_f32 v[50:51], v[250:251], v[210:211], v[50:51]
	v_max_f32_e32 v108, 0, v14
	v_max_f32_e32 v109, 0, v15
	v_pk_fma_f32 v[50:51], v[252:253], v[108:109], v[50:51]
	v_max_f32_e32 v210, 0, v16
	v_max_f32_e32 v211, 0, v17
	v_pk_fma_f32 v[50:51], v[254:255], v[210:211], v[50:51]
	s_waitcnt lgkmcnt(1)
	v_mfma_f32_32x32x16_bf16 v[212:227], v[78:81], v[46:49], v[212:227]
	v_max_f32_e32 v108, 0, v18
	v_max_f32_e32 v109, 0, v19
	v_pk_fma_f32 v[50:51], v[200:201], v[108:109], v[50:51]
	v_max_f32_e32 v210, 0, v20
	v_max_f32_e32 v211, 0, v21
	v_pk_fma_f32 v[50:51], v[202:203], v[210:211], v[50:51]
	v_add_f32_e32 v50, v50, v51
	v_ashrrev_i32_e32 v51, 31, v50
	s_waitcnt lgkmcnt(0)
	v_mfma_f32_32x32x16_bf16 v[212:227], v[82:85], v[196:199], v[212:227]
	v_or_b32_e32 v51, 0x80000000, v51
	s_cmpk_gt_i32 s11, 208
	s_cselect_b64 vcc, -1, 0
	v_xor_b32_e32 v50, v51, v50
	v_cndmask_b32_e32 v50, v123, v50, vcc
	global_store_dword v243, v50, s[8:9]
	v_mfma_f32_32x32x16_bf16 v[6:21], v[86:89], v[38:41], 0
	s_add_i32 m0, s10, 65536
	s_nop 0
	global_load_lds_dwordx4 v102, s[6:7]
	s_add_i32 m0, s10, 66560
	s_nop 0
	global_load_lds_dwordx4 v110, s[6:7]
	s_add_i32 m0, s10, 67584
	s_nop 0
	global_load_lds_dwordx4 v112, s[6:7]
	s_add_i32 m0, s10, 68608
	s_nop 0
	global_load_lds_dwordx4 v193, s[6:7]
	s_add_u32 s6, s6, 0x8000
	s_addc_u32 s7, s7, 0
	v_max_f32_e32 v108, 0, v212
	v_max_f32_e32 v109, 0, v213
	v_pk_mul_f32 v[0:1], v[22:23], v[108:109]
	v_max_f32_e32 v210, 0, v214
	v_max_f32_e32 v211, 0, v215
	v_pk_fma_f32 v[0:1], v[24:25], v[210:211], v[0:1]
	v_max_f32_e32 v108, 0, v216
	v_max_f32_e32 v109, 0, v217
	v_pk_fma_f32 v[0:1], v[26:27], v[108:109], v[0:1]
	v_mfma_f32_32x32x16_bf16 v[6:21], v[90:93], v[42:45], v[6:21]
	v_max_f32_e32 v210, 0, v218
	v_max_f32_e32 v211, 0, v219
	v_pk_fma_f32 v[0:1], v[28:29], v[210:211], v[0:1]
	v_max_f32_e32 v108, 0, v220
	v_max_f32_e32 v109, 0, v221
	v_pk_fma_f32 v[0:1], v[30:31], v[108:109], v[0:1]
	v_max_f32_e32 v210, 0, v222
	v_max_f32_e32 v211, 0, v223
	v_pk_fma_f32 v[0:1], v[32:33], v[210:211], v[0:1]
	v_mfma_f32_32x32x16_bf16 v[6:21], v[94:97], v[46:49], v[6:21]
	v_max_f32_e32 v108, 0, v224
	v_max_f32_e32 v109, 0, v225
	v_pk_fma_f32 v[0:1], v[34:35], v[108:109], v[0:1]
	v_max_f32_e32 v210, 0, v226
	v_max_f32_e32 v211, 0, v227
	v_pk_fma_f32 v[0:1], v[36:37], v[210:211], v[0:1]
	v_add_f32_e32 v0, v0, v1
	v_ashrrev_i32_e32 v1, 31, v0
	v_mfma_f32_32x32x16_bf16 v[6:21], v[98:101], v[196:199], v[6:21]
	s_waitcnt vmcnt(10)
	ds_read_b128 v[38:41], v5 offset:10496
	ds_read_b128 v[42:45], v52 offset:10496
	ds_read_b128 v[46:49], v55 offset:10496
	ds_read_b128 v[196:199], v56 offset:10496
	v_or_b32_e32 v1, 0x80000000, v1
	s_cmpk_gt_i32 s11, 216
	s_cselect_b64 vcc, -1, 0
	v_xor_b32_e32 v0, v1, v0
	v_cndmask_b32_e32 v159, v123, v0, vcc
	s_nop 3
	s_waitcnt lgkmcnt(3)
	v_mfma_f32_32x32x16_bf16 v[212:227], v[70:73], v[38:41], 0
	v_max_f32_e32 v108, 0, v6
	v_max_f32_e32 v109, 0, v7
	v_pk_mul_f32 v[50:51], v[244:245], v[108:109]
	v_max_f32_e32 v210, 0, v8
	v_max_f32_e32 v211, 0, v9
	v_pk_fma_f32 v[50:51], v[246:247], v[210:211], v[50:51]
	v_max_f32_e32 v108, 0, v10
	v_max_f32_e32 v109, 0, v11
	v_pk_fma_f32 v[50:51], v[248:249], v[108:109], v[50:51]
	s_waitcnt lgkmcnt(2)
	v_mfma_f32_32x32x16_bf16 v[212:227], v[74:77], v[42:45], v[212:227]
	v_max_f32_e32 v210, 0, v12
	v_max_f32_e32 v211, 0, v13
	v_pk_fma_f32 v[50:51], v[250:251], v[210:211], v[50:51]
	v_max_f32_e32 v108, 0, v14
	v_max_f32_e32 v109, 0, v15
	v_pk_fma_f32 v[50:51], v[252:253], v[108:109], v[50:51]
	v_max_f32_e32 v210, 0, v16
	v_max_f32_e32 v211, 0, v17
	v_pk_fma_f32 v[50:51], v[254:255], v[210:211], v[50:51]
	s_waitcnt lgkmcnt(1)
	v_mfma_f32_32x32x16_bf16 v[212:227], v[78:81], v[46:49], v[212:227]
	v_max_f32_e32 v108, 0, v18
	v_max_f32_e32 v109, 0, v19
	v_pk_fma_f32 v[50:51], v[200:201], v[108:109], v[50:51]
	v_max_f32_e32 v210, 0, v20
	v_max_f32_e32 v211, 0, v21
	v_pk_fma_f32 v[50:51], v[202:203], v[210:211], v[50:51]
	v_add_f32_e32 v50, v50, v51
	v_ashrrev_i32_e32 v51, 31, v50
	s_waitcnt lgkmcnt(0)
	v_mfma_f32_32x32x16_bf16 v[212:227], v[82:85], v[196:199], v[212:227]
	v_or_b32_e32 v51, 0x80000000, v51
	s_cmpk_gt_i32 s11, 216
	s_cselect_b64 vcc, -1, 0
	v_xor_b32_e32 v50, v51, v50
	v_cndmask_b32_e32 v50, v123, v50, vcc
	global_store_dword v243, v50, s[8:9] offset:2048
	s_add_u32 s8, s8, 0x1000
	s_addc_u32 s9, s9, 0
	v_mfma_f32_32x32x16_bf16 v[6:21], v[86:89], v[38:41], 0
	s_add_i32 m0, s10, 98304
	s_nop 0
	global_load_lds_dwordx4 v102, s[6:7]
	s_add_i32 m0, s10, 99328
	s_nop 0
	global_load_lds_dwordx4 v110, s[6:7]
	s_add_i32 m0, s10, 100352
	s_nop 0
	global_load_lds_dwordx4 v112, s[6:7]
	s_add_i32 m0, s10, 101376
	s_nop 0
	global_load_lds_dwordx4 v193, s[6:7]
	s_add_u32 s6, s6, 0x8000
	s_addc_u32 s7, s7, 0
	v_max_f32_e32 v108, 0, v212
	v_max_f32_e32 v109, 0, v213
	v_pk_mul_f32 v[0:1], v[22:23], v[108:109]
	v_max_f32_e32 v210, 0, v214
	v_max_f32_e32 v211, 0, v215
	v_pk_fma_f32 v[0:1], v[24:25], v[210:211], v[0:1]
	v_max_f32_e32 v108, 0, v216
	v_max_f32_e32 v109, 0, v217
	v_pk_fma_f32 v[0:1], v[26:27], v[108:109], v[0:1]
	v_mfma_f32_32x32x16_bf16 v[6:21], v[90:93], v[42:45], v[6:21]
	v_max_f32_e32 v210, 0, v218
	v_max_f32_e32 v211, 0, v219
	v_pk_fma_f32 v[0:1], v[28:29], v[210:211], v[0:1]
	v_max_f32_e32 v108, 0, v220
	v_max_f32_e32 v109, 0, v221
	v_pk_fma_f32 v[0:1], v[30:31], v[108:109], v[0:1]
	v_max_f32_e32 v210, 0, v222
	v_max_f32_e32 v211, 0, v223
	v_pk_fma_f32 v[0:1], v[32:33], v[210:211], v[0:1]
	v_mfma_f32_32x32x16_bf16 v[6:21], v[94:97], v[46:49], v[6:21]
	v_max_f32_e32 v108, 0, v224
	v_max_f32_e32 v109, 0, v225
	v_pk_fma_f32 v[0:1], v[34:35], v[108:109], v[0:1]
	v_max_f32_e32 v210, 0, v226
	v_max_f32_e32 v211, 0, v227
	v_pk_fma_f32 v[0:1], v[36:37], v[210:211], v[0:1]
	v_add_f32_e32 v0, v0, v1
	v_ashrrev_i32_e32 v1, 31, v0
	v_mfma_f32_32x32x16_bf16 v[6:21], v[98:101], v[196:199], v[6:21]
	s_waitcnt vmcnt(10)
	ds_read_b128 v[38:41], v5 offset:43264
	ds_read_b128 v[42:45], v52 offset:43264
	ds_read_b128 v[46:49], v55 offset:43264
	ds_read_b128 v[196:199], v56 offset:43264
	v_or_b32_e32 v1, 0x80000000, v1
	s_cmpk_gt_i32 s11, 224
	s_cselect_b64 vcc, -1, 0
	v_xor_b32_e32 v0, v1, v0
	v_cndmask_b32_e32 v162, v123, v0, vcc
	s_nop 3
	s_waitcnt lgkmcnt(3)
	v_mfma_f32_32x32x16_bf16 v[212:227], v[70:73], v[38:41], 0
	v_max_f32_e32 v108, 0, v6
	v_max_f32_e32 v109, 0, v7
	v_pk_mul_f32 v[50:51], v[244:245], v[108:109]
	v_max_f32_e32 v210, 0, v8
	v_max_f32_e32 v211, 0, v9
	v_pk_fma_f32 v[50:51], v[246:247], v[210:211], v[50:51]
	v_max_f32_e32 v108, 0, v10
	v_max_f32_e32 v109, 0, v11
	v_pk_fma_f32 v[50:51], v[248:249], v[108:109], v[50:51]
	s_waitcnt lgkmcnt(2)
	v_mfma_f32_32x32x16_bf16 v[212:227], v[74:77], v[42:45], v[212:227]
	v_max_f32_e32 v210, 0, v12
	v_max_f32_e32 v211, 0, v13
	v_pk_fma_f32 v[50:51], v[250:251], v[210:211], v[50:51]
	v_max_f32_e32 v108, 0, v14
	v_max_f32_e32 v109, 0, v15
	v_pk_fma_f32 v[50:51], v[252:253], v[108:109], v[50:51]
	v_max_f32_e32 v210, 0, v16
	v_max_f32_e32 v211, 0, v17
	v_pk_fma_f32 v[50:51], v[254:255], v[210:211], v[50:51]
	s_waitcnt lgkmcnt(1)
	v_mfma_f32_32x32x16_bf16 v[212:227], v[78:81], v[46:49], v[212:227]
	v_max_f32_e32 v108, 0, v18
	v_max_f32_e32 v109, 0, v19
	v_pk_fma_f32 v[50:51], v[200:201], v[108:109], v[50:51]
	v_max_f32_e32 v210, 0, v20
	v_max_f32_e32 v211, 0, v21
	v_pk_fma_f32 v[50:51], v[202:203], v[210:211], v[50:51]
	v_add_f32_e32 v50, v50, v51
	v_ashrrev_i32_e32 v51, 31, v50
	s_waitcnt lgkmcnt(0)
	v_mfma_f32_32x32x16_bf16 v[212:227], v[82:85], v[196:199], v[212:227]
	v_or_b32_e32 v51, 0x80000000, v51
	s_cmpk_gt_i32 s11, 224
	s_cselect_b64 vcc, -1, 0
	v_xor_b32_e32 v50, v51, v50
	v_cndmask_b32_e32 v50, v123, v50, vcc
	global_store_dword v243, v50, s[8:9]
	v_mfma_f32_32x32x16_bf16 v[6:21], v[86:89], v[38:41], 0
	s_add_i32 m0, s10, 0
	s_nop 0
	global_load_lds_dwordx4 v102, s[6:7]
	s_add_i32 m0, s10, 1024
	s_nop 0
	global_load_lds_dwordx4 v110, s[6:7]
	s_add_i32 m0, s10, 2048
	s_nop 0
	global_load_lds_dwordx4 v112, s[6:7]
	s_add_i32 m0, s10, 3072
	s_nop 0
	global_load_lds_dwordx4 v193, s[6:7]
	s_add_u32 s6, s6, 0x8000
	s_addc_u32 s7, s7, 0
	v_max_f32_e32 v108, 0, v212
	v_max_f32_e32 v109, 0, v213
	v_pk_mul_f32 v[0:1], v[22:23], v[108:109]
	v_max_f32_e32 v210, 0, v214
	v_max_f32_e32 v211, 0, v215
	v_pk_fma_f32 v[0:1], v[24:25], v[210:211], v[0:1]
	v_max_f32_e32 v108, 0, v216
	v_max_f32_e32 v109, 0, v217
	v_pk_fma_f32 v[0:1], v[26:27], v[108:109], v[0:1]
	v_mfma_f32_32x32x16_bf16 v[6:21], v[90:93], v[42:45], v[6:21]
	v_max_f32_e32 v210, 0, v218
	v_max_f32_e32 v211, 0, v219
	v_pk_fma_f32 v[0:1], v[28:29], v[210:211], v[0:1]
	v_max_f32_e32 v108, 0, v220
	v_max_f32_e32 v109, 0, v221
	v_pk_fma_f32 v[0:1], v[30:31], v[108:109], v[0:1]
	v_max_f32_e32 v210, 0, v222
	v_max_f32_e32 v211, 0, v223
	v_pk_fma_f32 v[0:1], v[32:33], v[210:211], v[0:1]
	v_mfma_f32_32x32x16_bf16 v[6:21], v[94:97], v[46:49], v[6:21]
	v_max_f32_e32 v108, 0, v224
	v_max_f32_e32 v109, 0, v225
	v_pk_fma_f32 v[0:1], v[34:35], v[108:109], v[0:1]
	v_max_f32_e32 v210, 0, v226
	v_max_f32_e32 v211, 0, v227
	v_pk_fma_f32 v[0:1], v[36:37], v[210:211], v[0:1]
	v_add_f32_e32 v0, v0, v1
	v_ashrrev_i32_e32 v1, 31, v0
	v_mfma_f32_32x32x16_bf16 v[6:21], v[98:101], v[196:199], v[6:21]
	s_waitcnt vmcnt(10)
	v_add_u32_e32 v228, 0x10000, v5
	ds_read_b128 v[38:41], v228 offset:10496
	v_add_u32_e32 v228, 0x10000, v52
	ds_read_b128 v[42:45], v228 offset:10496
	v_add_u32_e32 v228, 0x10000, v55
	ds_read_b128 v[46:49], v228 offset:10496
	v_add_u32_e32 v228, 0x10000, v56
	ds_read_b128 v[196:199], v228 offset:10496
	v_or_b32_e32 v1, 0x80000000, v1
	s_cmpk_gt_i32 s11, 232
	s_cselect_b64 vcc, -1, 0
	v_xor_b32_e32 v0, v1, v0
	v_cndmask_b32_e32 v161, v123, v0, vcc
	s_nop 3
	s_waitcnt lgkmcnt(3)
	v_mfma_f32_32x32x16_bf16 v[212:227], v[70:73], v[38:41], 0
	v_max_f32_e32 v108, 0, v6
	v_max_f32_e32 v109, 0, v7
	v_pk_mul_f32 v[50:51], v[244:245], v[108:109]
	v_max_f32_e32 v210, 0, v8
	v_max_f32_e32 v211, 0, v9
	v_pk_fma_f32 v[50:51], v[246:247], v[210:211], v[50:51]
	v_max_f32_e32 v108, 0, v10
	v_max_f32_e32 v109, 0, v11
	v_pk_fma_f32 v[50:51], v[248:249], v[108:109], v[50:51]
	s_waitcnt lgkmcnt(2)
	v_mfma_f32_32x32x16_bf16 v[212:227], v[74:77], v[42:45], v[212:227]
	v_max_f32_e32 v210, 0, v12
	v_max_f32_e32 v211, 0, v13
	v_pk_fma_f32 v[50:51], v[250:251], v[210:211], v[50:51]
	v_max_f32_e32 v108, 0, v14
	v_max_f32_e32 v109, 0, v15
	v_pk_fma_f32 v[50:51], v[252:253], v[108:109], v[50:51]
	v_max_f32_e32 v210, 0, v16
	v_max_f32_e32 v211, 0, v17
	v_pk_fma_f32 v[50:51], v[254:255], v[210:211], v[50:51]
	s_waitcnt lgkmcnt(1)
	v_mfma_f32_32x32x16_bf16 v[212:227], v[78:81], v[46:49], v[212:227]
	v_max_f32_e32 v108, 0, v18
	v_max_f32_e32 v109, 0, v19
	v_pk_fma_f32 v[50:51], v[200:201], v[108:109], v[50:51]
	v_max_f32_e32 v210, 0, v20
	v_max_f32_e32 v211, 0, v21
	v_pk_fma_f32 v[50:51], v[202:203], v[210:211], v[50:51]
	v_add_f32_e32 v50, v50, v51
	v_ashrrev_i32_e32 v51, 31, v50
	s_waitcnt lgkmcnt(0)
	v_mfma_f32_32x32x16_bf16 v[212:227], v[82:85], v[196:199], v[212:227]
	v_or_b32_e32 v51, 0x80000000, v51
	s_cmpk_gt_i32 s11, 232
	s_cselect_b64 vcc, -1, 0
	v_xor_b32_e32 v50, v51, v50
	v_cndmask_b32_e32 v50, v123, v50, vcc
	global_store_dword v243, v50, s[8:9] offset:2048
	s_add_u32 s8, s8, 0x1000
	s_addc_u32 s9, s9, 0
	v_mfma_f32_32x32x16_bf16 v[6:21], v[86:89], v[38:41], 0
	s_add_i32 m0, s10, 32768
	s_nop 0
	global_load_lds_dwordx4 v102, s[6:7]
	s_add_i32 m0, s10, 33792
	s_nop 0
	global_load_lds_dwordx4 v110, s[6:7]
	s_add_i32 m0, s10, 34816
	s_nop 0
	global_load_lds_dwordx4 v112, s[6:7]
	s_add_i32 m0, s10, 35840
	s_nop 0
	global_load_lds_dwordx4 v193, s[6:7]
	s_add_u32 s6, s6, 0x8000
	s_addc_u32 s7, s7, 0
	v_max_f32_e32 v108, 0, v212
	v_max_f32_e32 v109, 0, v213
	v_pk_mul_f32 v[0:1], v[22:23], v[108:109]
	v_max_f32_e32 v210, 0, v214
	v_max_f32_e32 v211, 0, v215
	v_pk_fma_f32 v[0:1], v[24:25], v[210:211], v[0:1]
	v_max_f32_e32 v108, 0, v216
	v_max_f32_e32 v109, 0, v217
	v_pk_fma_f32 v[0:1], v[26:27], v[108:109], v[0:1]
	v_mfma_f32_32x32x16_bf16 v[6:21], v[90:93], v[42:45], v[6:21]
	v_max_f32_e32 v210, 0, v218
	v_max_f32_e32 v211, 0, v219
	v_pk_fma_f32 v[0:1], v[28:29], v[210:211], v[0:1]
	v_max_f32_e32 v108, 0, v220
	v_max_f32_e32 v109, 0, v221
	v_pk_fma_f32 v[0:1], v[30:31], v[108:109], v[0:1]
	v_max_f32_e32 v210, 0, v222
	v_max_f32_e32 v211, 0, v223
	v_pk_fma_f32 v[0:1], v[32:33], v[210:211], v[0:1]
	v_mfma_f32_32x32x16_bf16 v[6:21], v[94:97], v[46:49], v[6:21]
	v_max_f32_e32 v108, 0, v224
	v_max_f32_e32 v109, 0, v225
	v_pk_fma_f32 v[0:1], v[34:35], v[108:109], v[0:1]
	v_max_f32_e32 v210, 0, v226
	v_max_f32_e32 v211, 0, v227
	v_pk_fma_f32 v[0:1], v[36:37], v[210:211], v[0:1]
	v_add_f32_e32 v0, v0, v1
	v_ashrrev_i32_e32 v1, 31, v0
	v_mfma_f32_32x32x16_bf16 v[6:21], v[98:101], v[196:199], v[6:21]
	s_waitcnt vmcnt(10)
	v_add_u32_e32 v228, 0x10000, v5
	ds_read_b128 v[38:41], v228 offset:43264
	v_add_u32_e32 v228, 0x10000, v52
	ds_read_b128 v[42:45], v228 offset:43264
	v_add_u32_e32 v228, 0x10000, v55
	ds_read_b128 v[46:49], v228 offset:43264
	v_add_u32_e32 v228, 0x10000, v56
	ds_read_b128 v[196:199], v228 offset:43264
	v_or_b32_e32 v1, 0x80000000, v1
	s_cmpk_gt_i32 s11, 240
	s_cselect_b64 vcc, -1, 0
	v_xor_b32_e32 v0, v1, v0
	v_cndmask_b32_e32 v163, v123, v0, vcc
	s_nop 3
	s_waitcnt lgkmcnt(3)
	v_mfma_f32_32x32x16_bf16 v[212:227], v[70:73], v[38:41], 0
	v_max_f32_e32 v108, 0, v6
	v_max_f32_e32 v109, 0, v7
	v_pk_mul_f32 v[50:51], v[244:245], v[108:109]
	v_max_f32_e32 v210, 0, v8
	v_max_f32_e32 v211, 0, v9
	v_pk_fma_f32 v[50:51], v[246:247], v[210:211], v[50:51]
	v_max_f32_e32 v108, 0, v10
	v_max_f32_e32 v109, 0, v11
	v_pk_fma_f32 v[50:51], v[248:249], v[108:109], v[50:51]
	s_waitcnt lgkmcnt(2)
	v_mfma_f32_32x32x16_bf16 v[212:227], v[74:77], v[42:45], v[212:227]
	v_max_f32_e32 v210, 0, v12
	v_max_f32_e32 v211, 0, v13
	v_pk_fma_f32 v[50:51], v[250:251], v[210:211], v[50:51]
	v_max_f32_e32 v108, 0, v14
	v_max_f32_e32 v109, 0, v15
	v_pk_fma_f32 v[50:51], v[252:253], v[108:109], v[50:51]
	v_max_f32_e32 v210, 0, v16
	v_max_f32_e32 v211, 0, v17
	v_pk_fma_f32 v[50:51], v[254:255], v[210:211], v[50:51]
	s_waitcnt lgkmcnt(1)
	v_mfma_f32_32x32x16_bf16 v[212:227], v[78:81], v[46:49], v[212:227]
	v_max_f32_e32 v108, 0, v18
	v_max_f32_e32 v109, 0, v19
	v_pk_fma_f32 v[50:51], v[200:201], v[108:109], v[50:51]
	v_max_f32_e32 v210, 0, v20
	v_max_f32_e32 v211, 0, v21
	v_pk_fma_f32 v[50:51], v[202:203], v[210:211], v[50:51]
	v_add_f32_e32 v50, v50, v51
	v_ashrrev_i32_e32 v51, 31, v50
	s_waitcnt lgkmcnt(0)
	v_mfma_f32_32x32x16_bf16 v[212:227], v[82:85], v[196:199], v[212:227]
	v_or_b32_e32 v51, 0x80000000, v51
	s_cmpk_gt_i32 s11, 240
	s_cselect_b64 vcc, -1, 0
	v_xor_b32_e32 v50, v51, v50
	v_cndmask_b32_e32 v50, v123, v50, vcc
	global_store_dword v243, v50, s[8:9]
	v_mfma_f32_32x32x16_bf16 v[6:21], v[86:89], v[38:41], 0
	s_add_i32 m0, s10, 65536
	s_nop 0
	global_load_lds_dwordx4 v102, s[6:7]
	s_add_i32 m0, s10, 66560
	s_nop 0
	global_load_lds_dwordx4 v110, s[6:7]
	s_add_i32 m0, s10, 67584
	s_nop 0
	global_load_lds_dwordx4 v112, s[6:7]
	s_add_i32 m0, s10, 68608
	s_nop 0
	global_load_lds_dwordx4 v193, s[6:7]
	s_add_u32 s6, s6, 0x8000
	s_addc_u32 s7, s7, 0
	v_max_f32_e32 v108, 0, v212
	v_max_f32_e32 v109, 0, v213
	v_pk_mul_f32 v[0:1], v[22:23], v[108:109]
	v_max_f32_e32 v210, 0, v214
	v_max_f32_e32 v211, 0, v215
	v_pk_fma_f32 v[0:1], v[24:25], v[210:211], v[0:1]
	v_max_f32_e32 v108, 0, v216
	v_max_f32_e32 v109, 0, v217
	v_pk_fma_f32 v[0:1], v[26:27], v[108:109], v[0:1]
	v_mfma_f32_32x32x16_bf16 v[6:21], v[90:93], v[42:45], v[6:21]
	v_max_f32_e32 v210, 0, v218
	v_max_f32_e32 v211, 0, v219
	v_pk_fma_f32 v[0:1], v[28:29], v[210:211], v[0:1]
	v_max_f32_e32 v108, 0, v220
	v_max_f32_e32 v109, 0, v221
	v_pk_fma_f32 v[0:1], v[30:31], v[108:109], v[0:1]
	v_max_f32_e32 v210, 0, v222
	v_max_f32_e32 v211, 0, v223
	v_pk_fma_f32 v[0:1], v[32:33], v[210:211], v[0:1]
	v_mfma_f32_32x32x16_bf16 v[6:21], v[94:97], v[46:49], v[6:21]
	v_max_f32_e32 v108, 0, v224
	v_max_f32_e32 v109, 0, v225
	v_pk_fma_f32 v[0:1], v[34:35], v[108:109], v[0:1]
	v_max_f32_e32 v210, 0, v226
	v_max_f32_e32 v211, 0, v227
	v_pk_fma_f32 v[0:1], v[36:37], v[210:211], v[0:1]
	v_add_f32_e32 v0, v0, v1
	v_ashrrev_i32_e32 v1, 31, v0
	v_mfma_f32_32x32x16_bf16 v[6:21], v[98:101], v[196:199], v[6:21]
	s_waitcnt vmcnt(10)
	ds_read_b128 v[38:41], v5 offset:10496
	ds_read_b128 v[42:45], v52 offset:10496
	ds_read_b128 v[46:49], v55 offset:10496
	ds_read_b128 v[196:199], v56 offset:10496
	v_or_b32_e32 v1, 0x80000000, v1
	s_cmpk_gt_i32 s11, 248
	s_cselect_b64 vcc, -1, 0
	v_xor_b32_e32 v0, v1, v0
	v_cndmask_b32_e32 v152, v123, v0, vcc
	s_nop 3
	v_max_f32_e32 v108, 0, v6
	v_max_f32_e32 v109, 0, v7
	v_pk_mul_f32 v[50:51], v[244:245], v[108:109]
	v_max_f32_e32 v210, 0, v8
	v_max_f32_e32 v211, 0, v9
	v_pk_fma_f32 v[50:51], v[246:247], v[210:211], v[50:51]
	v_max_f32_e32 v108, 0, v10
	v_max_f32_e32 v109, 0, v11
	v_pk_fma_f32 v[50:51], v[248:249], v[108:109], v[50:51]
	v_max_f32_e32 v210, 0, v12
	v_max_f32_e32 v211, 0, v13
	v_pk_fma_f32 v[50:51], v[250:251], v[210:211], v[50:51]
	v_max_f32_e32 v108, 0, v14
	v_max_f32_e32 v109, 0, v15
	v_pk_fma_f32 v[50:51], v[252:253], v[108:109], v[50:51]
	v_max_f32_e32 v210, 0, v16
	v_max_f32_e32 v211, 0, v17
	v_pk_fma_f32 v[50:51], v[254:255], v[210:211], v[50:51]
	v_max_f32_e32 v108, 0, v18
	v_max_f32_e32 v109, 0, v19
	v_pk_fma_f32 v[50:51], v[200:201], v[108:109], v[50:51]
	v_max_f32_e32 v210, 0, v20
	v_max_f32_e32 v211, 0, v21
	v_pk_fma_f32 v[50:51], v[202:203], v[210:211], v[50:51]
	v_add_f32_e32 v50, v50, v51
	v_ashrrev_i32_e32 v51, 31, v50
	v_or_b32_e32 v51, 0x80000000, v51
	s_cmpk_gt_i32 s11, 248
	s_cselect_b64 vcc, -1, 0
	v_xor_b32_e32 v50, v51, v50
	v_cndmask_b32_e32 v50, v123, v50, vcc
	global_store_dword v243, v50, s[8:9] offset:2048
	s_add_u32 s8, s8, 0x1000
	s_addc_u32 s9, s9, 0
	s_cmpk_gt_i32 s81, 32
	s_cbranch_scc0 .Lix_fill_4
	s_waitcnt lgkmcnt(3)
	v_mfma_f32_32x32x16_bf16 v[212:227], v[70:73], v[38:41], 0
	s_add_i32 m0, s10, 98304
	s_nop 0
	global_load_lds_dwordx4 v102, s[6:7]
	s_waitcnt lgkmcnt(2)
	v_mfma_f32_32x32x16_bf16 v[212:227], v[74:77], v[42:45], v[212:227]
	s_add_i32 m0, s10, 99328
	s_nop 0
	global_load_lds_dwordx4 v110, s[6:7]
	s_waitcnt lgkmcnt(1)
	v_mfma_f32_32x32x16_bf16 v[212:227], v[78:81], v[46:49], v[212:227]
	s_add_i32 m0, s10, 100352
	s_nop 0
	global_load_lds_dwordx4 v112, s[6:7]
	s_waitcnt lgkmcnt(0)
	v_mfma_f32_32x32x16_bf16 v[212:227], v[82:85], v[196:199], v[212:227]
	s_add_i32 m0, s10, 101376
	s_nop 0
	global_load_lds_dwordx4 v193, s[6:7]
	s_add_u32 s6, s6, 0x8000
	s_addc_u32 s7, s7, 0
	v_mfma_f32_32x32x16_bf16 v[6:21], v[86:89], v[38:41], 0
	s_nop 7
	s_nop 2
	v_max_f32_e32 v108, 0, v212
	v_max_f32_e32 v109, 0, v213
	v_pk_mul_f32 v[0:1], v[22:23], v[108:109]
	v_max_f32_e32 v210, 0, v214
	v_max_f32_e32 v211, 0, v215
	v_pk_fma_f32 v[0:1], v[24:25], v[210:211], v[0:1]
	v_max_f32_e32 v108, 0, v216
	v_max_f32_e32 v109, 0, v217
	v_pk_fma_f32 v[0:1], v[26:27], v[108:109], v[0:1]
	v_mfma_f32_32x32x16_bf16 v[6:21], v[90:93], v[42:45], v[6:21]
	v_max_f32_e32 v210, 0, v218
	v_max_f32_e32 v211, 0, v219
	v_pk_fma_f32 v[0:1], v[28:29], v[210:211], v[0:1]
	v_max_f32_e32 v108, 0, v220
	v_max_f32_e32 v109, 0, v221
	v_pk_fma_f32 v[0:1], v[30:31], v[108:109], v[0:1]
	v_max_f32_e32 v210, 0, v222
	v_max_f32_e32 v211, 0, v223
	v_pk_fma_f32 v[0:1], v[32:33], v[210:211], v[0:1]
	v_mfma_f32_32x32x16_bf16 v[6:21], v[94:97], v[46:49], v[6:21]
	v_max_f32_e32 v108, 0, v224
	v_max_f32_e32 v109, 0, v225
	v_pk_fma_f32 v[0:1], v[34:35], v[108:109], v[0:1]
	v_max_f32_e32 v210, 0, v226
	v_max_f32_e32 v211, 0, v227
	v_pk_fma_f32 v[0:1], v[36:37], v[210:211], v[0:1]
	v_add_f32_e32 v0, v0, v1
	v_ashrrev_i32_e32 v1, 31, v0
	v_mfma_f32_32x32x16_bf16 v[6:21], v[98:101], v[196:199], v[6:21]
	s_waitcnt vmcnt(10)
	ds_read_b128 v[38:41], v5 offset:43264
	ds_read_b128 v[42:45], v52 offset:43264
	ds_read_b128 v[46:49], v55 offset:43264
	ds_read_b128 v[196:199], v56 offset:43264
	v_or_b32_e32 v1, 0x80000000, v1
	s_cmpk_gt_i32 s11, 256
	s_cselect_b64 vcc, -1, 0
	v_xor_b32_e32 v0, v1, v0
	v_cndmask_b32_e32 v165, v123, v0, vcc
	s_nop 3
	s_waitcnt lgkmcnt(3)
	v_mfma_f32_32x32x16_bf16 v[212:227], v[70:73], v[38:41], 0
	v_max_f32_e32 v108, 0, v6
	v_max_f32_e32 v109, 0, v7
	v_pk_mul_f32 v[50:51], v[244:245], v[108:109]
	v_max_f32_e32 v210, 0, v8
	v_max_f32_e32 v211, 0, v9
	v_pk_fma_f32 v[50:51], v[246:247], v[210:211], v[50:51]
	v_max_f32_e32 v108, 0, v10
	v_max_f32_e32 v109, 0, v11
	v_pk_fma_f32 v[50:51], v[248:249], v[108:109], v[50:51]
	s_waitcnt lgkmcnt(2)
	v_mfma_f32_32x32x16_bf16 v[212:227], v[74:77], v[42:45], v[212:227]
	v_max_f32_e32 v210, 0, v12
	v_max_f32_e32 v211, 0, v13
	v_pk_fma_f32 v[50:51], v[250:251], v[210:211], v[50:51]
	v_max_f32_e32 v108, 0, v14
	v_max_f32_e32 v109, 0, v15
	v_pk_fma_f32 v[50:51], v[252:253], v[108:109], v[50:51]
	v_max_f32_e32 v210, 0, v16
	v_max_f32_e32 v211, 0, v17
	v_pk_fma_f32 v[50:51], v[254:255], v[210:211], v[50:51]
	s_waitcnt lgkmcnt(1)
	v_mfma_f32_32x32x16_bf16 v[212:227], v[78:81], v[46:49], v[212:227]
	v_max_f32_e32 v108, 0, v18
	v_max_f32_e32 v109, 0, v19
	v_pk_fma_f32 v[50:51], v[200:201], v[108:109], v[50:51]
	v_max_f32_e32 v210, 0, v20
	v_max_f32_e32 v211, 0, v21
	v_pk_fma_f32 v[50:51], v[202:203], v[210:211], v[50:51]
	v_add_f32_e32 v50, v50, v51
	v_ashrrev_i32_e32 v51, 31, v50
	s_waitcnt lgkmcnt(0)
	v_mfma_f32_32x32x16_bf16 v[212:227], v[82:85], v[196:199], v[212:227]
	v_or_b32_e32 v51, 0x80000000, v51
	s_cmpk_gt_i32 s11, 256
	s_cselect_b64 vcc, -1, 0
	v_xor_b32_e32 v50, v51, v50
	v_cndmask_b32_e32 v50, v123, v50, vcc
	global_store_dword v243, v50, s[8:9]
	v_mfma_f32_32x32x16_bf16 v[6:21], v[86:89], v[38:41], 0
	s_add_i32 m0, s10, 0
	s_nop 0
	global_load_lds_dwordx4 v102, s[6:7]
	s_add_i32 m0, s10, 1024
	s_nop 0
	global_load_lds_dwordx4 v110, s[6:7]
	s_add_i32 m0, s10, 2048
	s_nop 0
	global_load_lds_dwordx4 v112, s[6:7]
	s_add_i32 m0, s10, 3072
	s_nop 0
	global_load_lds_dwordx4 v193, s[6:7]
	s_add_u32 s6, s6, 0x8000
	s_addc_u32 s7, s7, 0
	v_max_f32_e32 v108, 0, v212
	v_max_f32_e32 v109, 0, v213
	v_pk_mul_f32 v[0:1], v[22:23], v[108:109]
	v_max_f32_e32 v210, 0, v214
	v_max_f32_e32 v211, 0, v215
	v_pk_fma_f32 v[0:1], v[24:25], v[210:211], v[0:1]
	v_max_f32_e32 v108, 0, v216
	v_max_f32_e32 v109, 0, v217
	v_pk_fma_f32 v[0:1], v[26:27], v[108:109], v[0:1]
	v_mfma_f32_32x32x16_bf16 v[6:21], v[90:93], v[42:45], v[6:21]
	v_max_f32_e32 v210, 0, v218
	v_max_f32_e32 v211, 0, v219
	v_pk_fma_f32 v[0:1], v[28:29], v[210:211], v[0:1]
	v_max_f32_e32 v108, 0, v220
	v_max_f32_e32 v109, 0, v221
	v_pk_fma_f32 v[0:1], v[30:31], v[108:109], v[0:1]
	v_max_f32_e32 v210, 0, v222
	v_max_f32_e32 v211, 0, v223
	v_pk_fma_f32 v[0:1], v[32:33], v[210:211], v[0:1]
	v_mfma_f32_32x32x16_bf16 v[6:21], v[94:97], v[46:49], v[6:21]
	v_max_f32_e32 v108, 0, v224
	v_max_f32_e32 v109, 0, v225
	v_pk_fma_f32 v[0:1], v[34:35], v[108:109], v[0:1]
	v_max_f32_e32 v210, 0, v226
	v_max_f32_e32 v211, 0, v227
	v_pk_fma_f32 v[0:1], v[36:37], v[210:211], v[0:1]
	v_add_f32_e32 v0, v0, v1
	v_ashrrev_i32_e32 v1, 31, v0
	v_mfma_f32_32x32x16_bf16 v[6:21], v[98:101], v[196:199], v[6:21]
	s_waitcnt vmcnt(10)
	v_add_u32_e32 v228, 0x10000, v5
	ds_read_b128 v[38:41], v228 offset:10496
	v_add_u32_e32 v228, 0x10000, v52
	ds_read_b128 v[42:45], v228 offset:10496
	v_add_u32_e32 v228, 0x10000, v55
	ds_read_b128 v[46:49], v228 offset:10496
	v_add_u32_e32 v228, 0x10000, v56
	ds_read_b128 v[196:199], v228 offset:10496
	v_or_b32_e32 v1, 0x80000000, v1
	s_cmpk_gt_i32 s11, 264
	s_cselect_b64 vcc, -1, 0
	v_xor_b32_e32 v0, v1, v0
	v_cndmask_b32_e32 v164, v123, v0, vcc
	s_nop 3
	s_waitcnt lgkmcnt(3)
	v_mfma_f32_32x32x16_bf16 v[212:227], v[70:73], v[38:41], 0
	v_max_f32_e32 v108, 0, v6
	v_max_f32_e32 v109, 0, v7
	v_pk_mul_f32 v[50:51], v[244:245], v[108:109]
	v_max_f32_e32 v210, 0, v8
	v_max_f32_e32 v211, 0, v9
	v_pk_fma_f32 v[50:51], v[246:247], v[210:211], v[50:51]
	v_max_f32_e32 v108, 0, v10
	v_max_f32_e32 v109, 0, v11
	v_pk_fma_f32 v[50:51], v[248:249], v[108:109], v[50:51]
	s_waitcnt lgkmcnt(2)
	v_mfma_f32_32x32x16_bf16 v[212:227], v[74:77], v[42:45], v[212:227]
	v_max_f32_e32 v210, 0, v12
	v_max_f32_e32 v211, 0, v13
	v_pk_fma_f32 v[50:51], v[250:251], v[210:211], v[50:51]
	v_max_f32_e32 v108, 0, v14
	v_max_f32_e32 v109, 0, v15
	v_pk_fma_f32 v[50:51], v[252:253], v[108:109], v[50:51]
	v_max_f32_e32 v210, 0, v16
	v_max_f32_e32 v211, 0, v17
	v_pk_fma_f32 v[50:51], v[254:255], v[210:211], v[50:51]
	s_waitcnt lgkmcnt(1)
	v_mfma_f32_32x32x16_bf16 v[212:227], v[78:81], v[46:49], v[212:227]
	v_max_f32_e32 v108, 0, v18
	v_max_f32_e32 v109, 0, v19
	v_pk_fma_f32 v[50:51], v[200:201], v[108:109], v[50:51]
	v_max_f32_e32 v210, 0, v20
	v_max_f32_e32 v211, 0, v21
	v_pk_fma_f32 v[50:51], v[202:203], v[210:211], v[50:51]
	v_add_f32_e32 v50, v50, v51
	v_ashrrev_i32_e32 v51, 31, v50
	s_waitcnt lgkmcnt(0)
	v_mfma_f32_32x32x16_bf16 v[212:227], v[82:85], v[196:199], v[212:227]
	v_or_b32_e32 v51, 0x80000000, v51
	s_cmpk_gt_i32 s11, 264
	s_cselect_b64 vcc, -1, 0
	v_xor_b32_e32 v50, v51, v50
	v_cndmask_b32_e32 v50, v123, v50, vcc
	global_store_dword v243, v50, s[8:9] offset:2048
	s_add_u32 s8, s8, 0x1000
	s_addc_u32 s9, s9, 0
	v_mfma_f32_32x32x16_bf16 v[6:21], v[86:89], v[38:41], 0
	s_add_i32 m0, s10, 32768
	s_nop 0
	global_load_lds_dwordx4 v102, s[6:7]
	s_add_i32 m0, s10, 33792
	s_nop 0
	global_load_lds_dwordx4 v110, s[6:7]
	s_add_i32 m0, s10, 34816
	s_nop 0
	global_load_lds_dwordx4 v112, s[6:7]
	s_add_i32 m0, s10, 35840
	s_nop 0
	global_load_lds_dwordx4 v193, s[6:7]
	s_add_u32 s6, s6, 0x8000
	s_addc_u32 s7, s7, 0
	v_max_f32_e32 v108, 0, v212
	v_max_f32_e32 v109, 0, v213
	v_pk_mul_f32 v[0:1], v[22:23], v[108:109]
	v_max_f32_e32 v210, 0, v214
	v_max_f32_e32 v211, 0, v215
	v_pk_fma_f32 v[0:1], v[24:25], v[210:211], v[0:1]
	v_max_f32_e32 v108, 0, v216
	v_max_f32_e32 v109, 0, v217
	v_pk_fma_f32 v[0:1], v[26:27], v[108:109], v[0:1]
	v_mfma_f32_32x32x16_bf16 v[6:21], v[90:93], v[42:45], v[6:21]
	v_max_f32_e32 v210, 0, v218
	v_max_f32_e32 v211, 0, v219
	v_pk_fma_f32 v[0:1], v[28:29], v[210:211], v[0:1]
	v_max_f32_e32 v108, 0, v220
	v_max_f32_e32 v109, 0, v221
	v_pk_fma_f32 v[0:1], v[30:31], v[108:109], v[0:1]
	v_max_f32_e32 v210, 0, v222
	v_max_f32_e32 v211, 0, v223
	v_pk_fma_f32 v[0:1], v[32:33], v[210:211], v[0:1]
	v_mfma_f32_32x32x16_bf16 v[6:21], v[94:97], v[46:49], v[6:21]
	v_max_f32_e32 v108, 0, v224
	v_max_f32_e32 v109, 0, v225
	v_pk_fma_f32 v[0:1], v[34:35], v[108:109], v[0:1]
	v_max_f32_e32 v210, 0, v226
	v_max_f32_e32 v211, 0, v227
	v_pk_fma_f32 v[0:1], v[36:37], v[210:211], v[0:1]
	v_add_f32_e32 v0, v0, v1
	v_ashrrev_i32_e32 v1, 31, v0
	v_mfma_f32_32x32x16_bf16 v[6:21], v[98:101], v[196:199], v[6:21]
	s_waitcnt vmcnt(10)
	v_add_u32_e32 v228, 0x10000, v5
	ds_read_b128 v[38:41], v228 offset:43264
	v_add_u32_e32 v228, 0x10000, v52
	ds_read_b128 v[42:45], v228 offset:43264
	v_add_u32_e32 v228, 0x10000, v55
	ds_read_b128 v[46:49], v228 offset:43264
	v_add_u32_e32 v228, 0x10000, v56
	ds_read_b128 v[196:199], v228 offset:43264
	v_or_b32_e32 v1, 0x80000000, v1
	s_cmpk_gt_i32 s11, 272
	s_cselect_b64 vcc, -1, 0
	v_xor_b32_e32 v0, v1, v0
	v_cndmask_b32_e32 v167, v123, v0, vcc
	s_nop 3
	s_waitcnt lgkmcnt(3)
	v_mfma_f32_32x32x16_bf16 v[212:227], v[70:73], v[38:41], 0
	v_max_f32_e32 v108, 0, v6
	v_max_f32_e32 v109, 0, v7
	v_pk_mul_f32 v[50:51], v[244:245], v[108:109]
	v_max_f32_e32 v210, 0, v8
	v_max_f32_e32 v211, 0, v9
	v_pk_fma_f32 v[50:51], v[246:247], v[210:211], v[50:51]
	v_max_f32_e32 v108, 0, v10
	v_max_f32_e32 v109, 0, v11
	v_pk_fma_f32 v[50:51], v[248:249], v[108:109], v[50:51]
	s_waitcnt lgkmcnt(2)
	v_mfma_f32_32x32x16_bf16 v[212:227], v[74:77], v[42:45], v[212:227]
	v_max_f32_e32 v210, 0, v12
	v_max_f32_e32 v211, 0, v13
	v_pk_fma_f32 v[50:51], v[250:251], v[210:211], v[50:51]
	v_max_f32_e32 v108, 0, v14
	v_max_f32_e32 v109, 0, v15
	v_pk_fma_f32 v[50:51], v[252:253], v[108:109], v[50:51]
	v_max_f32_e32 v210, 0, v16
	v_max_f32_e32 v211, 0, v17
	v_pk_fma_f32 v[50:51], v[254:255], v[210:211], v[50:51]
	s_waitcnt lgkmcnt(1)
	v_mfma_f32_32x32x16_bf16 v[212:227], v[78:81], v[46:49], v[212:227]
	v_max_f32_e32 v108, 0, v18
	v_max_f32_e32 v109, 0, v19
	v_pk_fma_f32 v[50:51], v[200:201], v[108:109], v[50:51]
	v_max_f32_e32 v210, 0, v20
	v_max_f32_e32 v211, 0, v21
	v_pk_fma_f32 v[50:51], v[202:203], v[210:211], v[50:51]
	v_add_f32_e32 v50, v50, v51
	v_ashrrev_i32_e32 v51, 31, v50
	s_waitcnt lgkmcnt(0)
	v_mfma_f32_32x32x16_bf16 v[212:227], v[82:85], v[196:199], v[212:227]
	v_or_b32_e32 v51, 0x80000000, v51
	s_cmpk_gt_i32 s11, 272
	s_cselect_b64 vcc, -1, 0
	v_xor_b32_e32 v50, v51, v50
	v_cndmask_b32_e32 v50, v123, v50, vcc
	global_store_dword v243, v50, s[8:9]
	v_mfma_f32_32x32x16_bf16 v[6:21], v[86:89], v[38:41], 0
	s_add_i32 m0, s10, 65536
	s_nop 0
	global_load_lds_dwordx4 v102, s[6:7]
	s_add_i32 m0, s10, 66560
	s_nop 0
	global_load_lds_dwordx4 v110, s[6:7]
	s_add_i32 m0, s10, 67584
	s_nop 0
	global_load_lds_dwordx4 v112, s[6:7]
	s_add_i32 m0, s10, 68608
	s_nop 0
	global_load_lds_dwordx4 v193, s[6:7]
	s_add_u32 s6, s6, 0x8000
	s_addc_u32 s7, s7, 0
	v_max_f32_e32 v108, 0, v212
	v_max_f32_e32 v109, 0, v213
	v_pk_mul_f32 v[0:1], v[22:23], v[108:109]
	v_max_f32_e32 v210, 0, v214
	v_max_f32_e32 v211, 0, v215
	v_pk_fma_f32 v[0:1], v[24:25], v[210:211], v[0:1]
	v_max_f32_e32 v108, 0, v216
	v_max_f32_e32 v109, 0, v217
	v_pk_fma_f32 v[0:1], v[26:27], v[108:109], v[0:1]
	v_mfma_f32_32x32x16_bf16 v[6:21], v[90:93], v[42:45], v[6:21]
	v_max_f32_e32 v210, 0, v218
	v_max_f32_e32 v211, 0, v219
	v_pk_fma_f32 v[0:1], v[28:29], v[210:211], v[0:1]
	v_max_f32_e32 v108, 0, v220
	v_max_f32_e32 v109, 0, v221
	v_pk_fma_f32 v[0:1], v[30:31], v[108:109], v[0:1]
	v_max_f32_e32 v210, 0, v222
	v_max_f32_e32 v211, 0, v223
	v_pk_fma_f32 v[0:1], v[32:33], v[210:211], v[0:1]
	v_mfma_f32_32x32x16_bf16 v[6:21], v[94:97], v[46:49], v[6:21]
	v_max_f32_e32 v108, 0, v224
	v_max_f32_e32 v109, 0, v225
	v_pk_fma_f32 v[0:1], v[34:35], v[108:109], v[0:1]
	v_max_f32_e32 v210, 0, v226
	v_max_f32_e32 v211, 0, v227
	v_pk_fma_f32 v[0:1], v[36:37], v[210:211], v[0:1]
	v_add_f32_e32 v0, v0, v1
	v_ashrrev_i32_e32 v1, 31, v0
	v_mfma_f32_32x32x16_bf16 v[6:21], v[98:101], v[196:199], v[6:21]
	s_waitcnt vmcnt(10)
	ds_read_b128 v[38:41], v5 offset:10496
	ds_read_b128 v[42:45], v52 offset:10496
	ds_read_b128 v[46:49], v55 offset:10496
	ds_read_b128 v[196:199], v56 offset:10496
	v_or_b32_e32 v1, 0x80000000, v1
	s_cmpk_gt_i32 s11, 280
	s_cselect_b64 vcc, -1, 0
	v_xor_b32_e32 v0, v1, v0
	v_cndmask_b32_e32 v166, v123, v0, vcc
	s_nop 3
	s_waitcnt lgkmcnt(3)
	v_mfma_f32_32x32x16_bf16 v[212:227], v[70:73], v[38:41], 0
	v_max_f32_e32 v108, 0, v6
	v_max_f32_e32 v109, 0, v7
	v_pk_mul_f32 v[50:51], v[244:245], v[108:109]
	v_max_f32_e32 v210, 0, v8
	v_max_f32_e32 v211, 0, v9
	v_pk_fma_f32 v[50:51], v[246:247], v[210:211], v[50:51]
	v_max_f32_e32 v108, 0, v10
	v_max_f32_e32 v109, 0, v11
	v_pk_fma_f32 v[50:51], v[248:249], v[108:109], v[50:51]
	s_waitcnt lgkmcnt(2)
	v_mfma_f32_32x32x16_bf16 v[212:227], v[74:77], v[42:45], v[212:227]
	v_max_f32_e32 v210, 0, v12
	v_max_f32_e32 v211, 0, v13
	v_pk_fma_f32 v[50:51], v[250:251], v[210:211], v[50:51]
	v_max_f32_e32 v108, 0, v14
	v_max_f32_e32 v109, 0, v15
	v_pk_fma_f32 v[50:51], v[252:253], v[108:109], v[50:51]
	v_max_f32_e32 v210, 0, v16
	v_max_f32_e32 v211, 0, v17
	v_pk_fma_f32 v[50:51], v[254:255], v[210:211], v[50:51]
	s_waitcnt lgkmcnt(1)
	v_mfma_f32_32x32x16_bf16 v[212:227], v[78:81], v[46:49], v[212:227]
	v_max_f32_e32 v108, 0, v18
	v_max_f32_e32 v109, 0, v19
	v_pk_fma_f32 v[50:51], v[200:201], v[108:109], v[50:51]
	v_max_f32_e32 v210, 0, v20
	v_max_f32_e32 v211, 0, v21
	v_pk_fma_f32 v[50:51], v[202:203], v[210:211], v[50:51]
	v_add_f32_e32 v50, v50, v51
	v_ashrrev_i32_e32 v51, 31, v50
	s_waitcnt lgkmcnt(0)
	v_mfma_f32_32x32x16_bf16 v[212:227], v[82:85], v[196:199], v[212:227]
	v_or_b32_e32 v51, 0x80000000, v51
	s_cmpk_gt_i32 s11, 280
	s_cselect_b64 vcc, -1, 0
	v_xor_b32_e32 v50, v51, v50
	v_cndmask_b32_e32 v50, v123, v50, vcc
	global_store_dword v243, v50, s[8:9] offset:2048
	s_add_u32 s8, s8, 0x1000
	s_addc_u32 s9, s9, 0
	v_mfma_f32_32x32x16_bf16 v[6:21], v[86:89], v[38:41], 0
	s_add_i32 m0, s10, 98304
	s_nop 0
	global_load_lds_dwordx4 v102, s[6:7]
	s_add_i32 m0, s10, 99328
	s_nop 0
	global_load_lds_dwordx4 v110, s[6:7]
	s_add_i32 m0, s10, 100352
	s_nop 0
	global_load_lds_dwordx4 v112, s[6:7]
	s_add_i32 m0, s10, 101376
	s_nop 0
	global_load_lds_dwordx4 v193, s[6:7]
	s_add_u32 s6, s6, 0x8000
	s_addc_u32 s7, s7, 0
	v_max_f32_e32 v108, 0, v212
	v_max_f32_e32 v109, 0, v213
	v_pk_mul_f32 v[0:1], v[22:23], v[108:109]
	v_max_f32_e32 v210, 0, v214
	v_max_f32_e32 v211, 0, v215
	v_pk_fma_f32 v[0:1], v[24:25], v[210:211], v[0:1]
	v_max_f32_e32 v108, 0, v216
	v_max_f32_e32 v109, 0, v217
	v_pk_fma_f32 v[0:1], v[26:27], v[108:109], v[0:1]
	v_mfma_f32_32x32x16_bf16 v[6:21], v[90:93], v[42:45], v[6:21]
	v_max_f32_e32 v210, 0, v218
	v_max_f32_e32 v211, 0, v219
	v_pk_fma_f32 v[0:1], v[28:29], v[210:211], v[0:1]
	v_max_f32_e32 v108, 0, v220
	v_max_f32_e32 v109, 0, v221
	v_pk_fma_f32 v[0:1], v[30:31], v[108:109], v[0:1]
	v_max_f32_e32 v210, 0, v222
	v_max_f32_e32 v211, 0, v223
	v_pk_fma_f32 v[0:1], v[32:33], v[210:211], v[0:1]
	v_mfma_f32_32x32x16_bf16 v[6:21], v[94:97], v[46:49], v[6:21]
	v_max_f32_e32 v108, 0, v224
	v_max_f32_e32 v109, 0, v225
	v_pk_fma_f32 v[0:1], v[34:35], v[108:109], v[0:1]
	v_max_f32_e32 v210, 0, v226
	v_max_f32_e32 v211, 0, v227
	v_pk_fma_f32 v[0:1], v[36:37], v[210:211], v[0:1]
	v_add_f32_e32 v0, v0, v1
	v_ashrrev_i32_e32 v1, 31, v0
	v_mfma_f32_32x32x16_bf16 v[6:21], v[98:101], v[196:199], v[6:21]
	s_waitcnt vmcnt(10)
	ds_read_b128 v[38:41], v5 offset:43264
	ds_read_b128 v[42:45], v52 offset:43264
	ds_read_b128 v[46:49], v55 offset:43264
	ds_read_b128 v[196:199], v56 offset:43264
	v_or_b32_e32 v1, 0x80000000, v1
	s_cmpk_gt_i32 s11, 288
	s_cselect_b64 vcc, -1, 0
	v_xor_b32_e32 v0, v1, v0
	v_cndmask_b32_e32 v170, v123, v0, vcc
	s_nop 3
	s_waitcnt lgkmcnt(3)
	v_mfma_f32_32x32x16_bf16 v[212:227], v[70:73], v[38:41], 0
	v_max_f32_e32 v108, 0, v6
	v_max_f32_e32 v109, 0, v7
	v_pk_mul_f32 v[50:51], v[244:245], v[108:109]
	v_max_f32_e32 v210, 0, v8
	v_max_f32_e32 v211, 0, v9
	v_pk_fma_f32 v[50:51], v[246:247], v[210:211], v[50:51]
	v_max_f32_e32 v108, 0, v10
	v_max_f32_e32 v109, 0, v11
	v_pk_fma_f32 v[50:51], v[248:249], v[108:109], v[50:51]
	s_waitcnt lgkmcnt(2)
	v_mfma_f32_32x32x16_bf16 v[212:227], v[74:77], v[42:45], v[212:227]
	v_max_f32_e32 v210, 0, v12
	v_max_f32_e32 v211, 0, v13
	v_pk_fma_f32 v[50:51], v[250:251], v[210:211], v[50:51]
	v_max_f32_e32 v108, 0, v14
	v_max_f32_e32 v109, 0, v15
	v_pk_fma_f32 v[50:51], v[252:253], v[108:109], v[50:51]
	v_max_f32_e32 v210, 0, v16
	v_max_f32_e32 v211, 0, v17
	v_pk_fma_f32 v[50:51], v[254:255], v[210:211], v[50:51]
	s_waitcnt lgkmcnt(1)
	v_mfma_f32_32x32x16_bf16 v[212:227], v[78:81], v[46:49], v[212:227]
	v_max_f32_e32 v108, 0, v18
	v_max_f32_e32 v109, 0, v19
	v_pk_fma_f32 v[50:51], v[200:201], v[108:109], v[50:51]
	v_max_f32_e32 v210, 0, v20
	v_max_f32_e32 v211, 0, v21
	v_pk_fma_f32 v[50:51], v[202:203], v[210:211], v[50:51]
	v_add_f32_e32 v50, v50, v51
	v_ashrrev_i32_e32 v51, 31, v50
	s_waitcnt lgkmcnt(0)
	v_mfma_f32_32x32x16_bf16 v[212:227], v[82:85], v[196:199], v[212:227]
	v_or_b32_e32 v51, 0x80000000, v51
	s_cmpk_gt_i32 s11, 288
	s_cselect_b64 vcc, -1, 0
	v_xor_b32_e32 v50, v51, v50
	v_cndmask_b32_e32 v50, v123, v50, vcc
	global_store_dword v243, v50, s[8:9]
	v_mfma_f32_32x32x16_bf16 v[6:21], v[86:89], v[38:41], 0
	s_add_i32 m0, s10, 0
	s_nop 0
	global_load_lds_dwordx4 v102, s[6:7]
	s_add_i32 m0, s10, 1024
	s_nop 0
	global_load_lds_dwordx4 v110, s[6:7]
	s_add_i32 m0, s10, 2048
	s_nop 0
	global_load_lds_dwordx4 v112, s[6:7]
	s_add_i32 m0, s10, 3072
	s_nop 0
	global_load_lds_dwordx4 v193, s[6:7]
	s_add_u32 s6, s6, 0x8000
	s_addc_u32 s7, s7, 0
	v_max_f32_e32 v108, 0, v212
	v_max_f32_e32 v109, 0, v213
	v_pk_mul_f32 v[0:1], v[22:23], v[108:109]
	v_max_f32_e32 v210, 0, v214
	v_max_f32_e32 v211, 0, v215
	v_pk_fma_f32 v[0:1], v[24:25], v[210:211], v[0:1]
	v_max_f32_e32 v108, 0, v216
	v_max_f32_e32 v109, 0, v217
	v_pk_fma_f32 v[0:1], v[26:27], v[108:109], v[0:1]
	v_mfma_f32_32x32x16_bf16 v[6:21], v[90:93], v[42:45], v[6:21]
	v_max_f32_e32 v210, 0, v218
	v_max_f32_e32 v211, 0, v219
	v_pk_fma_f32 v[0:1], v[28:29], v[210:211], v[0:1]
	v_max_f32_e32 v108, 0, v220
	v_max_f32_e32 v109, 0, v221
	v_pk_fma_f32 v[0:1], v[30:31], v[108:109], v[0:1]
	v_max_f32_e32 v210, 0, v222
	v_max_f32_e32 v211, 0, v223
	v_pk_fma_f32 v[0:1], v[32:33], v[210:211], v[0:1]
	v_mfma_f32_32x32x16_bf16 v[6:21], v[94:97], v[46:49], v[6:21]
	v_max_f32_e32 v108, 0, v224
	v_max_f32_e32 v109, 0, v225
	v_pk_fma_f32 v[0:1], v[34:35], v[108:109], v[0:1]
	v_max_f32_e32 v210, 0, v226
	v_max_f32_e32 v211, 0, v227
	v_pk_fma_f32 v[0:1], v[36:37], v[210:211], v[0:1]
	v_add_f32_e32 v0, v0, v1
	v_ashrrev_i32_e32 v1, 31, v0
	v_mfma_f32_32x32x16_bf16 v[6:21], v[98:101], v[196:199], v[6:21]
	s_waitcnt vmcnt(10)
	v_add_u32_e32 v228, 0x10000, v5
	ds_read_b128 v[38:41], v228 offset:10496
	v_add_u32_e32 v228, 0x10000, v52
	ds_read_b128 v[42:45], v228 offset:10496
	v_add_u32_e32 v228, 0x10000, v55
	ds_read_b128 v[46:49], v228 offset:10496
	v_add_u32_e32 v228, 0x10000, v56
	ds_read_b128 v[196:199], v228 offset:10496
	v_or_b32_e32 v1, 0x80000000, v1
	s_cmpk_gt_i32 s11, 296
	s_cselect_b64 vcc, -1, 0
	v_xor_b32_e32 v0, v1, v0
	v_cndmask_b32_e32 v169, v123, v0, vcc
	s_nop 3
	s_waitcnt lgkmcnt(3)
	v_mfma_f32_32x32x16_bf16 v[212:227], v[70:73], v[38:41], 0
	v_max_f32_e32 v108, 0, v6
	v_max_f32_e32 v109, 0, v7
	v_pk_mul_f32 v[50:51], v[244:245], v[108:109]
	v_max_f32_e32 v210, 0, v8
	v_max_f32_e32 v211, 0, v9
	v_pk_fma_f32 v[50:51], v[246:247], v[210:211], v[50:51]
	v_max_f32_e32 v108, 0, v10
	v_max_f32_e32 v109, 0, v11
	v_pk_fma_f32 v[50:51], v[248:249], v[108:109], v[50:51]
	s_waitcnt lgkmcnt(2)
	v_mfma_f32_32x32x16_bf16 v[212:227], v[74:77], v[42:45], v[212:227]
	v_max_f32_e32 v210, 0, v12
	v_max_f32_e32 v211, 0, v13
	v_pk_fma_f32 v[50:51], v[250:251], v[210:211], v[50:51]
	v_max_f32_e32 v108, 0, v14
	v_max_f32_e32 v109, 0, v15
	v_pk_fma_f32 v[50:51], v[252:253], v[108:109], v[50:51]
	v_max_f32_e32 v210, 0, v16
	v_max_f32_e32 v211, 0, v17
	v_pk_fma_f32 v[50:51], v[254:255], v[210:211], v[50:51]
	s_waitcnt lgkmcnt(1)
	v_mfma_f32_32x32x16_bf16 v[212:227], v[78:81], v[46:49], v[212:227]
	v_max_f32_e32 v108, 0, v18
	v_max_f32_e32 v109, 0, v19
	v_pk_fma_f32 v[50:51], v[200:201], v[108:109], v[50:51]
	v_max_f32_e32 v210, 0, v20
	v_max_f32_e32 v211, 0, v21
	v_pk_fma_f32 v[50:51], v[202:203], v[210:211], v[50:51]
	v_add_f32_e32 v50, v50, v51
	v_ashrrev_i32_e32 v51, 31, v50
	s_waitcnt lgkmcnt(0)
	v_mfma_f32_32x32x16_bf16 v[212:227], v[82:85], v[196:199], v[212:227]
	v_or_b32_e32 v51, 0x80000000, v51
	s_cmpk_gt_i32 s11, 296
	s_cselect_b64 vcc, -1, 0
	v_xor_b32_e32 v50, v51, v50
	v_cndmask_b32_e32 v50, v123, v50, vcc
	global_store_dword v243, v50, s[8:9] offset:2048
	s_add_u32 s8, s8, 0x1000
	s_addc_u32 s9, s9, 0
	v_mfma_f32_32x32x16_bf16 v[6:21], v[86:89], v[38:41], 0
	s_add_i32 m0, s10, 32768
	s_nop 0
	global_load_lds_dwordx4 v102, s[6:7]
	s_add_i32 m0, s10, 33792
	s_nop 0
	global_load_lds_dwordx4 v110, s[6:7]
	s_add_i32 m0, s10, 34816
	s_nop 0
	global_load_lds_dwordx4 v112, s[6:7]
	s_add_i32 m0, s10, 35840
	s_nop 0
	global_load_lds_dwordx4 v193, s[6:7]
	s_add_u32 s6, s6, 0x8000
	s_addc_u32 s7, s7, 0
	v_max_f32_e32 v108, 0, v212
	v_max_f32_e32 v109, 0, v213
	v_pk_mul_f32 v[0:1], v[22:23], v[108:109]
	v_max_f32_e32 v210, 0, v214
	v_max_f32_e32 v211, 0, v215
	v_pk_fma_f32 v[0:1], v[24:25], v[210:211], v[0:1]
	v_max_f32_e32 v108, 0, v216
	v_max_f32_e32 v109, 0, v217
	v_pk_fma_f32 v[0:1], v[26:27], v[108:109], v[0:1]
	v_mfma_f32_32x32x16_bf16 v[6:21], v[90:93], v[42:45], v[6:21]
	v_max_f32_e32 v210, 0, v218
	v_max_f32_e32 v211, 0, v219
	v_pk_fma_f32 v[0:1], v[28:29], v[210:211], v[0:1]
	v_max_f32_e32 v108, 0, v220
	v_max_f32_e32 v109, 0, v221
	v_pk_fma_f32 v[0:1], v[30:31], v[108:109], v[0:1]
	v_max_f32_e32 v210, 0, v222
	v_max_f32_e32 v211, 0, v223
	v_pk_fma_f32 v[0:1], v[32:33], v[210:211], v[0:1]
	v_mfma_f32_32x32x16_bf16 v[6:21], v[94:97], v[46:49], v[6:21]
	v_max_f32_e32 v108, 0, v224
	v_max_f32_e32 v109, 0, v225
	v_pk_fma_f32 v[0:1], v[34:35], v[108:109], v[0:1]
	v_max_f32_e32 v210, 0, v226
	v_max_f32_e32 v211, 0, v227
	v_pk_fma_f32 v[0:1], v[36:37], v[210:211], v[0:1]
	v_add_f32_e32 v0, v0, v1
	v_ashrrev_i32_e32 v1, 31, v0
	v_mfma_f32_32x32x16_bf16 v[6:21], v[98:101], v[196:199], v[6:21]
	s_waitcnt vmcnt(10)
	v_add_u32_e32 v228, 0x10000, v5
	ds_read_b128 v[38:41], v228 offset:43264
	v_add_u32_e32 v228, 0x10000, v52
	ds_read_b128 v[42:45], v228 offset:43264
	v_add_u32_e32 v228, 0x10000, v55
	ds_read_b128 v[46:49], v228 offset:43264
	v_add_u32_e32 v228, 0x10000, v56
	ds_read_b128 v[196:199], v228 offset:43264
	v_or_b32_e32 v1, 0x80000000, v1
	s_cmpk_gt_i32 s11, 304
	s_cselect_b64 vcc, -1, 0
	v_xor_b32_e32 v0, v1, v0
	v_cndmask_b32_e32 v172, v123, v0, vcc
	s_nop 3
	s_waitcnt lgkmcnt(3)
	v_mfma_f32_32x32x16_bf16 v[212:227], v[70:73], v[38:41], 0
	v_max_f32_e32 v108, 0, v6
	v_max_f32_e32 v109, 0, v7
	v_pk_mul_f32 v[50:51], v[244:245], v[108:109]
	v_max_f32_e32 v210, 0, v8
	v_max_f32_e32 v211, 0, v9
	v_pk_fma_f32 v[50:51], v[246:247], v[210:211], v[50:51]
	v_max_f32_e32 v108, 0, v10
	v_max_f32_e32 v109, 0, v11
	v_pk_fma_f32 v[50:51], v[248:249], v[108:109], v[50:51]
	s_waitcnt lgkmcnt(2)
	v_mfma_f32_32x32x16_bf16 v[212:227], v[74:77], v[42:45], v[212:227]
	v_max_f32_e32 v210, 0, v12
	v_max_f32_e32 v211, 0, v13
	v_pk_fma_f32 v[50:51], v[250:251], v[210:211], v[50:51]
	v_max_f32_e32 v108, 0, v14
	v_max_f32_e32 v109, 0, v15
	v_pk_fma_f32 v[50:51], v[252:253], v[108:109], v[50:51]
	v_max_f32_e32 v210, 0, v16
	v_max_f32_e32 v211, 0, v17
	v_pk_fma_f32 v[50:51], v[254:255], v[210:211], v[50:51]
	s_waitcnt lgkmcnt(1)
	v_mfma_f32_32x32x16_bf16 v[212:227], v[78:81], v[46:49], v[212:227]
	v_max_f32_e32 v108, 0, v18
	v_max_f32_e32 v109, 0, v19
	v_pk_fma_f32 v[50:51], v[200:201], v[108:109], v[50:51]
	v_max_f32_e32 v210, 0, v20
	v_max_f32_e32 v211, 0, v21
	v_pk_fma_f32 v[50:51], v[202:203], v[210:211], v[50:51]
	v_add_f32_e32 v50, v50, v51
	v_ashrrev_i32_e32 v51, 31, v50
	s_waitcnt lgkmcnt(0)
	v_mfma_f32_32x32x16_bf16 v[212:227], v[82:85], v[196:199], v[212:227]
	v_or_b32_e32 v51, 0x80000000, v51
	s_cmpk_gt_i32 s11, 304
	s_cselect_b64 vcc, -1, 0
	v_xor_b32_e32 v50, v51, v50
	v_cndmask_b32_e32 v50, v123, v50, vcc
	global_store_dword v243, v50, s[8:9]
	v_mfma_f32_32x32x16_bf16 v[6:21], v[86:89], v[38:41], 0
	s_add_i32 m0, s10, 65536
	s_nop 0
	global_load_lds_dwordx4 v102, s[6:7]
	s_add_i32 m0, s10, 66560
	s_nop 0
	global_load_lds_dwordx4 v110, s[6:7]
	s_add_i32 m0, s10, 67584
	s_nop 0
	global_load_lds_dwordx4 v112, s[6:7]
	s_add_i32 m0, s10, 68608
	s_nop 0
	global_load_lds_dwordx4 v193, s[6:7]
	s_add_u32 s6, s6, 0x8000
	s_addc_u32 s7, s7, 0
	v_max_f32_e32 v108, 0, v212
	v_max_f32_e32 v109, 0, v213
	v_pk_mul_f32 v[0:1], v[22:23], v[108:109]
	v_max_f32_e32 v210, 0, v214
	v_max_f32_e32 v211, 0, v215
	v_pk_fma_f32 v[0:1], v[24:25], v[210:211], v[0:1]
	v_max_f32_e32 v108, 0, v216
	v_max_f32_e32 v109, 0, v217
	v_pk_fma_f32 v[0:1], v[26:27], v[108:109], v[0:1]
	v_mfma_f32_32x32x16_bf16 v[6:21], v[90:93], v[42:45], v[6:21]
	v_max_f32_e32 v210, 0, v218
	v_max_f32_e32 v211, 0, v219
	v_pk_fma_f32 v[0:1], v[28:29], v[210:211], v[0:1]
	v_max_f32_e32 v108, 0, v220
	v_max_f32_e32 v109, 0, v221
	v_pk_fma_f32 v[0:1], v[30:31], v[108:109], v[0:1]
	v_max_f32_e32 v210, 0, v222
	v_max_f32_e32 v211, 0, v223
	v_pk_fma_f32 v[0:1], v[32:33], v[210:211], v[0:1]
	v_mfma_f32_32x32x16_bf16 v[6:21], v[94:97], v[46:49], v[6:21]
	v_max_f32_e32 v108, 0, v224
	v_max_f32_e32 v109, 0, v225
	v_pk_fma_f32 v[0:1], v[34:35], v[108:109], v[0:1]
	v_max_f32_e32 v210, 0, v226
	v_max_f32_e32 v211, 0, v227
	v_pk_fma_f32 v[0:1], v[36:37], v[210:211], v[0:1]
	v_add_f32_e32 v0, v0, v1
	v_ashrrev_i32_e32 v1, 31, v0
	v_mfma_f32_32x32x16_bf16 v[6:21], v[98:101], v[196:199], v[6:21]
	s_waitcnt vmcnt(10)
	ds_read_b128 v[38:41], v5 offset:10496
	ds_read_b128 v[42:45], v52 offset:10496
	ds_read_b128 v[46:49], v55 offset:10496
	ds_read_b128 v[196:199], v56 offset:10496
	v_or_b32_e32 v1, 0x80000000, v1
	s_cmpk_gt_i32 s11, 312
	s_cselect_b64 vcc, -1, 0
	v_xor_b32_e32 v0, v1, v0
	v_cndmask_b32_e32 v171, v123, v0, vcc
	s_nop 3
	v_max_f32_e32 v108, 0, v6
	v_max_f32_e32 v109, 0, v7
	v_pk_mul_f32 v[50:51], v[244:245], v[108:109]
	v_max_f32_e32 v210, 0, v8
	v_max_f32_e32 v211, 0, v9
	v_pk_fma_f32 v[50:51], v[246:247], v[210:211], v[50:51]
	v_max_f32_e32 v108, 0, v10
	v_max_f32_e32 v109, 0, v11
	v_pk_fma_f32 v[50:51], v[248:249], v[108:109], v[50:51]
	v_max_f32_e32 v210, 0, v12
	v_max_f32_e32 v211, 0, v13
	v_pk_fma_f32 v[50:51], v[250:251], v[210:211], v[50:51]
	v_max_f32_e32 v108, 0, v14
	v_max_f32_e32 v109, 0, v15
	v_pk_fma_f32 v[50:51], v[252:253], v[108:109], v[50:51]
	v_max_f32_e32 v210, 0, v16
	v_max_f32_e32 v211, 0, v17
	v_pk_fma_f32 v[50:51], v[254:255], v[210:211], v[50:51]
	v_max_f32_e32 v108, 0, v18
	v_max_f32_e32 v109, 0, v19
	v_pk_fma_f32 v[50:51], v[200:201], v[108:109], v[50:51]
	v_max_f32_e32 v210, 0, v20
	v_max_f32_e32 v211, 0, v21
	v_pk_fma_f32 v[50:51], v[202:203], v[210:211], v[50:51]
	v_add_f32_e32 v50, v50, v51
	v_ashrrev_i32_e32 v51, 31, v50
	v_or_b32_e32 v51, 0x80000000, v51
	s_cmpk_gt_i32 s11, 312
	s_cselect_b64 vcc, -1, 0
	v_xor_b32_e32 v50, v51, v50
	v_cndmask_b32_e32 v50, v123, v50, vcc
	global_store_dword v243, v50, s[8:9] offset:2048
	s_add_u32 s8, s8, 0x1000
	s_addc_u32 s9, s9, 0
	s_cmpk_gt_i32 s81, 40
	s_cbranch_scc0 .Lix_fill_5
	s_waitcnt lgkmcnt(3)
	v_mfma_f32_32x32x16_bf16 v[212:227], v[70:73], v[38:41], 0
	s_add_i32 m0, s10, 98304
	s_nop 0
	global_load_lds_dwordx4 v102, s[6:7]
	s_waitcnt lgkmcnt(2)
	v_mfma_f32_32x32x16_bf16 v[212:227], v[74:77], v[42:45], v[212:227]
	s_add_i32 m0, s10, 99328
	s_nop 0
	global_load_lds_dwordx4 v110, s[6:7]
	s_waitcnt lgkmcnt(1)
	v_mfma_f32_32x32x16_bf16 v[212:227], v[78:81], v[46:49], v[212:227]
	s_add_i32 m0, s10, 100352
	s_nop 0
	global_load_lds_dwordx4 v112, s[6:7]
	s_waitcnt lgkmcnt(0)
	v_mfma_f32_32x32x16_bf16 v[212:227], v[82:85], v[196:199], v[212:227]
	s_add_i32 m0, s10, 101376
	s_nop 0
	global_load_lds_dwordx4 v193, s[6:7]
	s_add_u32 s6, s6, 0x8000
	s_addc_u32 s7, s7, 0
	v_mfma_f32_32x32x16_bf16 v[6:21], v[86:89], v[38:41], 0
	s_nop 7
	s_nop 2
	v_max_f32_e32 v108, 0, v212
	v_max_f32_e32 v109, 0, v213
	v_pk_mul_f32 v[0:1], v[22:23], v[108:109]
	v_max_f32_e32 v210, 0, v214
	v_max_f32_e32 v211, 0, v215
	v_pk_fma_f32 v[0:1], v[24:25], v[210:211], v[0:1]
	v_max_f32_e32 v108, 0, v216
	v_max_f32_e32 v109, 0, v217
	v_pk_fma_f32 v[0:1], v[26:27], v[108:109], v[0:1]
	v_mfma_f32_32x32x16_bf16 v[6:21], v[90:93], v[42:45], v[6:21]
	v_max_f32_e32 v210, 0, v218
	v_max_f32_e32 v211, 0, v219
	v_pk_fma_f32 v[0:1], v[28:29], v[210:211], v[0:1]
	v_max_f32_e32 v108, 0, v220
	v_max_f32_e32 v109, 0, v221
	v_pk_fma_f32 v[0:1], v[30:31], v[108:109], v[0:1]
	v_max_f32_e32 v210, 0, v222
	v_max_f32_e32 v211, 0, v223
	v_pk_fma_f32 v[0:1], v[32:33], v[210:211], v[0:1]
	v_mfma_f32_32x32x16_bf16 v[6:21], v[94:97], v[46:49], v[6:21]
	v_max_f32_e32 v108, 0, v224
	v_max_f32_e32 v109, 0, v225
	v_pk_fma_f32 v[0:1], v[34:35], v[108:109], v[0:1]
	v_max_f32_e32 v210, 0, v226
	v_max_f32_e32 v211, 0, v227
	v_pk_fma_f32 v[0:1], v[36:37], v[210:211], v[0:1]
	v_add_f32_e32 v0, v0, v1
	v_ashrrev_i32_e32 v1, 31, v0
	v_mfma_f32_32x32x16_bf16 v[6:21], v[98:101], v[196:199], v[6:21]
	s_waitcnt vmcnt(10)
	ds_read_b128 v[38:41], v5 offset:43264
	ds_read_b128 v[42:45], v52 offset:43264
	ds_read_b128 v[46:49], v55 offset:43264
	ds_read_b128 v[196:199], v56 offset:43264
	v_or_b32_e32 v1, 0x80000000, v1
	s_cmpk_gt_i32 s11, 320
	s_cselect_b64 vcc, -1, 0
	v_xor_b32_e32 v0, v1, v0
	v_cndmask_b32_e32 v174, v123, v0, vcc
	s_nop 3
	s_waitcnt lgkmcnt(3)
	v_mfma_f32_32x32x16_bf16 v[212:227], v[70:73], v[38:41], 0
	v_max_f32_e32 v108, 0, v6
	v_max_f32_e32 v109, 0, v7
	v_pk_mul_f32 v[50:51], v[244:245], v[108:109]
	v_max_f32_e32 v210, 0, v8
	v_max_f32_e32 v211, 0, v9
	v_pk_fma_f32 v[50:51], v[246:247], v[210:211], v[50:51]
	v_max_f32_e32 v108, 0, v10
	v_max_f32_e32 v109, 0, v11
	v_pk_fma_f32 v[50:51], v[248:249], v[108:109], v[50:51]
	s_waitcnt lgkmcnt(2)
	v_mfma_f32_32x32x16_bf16 v[212:227], v[74:77], v[42:45], v[212:227]
	v_max_f32_e32 v210, 0, v12
	v_max_f32_e32 v211, 0, v13
	v_pk_fma_f32 v[50:51], v[250:251], v[210:211], v[50:51]
	v_max_f32_e32 v108, 0, v14
	v_max_f32_e32 v109, 0, v15
	v_pk_fma_f32 v[50:51], v[252:253], v[108:109], v[50:51]
	v_max_f32_e32 v210, 0, v16
	v_max_f32_e32 v211, 0, v17
	v_pk_fma_f32 v[50:51], v[254:255], v[210:211], v[50:51]
	s_waitcnt lgkmcnt(1)
	v_mfma_f32_32x32x16_bf16 v[212:227], v[78:81], v[46:49], v[212:227]
	v_max_f32_e32 v108, 0, v18
	v_max_f32_e32 v109, 0, v19
	v_pk_fma_f32 v[50:51], v[200:201], v[108:109], v[50:51]
	v_max_f32_e32 v210, 0, v20
	v_max_f32_e32 v211, 0, v21
	v_pk_fma_f32 v[50:51], v[202:203], v[210:211], v[50:51]
	v_add_f32_e32 v50, v50, v51
	v_ashrrev_i32_e32 v51, 31, v50
	s_waitcnt lgkmcnt(0)
	v_mfma_f32_32x32x16_bf16 v[212:227], v[82:85], v[196:199], v[212:227]
	v_or_b32_e32 v51, 0x80000000, v51
	s_cmpk_gt_i32 s11, 320
	s_cselect_b64 vcc, -1, 0
	v_xor_b32_e32 v50, v51, v50
	v_cndmask_b32_e32 v50, v123, v50, vcc
	global_store_dword v243, v50, s[8:9]
	v_mfma_f32_32x32x16_bf16 v[6:21], v[86:89], v[38:41], 0
	s_add_i32 m0, s10, 0
	s_nop 0
	global_load_lds_dwordx4 v102, s[6:7]
	s_add_i32 m0, s10, 1024
	s_nop 0
	global_load_lds_dwordx4 v110, s[6:7]
	s_add_i32 m0, s10, 2048
	s_nop 0
	global_load_lds_dwordx4 v112, s[6:7]
	s_add_i32 m0, s10, 3072
	s_nop 0
	global_load_lds_dwordx4 v193, s[6:7]
	s_add_u32 s6, s6, 0x8000
	s_addc_u32 s7, s7, 0
	v_max_f32_e32 v108, 0, v212
	v_max_f32_e32 v109, 0, v213
	v_pk_mul_f32 v[0:1], v[22:23], v[108:109]
	v_max_f32_e32 v210, 0, v214
	v_max_f32_e32 v211, 0, v215
	v_pk_fma_f32 v[0:1], v[24:25], v[210:211], v[0:1]
	v_max_f32_e32 v108, 0, v216
	v_max_f32_e32 v109, 0, v217
	v_pk_fma_f32 v[0:1], v[26:27], v[108:109], v[0:1]
	v_mfma_f32_32x32x16_bf16 v[6:21], v[90:93], v[42:45], v[6:21]
	v_max_f32_e32 v210, 0, v218
	v_max_f32_e32 v211, 0, v219
	v_pk_fma_f32 v[0:1], v[28:29], v[210:211], v[0:1]
	v_max_f32_e32 v108, 0, v220
	v_max_f32_e32 v109, 0, v221
	v_pk_fma_f32 v[0:1], v[30:31], v[108:109], v[0:1]
	v_max_f32_e32 v210, 0, v222
	v_max_f32_e32 v211, 0, v223
	v_pk_fma_f32 v[0:1], v[32:33], v[210:211], v[0:1]
	v_mfma_f32_32x32x16_bf16 v[6:21], v[94:97], v[46:49], v[6:21]
	v_max_f32_e32 v108, 0, v224
	v_max_f32_e32 v109, 0, v225
	v_pk_fma_f32 v[0:1], v[34:35], v[108:109], v[0:1]
	v_max_f32_e32 v210, 0, v226
	v_max_f32_e32 v211, 0, v227
	v_pk_fma_f32 v[0:1], v[36:37], v[210:211], v[0:1]
	v_add_f32_e32 v0, v0, v1
	v_ashrrev_i32_e32 v1, 31, v0
	v_mfma_f32_32x32x16_bf16 v[6:21], v[98:101], v[196:199], v[6:21]
	s_waitcnt vmcnt(10)
	v_add_u32_e32 v228, 0x10000, v5
	ds_read_b128 v[38:41], v228 offset:10496
	v_add_u32_e32 v228, 0x10000, v52
	ds_read_b128 v[42:45], v228 offset:10496
	v_add_u32_e32 v228, 0x10000, v55
	ds_read_b128 v[46:49], v228 offset:10496
	v_add_u32_e32 v228, 0x10000, v56
	ds_read_b128 v[196:199], v228 offset:10496
	v_or_b32_e32 v1, 0x80000000, v1
	s_cmpk_gt_i32 s11, 328
	s_cselect_b64 vcc, -1, 0
	v_xor_b32_e32 v0, v1, v0
	v_cndmask_b32_e32 v173, v123, v0, vcc
	s_nop 3
	s_waitcnt lgkmcnt(3)
	v_mfma_f32_32x32x16_bf16 v[212:227], v[70:73], v[38:41], 0
	v_max_f32_e32 v108, 0, v6
	v_max_f32_e32 v109, 0, v7
	v_pk_mul_f32 v[50:51], v[244:245], v[108:109]
	v_max_f32_e32 v210, 0, v8
	v_max_f32_e32 v211, 0, v9
	v_pk_fma_f32 v[50:51], v[246:247], v[210:211], v[50:51]
	v_max_f32_e32 v108, 0, v10
	v_max_f32_e32 v109, 0, v11
	v_pk_fma_f32 v[50:51], v[248:249], v[108:109], v[50:51]
	s_waitcnt lgkmcnt(2)
	v_mfma_f32_32x32x16_bf16 v[212:227], v[74:77], v[42:45], v[212:227]
	v_max_f32_e32 v210, 0, v12
	v_max_f32_e32 v211, 0, v13
	v_pk_fma_f32 v[50:51], v[250:251], v[210:211], v[50:51]
	v_max_f32_e32 v108, 0, v14
	v_max_f32_e32 v109, 0, v15
	v_pk_fma_f32 v[50:51], v[252:253], v[108:109], v[50:51]
	v_max_f32_e32 v210, 0, v16
	v_max_f32_e32 v211, 0, v17
	v_pk_fma_f32 v[50:51], v[254:255], v[210:211], v[50:51]
	s_waitcnt lgkmcnt(1)
	v_mfma_f32_32x32x16_bf16 v[212:227], v[78:81], v[46:49], v[212:227]
	v_max_f32_e32 v108, 0, v18
	v_max_f32_e32 v109, 0, v19
	v_pk_fma_f32 v[50:51], v[200:201], v[108:109], v[50:51]
	v_max_f32_e32 v210, 0, v20
	v_max_f32_e32 v211, 0, v21
	v_pk_fma_f32 v[50:51], v[202:203], v[210:211], v[50:51]
	v_add_f32_e32 v50, v50, v51
	v_ashrrev_i32_e32 v51, 31, v50
	s_waitcnt lgkmcnt(0)
	v_mfma_f32_32x32x16_bf16 v[212:227], v[82:85], v[196:199], v[212:227]
	v_or_b32_e32 v51, 0x80000000, v51
	s_cmpk_gt_i32 s11, 328
	s_cselect_b64 vcc, -1, 0
	v_xor_b32_e32 v50, v51, v50
	v_cndmask_b32_e32 v50, v123, v50, vcc
	global_store_dword v243, v50, s[8:9] offset:2048
	s_add_u32 s8, s8, 0x1000
	s_addc_u32 s9, s9, 0
	v_mfma_f32_32x32x16_bf16 v[6:21], v[86:89], v[38:41], 0
	s_add_i32 m0, s10, 32768
	s_nop 0
	global_load_lds_dwordx4 v102, s[6:7]
	s_add_i32 m0, s10, 33792
	s_nop 0
	global_load_lds_dwordx4 v110, s[6:7]
	s_add_i32 m0, s10, 34816
	s_nop 0
	global_load_lds_dwordx4 v112, s[6:7]
	s_add_i32 m0, s10, 35840
	s_nop 0
	global_load_lds_dwordx4 v193, s[6:7]
	s_add_u32 s6, s6, 0x8000
	s_addc_u32 s7, s7, 0
	v_max_f32_e32 v108, 0, v212
	v_max_f32_e32 v109, 0, v213
	v_pk_mul_f32 v[0:1], v[22:23], v[108:109]
	v_max_f32_e32 v210, 0, v214
	v_max_f32_e32 v211, 0, v215
	v_pk_fma_f32 v[0:1], v[24:25], v[210:211], v[0:1]
	v_max_f32_e32 v108, 0, v216
	v_max_f32_e32 v109, 0, v217
	v_pk_fma_f32 v[0:1], v[26:27], v[108:109], v[0:1]
	v_mfma_f32_32x32x16_bf16 v[6:21], v[90:93], v[42:45], v[6:21]
	v_max_f32_e32 v210, 0, v218
	v_max_f32_e32 v211, 0, v219
	v_pk_fma_f32 v[0:1], v[28:29], v[210:211], v[0:1]
	v_max_f32_e32 v108, 0, v220
	v_max_f32_e32 v109, 0, v221
	v_pk_fma_f32 v[0:1], v[30:31], v[108:109], v[0:1]
	v_max_f32_e32 v210, 0, v222
	v_max_f32_e32 v211, 0, v223
	v_pk_fma_f32 v[0:1], v[32:33], v[210:211], v[0:1]
	v_mfma_f32_32x32x16_bf16 v[6:21], v[94:97], v[46:49], v[6:21]
	v_max_f32_e32 v108, 0, v224
	v_max_f32_e32 v109, 0, v225
	v_pk_fma_f32 v[0:1], v[34:35], v[108:109], v[0:1]
	v_max_f32_e32 v210, 0, v226
	v_max_f32_e32 v211, 0, v227
	v_pk_fma_f32 v[0:1], v[36:37], v[210:211], v[0:1]
	v_add_f32_e32 v0, v0, v1
	v_ashrrev_i32_e32 v1, 31, v0
	v_mfma_f32_32x32x16_bf16 v[6:21], v[98:101], v[196:199], v[6:21]
	s_waitcnt vmcnt(10)
	v_add_u32_e32 v228, 0x10000, v5
	ds_read_b128 v[38:41], v228 offset:43264
	v_add_u32_e32 v228, 0x10000, v52
	ds_read_b128 v[42:45], v228 offset:43264
	v_add_u32_e32 v228, 0x10000, v55
	ds_read_b128 v[46:49], v228 offset:43264
	v_add_u32_e32 v228, 0x10000, v56
	ds_read_b128 v[196:199], v228 offset:43264
	v_or_b32_e32 v1, 0x80000000, v1
	s_cmpk_gt_i32 s11, 336
	s_cselect_b64 vcc, -1, 0
	v_xor_b32_e32 v0, v1, v0
	v_cndmask_b32_e32 v176, v123, v0, vcc
	s_nop 3
	s_waitcnt lgkmcnt(3)
	v_mfma_f32_32x32x16_bf16 v[212:227], v[70:73], v[38:41], 0
	v_max_f32_e32 v108, 0, v6
	v_max_f32_e32 v109, 0, v7
	v_pk_mul_f32 v[50:51], v[244:245], v[108:109]
	v_max_f32_e32 v210, 0, v8
	v_max_f32_e32 v211, 0, v9
	v_pk_fma_f32 v[50:51], v[246:247], v[210:211], v[50:51]
	v_max_f32_e32 v108, 0, v10
	v_max_f32_e32 v109, 0, v11
	v_pk_fma_f32 v[50:51], v[248:249], v[108:109], v[50:51]
	s_waitcnt lgkmcnt(2)
	v_mfma_f32_32x32x16_bf16 v[212:227], v[74:77], v[42:45], v[212:227]
	v_max_f32_e32 v210, 0, v12
	v_max_f32_e32 v211, 0, v13
	v_pk_fma_f32 v[50:51], v[250:251], v[210:211], v[50:51]
	v_max_f32_e32 v108, 0, v14
	v_max_f32_e32 v109, 0, v15
	v_pk_fma_f32 v[50:51], v[252:253], v[108:109], v[50:51]
	v_max_f32_e32 v210, 0, v16
	v_max_f32_e32 v211, 0, v17
	v_pk_fma_f32 v[50:51], v[254:255], v[210:211], v[50:51]
	s_waitcnt lgkmcnt(1)
	v_mfma_f32_32x32x16_bf16 v[212:227], v[78:81], v[46:49], v[212:227]
	v_max_f32_e32 v108, 0, v18
	v_max_f32_e32 v109, 0, v19
	v_pk_fma_f32 v[50:51], v[200:201], v[108:109], v[50:51]
	v_max_f32_e32 v210, 0, v20
	v_max_f32_e32 v211, 0, v21
	v_pk_fma_f32 v[50:51], v[202:203], v[210:211], v[50:51]
	v_add_f32_e32 v50, v50, v51
	v_ashrrev_i32_e32 v51, 31, v50
	s_waitcnt lgkmcnt(0)
	v_mfma_f32_32x32x16_bf16 v[212:227], v[82:85], v[196:199], v[212:227]
	v_or_b32_e32 v51, 0x80000000, v51
	s_cmpk_gt_i32 s11, 336
	s_cselect_b64 vcc, -1, 0
	v_xor_b32_e32 v50, v51, v50
	v_cndmask_b32_e32 v50, v123, v50, vcc
	global_store_dword v243, v50, s[8:9]
	v_mfma_f32_32x32x16_bf16 v[6:21], v[86:89], v[38:41], 0
	s_add_i32 m0, s10, 65536
	s_nop 0
	global_load_lds_dwordx4 v102, s[6:7]
	s_add_i32 m0, s10, 66560
	s_nop 0
	global_load_lds_dwordx4 v110, s[6:7]
	s_add_i32 m0, s10, 67584
	s_nop 0
	global_load_lds_dwordx4 v112, s[6:7]
	s_add_i32 m0, s10, 68608
	s_nop 0
	global_load_lds_dwordx4 v193, s[6:7]
	s_add_u32 s6, s6, 0x8000
	s_addc_u32 s7, s7, 0
	v_max_f32_e32 v108, 0, v212
	v_max_f32_e32 v109, 0, v213
	v_pk_mul_f32 v[0:1], v[22:23], v[108:109]
	v_max_f32_e32 v210, 0, v214
	v_max_f32_e32 v211, 0, v215
	v_pk_fma_f32 v[0:1], v[24:25], v[210:211], v[0:1]
	v_max_f32_e32 v108, 0, v216
	v_max_f32_e32 v109, 0, v217
	v_pk_fma_f32 v[0:1], v[26:27], v[108:109], v[0:1]
	v_mfma_f32_32x32x16_bf16 v[6:21], v[90:93], v[42:45], v[6:21]
	v_max_f32_e32 v210, 0, v218
	v_max_f32_e32 v211, 0, v219
	v_pk_fma_f32 v[0:1], v[28:29], v[210:211], v[0:1]
	v_max_f32_e32 v108, 0, v220
	v_max_f32_e32 v109, 0, v221
	v_pk_fma_f32 v[0:1], v[30:31], v[108:109], v[0:1]
	v_max_f32_e32 v210, 0, v222
	v_max_f32_e32 v211, 0, v223
	v_pk_fma_f32 v[0:1], v[32:33], v[210:211], v[0:1]
	v_mfma_f32_32x32x16_bf16 v[6:21], v[94:97], v[46:49], v[6:21]
	v_max_f32_e32 v108, 0, v224
	v_max_f32_e32 v109, 0, v225
	v_pk_fma_f32 v[0:1], v[34:35], v[108:109], v[0:1]
	v_max_f32_e32 v210, 0, v226
	v_max_f32_e32 v211, 0, v227
	v_pk_fma_f32 v[0:1], v[36:37], v[210:211], v[0:1]
	v_add_f32_e32 v0, v0, v1
	v_ashrrev_i32_e32 v1, 31, v0
	v_mfma_f32_32x32x16_bf16 v[6:21], v[98:101], v[196:199], v[6:21]
	s_waitcnt vmcnt(10)
	ds_read_b128 v[38:41], v5 offset:10496
	ds_read_b128 v[42:45], v52 offset:10496
	ds_read_b128 v[46:49], v55 offset:10496
	ds_read_b128 v[196:199], v56 offset:10496
	v_or_b32_e32 v1, 0x80000000, v1
	s_cmpk_gt_i32 s11, 344
	s_cselect_b64 vcc, -1, 0
	v_xor_b32_e32 v0, v1, v0
	v_cndmask_b32_e32 v175, v123, v0, vcc
	s_nop 3
	s_waitcnt lgkmcnt(3)
	v_mfma_f32_32x32x16_bf16 v[212:227], v[70:73], v[38:41], 0
	v_max_f32_e32 v108, 0, v6
	v_max_f32_e32 v109, 0, v7
	v_pk_mul_f32 v[50:51], v[244:245], v[108:109]
	v_max_f32_e32 v210, 0, v8
	v_max_f32_e32 v211, 0, v9
	v_pk_fma_f32 v[50:51], v[246:247], v[210:211], v[50:51]
	v_max_f32_e32 v108, 0, v10
	v_max_f32_e32 v109, 0, v11
	v_pk_fma_f32 v[50:51], v[248:249], v[108:109], v[50:51]
	s_waitcnt lgkmcnt(2)
	v_mfma_f32_32x32x16_bf16 v[212:227], v[74:77], v[42:45], v[212:227]
	v_max_f32_e32 v210, 0, v12
	v_max_f32_e32 v211, 0, v13
	v_pk_fma_f32 v[50:51], v[250:251], v[210:211], v[50:51]
	v_max_f32_e32 v108, 0, v14
	v_max_f32_e32 v109, 0, v15
	v_pk_fma_f32 v[50:51], v[252:253], v[108:109], v[50:51]
	v_max_f32_e32 v210, 0, v16
	v_max_f32_e32 v211, 0, v17
	v_pk_fma_f32 v[50:51], v[254:255], v[210:211], v[50:51]
	s_waitcnt lgkmcnt(1)
	v_mfma_f32_32x32x16_bf16 v[212:227], v[78:81], v[46:49], v[212:227]
	v_max_f32_e32 v108, 0, v18
	v_max_f32_e32 v109, 0, v19
	v_pk_fma_f32 v[50:51], v[200:201], v[108:109], v[50:51]
	v_max_f32_e32 v210, 0, v20
	v_max_f32_e32 v211, 0, v21
	v_pk_fma_f32 v[50:51], v[202:203], v[210:211], v[50:51]
	v_add_f32_e32 v50, v50, v51
	v_ashrrev_i32_e32 v51, 31, v50
	s_waitcnt lgkmcnt(0)
	v_mfma_f32_32x32x16_bf16 v[212:227], v[82:85], v[196:199], v[212:227]
	v_or_b32_e32 v51, 0x80000000, v51
	s_cmpk_gt_i32 s11, 344
	s_cselect_b64 vcc, -1, 0
	v_xor_b32_e32 v50, v51, v50
	v_cndmask_b32_e32 v50, v123, v50, vcc
	global_store_dword v243, v50, s[8:9] offset:2048
	s_add_u32 s8, s8, 0x1000
	s_addc_u32 s9, s9, 0
	v_mfma_f32_32x32x16_bf16 v[6:21], v[86:89], v[38:41], 0
	s_add_i32 m0, s10, 98304
	s_nop 0
	global_load_lds_dwordx4 v102, s[6:7]
	s_add_i32 m0, s10, 99328
	s_nop 0
	global_load_lds_dwordx4 v110, s[6:7]
	s_add_i32 m0, s10, 100352
	s_nop 0
	global_load_lds_dwordx4 v112, s[6:7]
	s_add_i32 m0, s10, 101376
	s_nop 0
	global_load_lds_dwordx4 v193, s[6:7]
	s_add_u32 s6, s6, 0x8000
	s_addc_u32 s7, s7, 0
	v_max_f32_e32 v108, 0, v212
	v_max_f32_e32 v109, 0, v213
	v_pk_mul_f32 v[0:1], v[22:23], v[108:109]
	v_max_f32_e32 v210, 0, v214
	v_max_f32_e32 v211, 0, v215
	v_pk_fma_f32 v[0:1], v[24:25], v[210:211], v[0:1]
	v_max_f32_e32 v108, 0, v216
	v_max_f32_e32 v109, 0, v217
	v_pk_fma_f32 v[0:1], v[26:27], v[108:109], v[0:1]
	v_mfma_f32_32x32x16_bf16 v[6:21], v[90:93], v[42:45], v[6:21]
	v_max_f32_e32 v210, 0, v218
	v_max_f32_e32 v211, 0, v219
	v_pk_fma_f32 v[0:1], v[28:29], v[210:211], v[0:1]
	v_max_f32_e32 v108, 0, v220
	v_max_f32_e32 v109, 0, v221
	v_pk_fma_f32 v[0:1], v[30:31], v[108:109], v[0:1]
	v_max_f32_e32 v210, 0, v222
	v_max_f32_e32 v211, 0, v223
	v_pk_fma_f32 v[0:1], v[32:33], v[210:211], v[0:1]
	v_mfma_f32_32x32x16_bf16 v[6:21], v[94:97], v[46:49], v[6:21]
	v_max_f32_e32 v108, 0, v224
	v_max_f32_e32 v109, 0, v225
	v_pk_fma_f32 v[0:1], v[34:35], v[108:109], v[0:1]
	v_max_f32_e32 v210, 0, v226
	v_max_f32_e32 v211, 0, v227
	v_pk_fma_f32 v[0:1], v[36:37], v[210:211], v[0:1]
	v_add_f32_e32 v0, v0, v1
	v_ashrrev_i32_e32 v1, 31, v0
	v_mfma_f32_32x32x16_bf16 v[6:21], v[98:101], v[196:199], v[6:21]
	s_waitcnt vmcnt(10)
	ds_read_b128 v[38:41], v5 offset:43264
	ds_read_b128 v[42:45], v52 offset:43264
	ds_read_b128 v[46:49], v55 offset:43264
	ds_read_b128 v[196:199], v56 offset:43264
	v_or_b32_e32 v1, 0x80000000, v1
	s_cmpk_gt_i32 s11, 352
	s_cselect_b64 vcc, -1, 0
	v_xor_b32_e32 v0, v1, v0
	v_cndmask_b32_e32 v178, v123, v0, vcc
	s_nop 3
	s_waitcnt lgkmcnt(3)
	v_mfma_f32_32x32x16_bf16 v[212:227], v[70:73], v[38:41], 0
	v_max_f32_e32 v108, 0, v6
	v_max_f32_e32 v109, 0, v7
	v_pk_mul_f32 v[50:51], v[244:245], v[108:109]
	v_max_f32_e32 v210, 0, v8
	v_max_f32_e32 v211, 0, v9
	v_pk_fma_f32 v[50:51], v[246:247], v[210:211], v[50:51]
	v_max_f32_e32 v108, 0, v10
	v_max_f32_e32 v109, 0, v11
	v_pk_fma_f32 v[50:51], v[248:249], v[108:109], v[50:51]
	s_waitcnt lgkmcnt(2)
	v_mfma_f32_32x32x16_bf16 v[212:227], v[74:77], v[42:45], v[212:227]
	v_max_f32_e32 v210, 0, v12
	v_max_f32_e32 v211, 0, v13
	v_pk_fma_f32 v[50:51], v[250:251], v[210:211], v[50:51]
	v_max_f32_e32 v108, 0, v14
	v_max_f32_e32 v109, 0, v15
	v_pk_fma_f32 v[50:51], v[252:253], v[108:109], v[50:51]
	v_max_f32_e32 v210, 0, v16
	v_max_f32_e32 v211, 0, v17
	v_pk_fma_f32 v[50:51], v[254:255], v[210:211], v[50:51]
	s_waitcnt lgkmcnt(1)
	v_mfma_f32_32x32x16_bf16 v[212:227], v[78:81], v[46:49], v[212:227]
	v_max_f32_e32 v108, 0, v18
	v_max_f32_e32 v109, 0, v19
	v_pk_fma_f32 v[50:51], v[200:201], v[108:109], v[50:51]
	v_max_f32_e32 v210, 0, v20
	v_max_f32_e32 v211, 0, v21
	v_pk_fma_f32 v[50:51], v[202:203], v[210:211], v[50:51]
	v_add_f32_e32 v50, v50, v51
	v_ashrrev_i32_e32 v51, 31, v50
	s_waitcnt lgkmcnt(0)
	v_mfma_f32_32x32x16_bf16 v[212:227], v[82:85], v[196:199], v[212:227]
	v_or_b32_e32 v51, 0x80000000, v51
	s_cmpk_gt_i32 s11, 352
	s_cselect_b64 vcc, -1, 0
	v_xor_b32_e32 v50, v51, v50
	v_cndmask_b32_e32 v50, v123, v50, vcc
	global_store_dword v243, v50, s[8:9]
	v_mfma_f32_32x32x16_bf16 v[6:21], v[86:89], v[38:41], 0
	s_add_i32 m0, s10, 0
	s_nop 0
	global_load_lds_dwordx4 v102, s[6:7]
	s_add_i32 m0, s10, 1024
	s_nop 0
	global_load_lds_dwordx4 v110, s[6:7]
	s_add_i32 m0, s10, 2048
	s_nop 0
	global_load_lds_dwordx4 v112, s[6:7]
	s_add_i32 m0, s10, 3072
	s_nop 0
	global_load_lds_dwordx4 v193, s[6:7]
	s_add_u32 s6, s6, 0x8000
	s_addc_u32 s7, s7, 0
	v_max_f32_e32 v108, 0, v212
	v_max_f32_e32 v109, 0, v213
	v_pk_mul_f32 v[0:1], v[22:23], v[108:109]
	v_max_f32_e32 v210, 0, v214
	v_max_f32_e32 v211, 0, v215
	v_pk_fma_f32 v[0:1], v[24:25], v[210:211], v[0:1]
	v_max_f32_e32 v108, 0, v216
	v_max_f32_e32 v109, 0, v217
	v_pk_fma_f32 v[0:1], v[26:27], v[108:109], v[0:1]
	v_mfma_f32_32x32x16_bf16 v[6:21], v[90:93], v[42:45], v[6:21]
	v_max_f32_e32 v210, 0, v218
	v_max_f32_e32 v211, 0, v219
	v_pk_fma_f32 v[0:1], v[28:29], v[210:211], v[0:1]
	v_max_f32_e32 v108, 0, v220
	v_max_f32_e32 v109, 0, v221
	v_pk_fma_f32 v[0:1], v[30:31], v[108:109], v[0:1]
	v_max_f32_e32 v210, 0, v222
	v_max_f32_e32 v211, 0, v223
	v_pk_fma_f32 v[0:1], v[32:33], v[210:211], v[0:1]
	v_mfma_f32_32x32x16_bf16 v[6:21], v[94:97], v[46:49], v[6:21]
	v_max_f32_e32 v108, 0, v224
	v_max_f32_e32 v109, 0, v225
	v_pk_fma_f32 v[0:1], v[34:35], v[108:109], v[0:1]
	v_max_f32_e32 v210, 0, v226
	v_max_f32_e32 v211, 0, v227
	v_pk_fma_f32 v[0:1], v[36:37], v[210:211], v[0:1]
	v_add_f32_e32 v0, v0, v1
	v_ashrrev_i32_e32 v1, 31, v0
	v_mfma_f32_32x32x16_bf16 v[6:21], v[98:101], v[196:199], v[6:21]
	s_waitcnt vmcnt(10)
	v_add_u32_e32 v228, 0x10000, v5
	ds_read_b128 v[38:41], v228 offset:10496
	v_add_u32_e32 v228, 0x10000, v52
	ds_read_b128 v[42:45], v228 offset:10496
	v_add_u32_e32 v228, 0x10000, v55
	ds_read_b128 v[46:49], v228 offset:10496
	v_add_u32_e32 v228, 0x10000, v56
	ds_read_b128 v[196:199], v228 offset:10496
	v_or_b32_e32 v1, 0x80000000, v1
	s_cmpk_gt_i32 s11, 360
	s_cselect_b64 vcc, -1, 0
	v_xor_b32_e32 v0, v1, v0
	v_cndmask_b32_e32 v177, v123, v0, vcc
	s_nop 3
	s_waitcnt lgkmcnt(3)
	v_mfma_f32_32x32x16_bf16 v[212:227], v[70:73], v[38:41], 0
	v_max_f32_e32 v108, 0, v6
	v_max_f32_e32 v109, 0, v7
	v_pk_mul_f32 v[50:51], v[244:245], v[108:109]
	v_max_f32_e32 v210, 0, v8
	v_max_f32_e32 v211, 0, v9
	v_pk_fma_f32 v[50:51], v[246:247], v[210:211], v[50:51]
	v_max_f32_e32 v108, 0, v10
	v_max_f32_e32 v109, 0, v11
	v_pk_fma_f32 v[50:51], v[248:249], v[108:109], v[50:51]
	s_waitcnt lgkmcnt(2)
	v_mfma_f32_32x32x16_bf16 v[212:227], v[74:77], v[42:45], v[212:227]
	v_max_f32_e32 v210, 0, v12
	v_max_f32_e32 v211, 0, v13
	v_pk_fma_f32 v[50:51], v[250:251], v[210:211], v[50:51]
	v_max_f32_e32 v108, 0, v14
	v_max_f32_e32 v109, 0, v15
	v_pk_fma_f32 v[50:51], v[252:253], v[108:109], v[50:51]
	v_max_f32_e32 v210, 0, v16
	v_max_f32_e32 v211, 0, v17
	v_pk_fma_f32 v[50:51], v[254:255], v[210:211], v[50:51]
	s_waitcnt lgkmcnt(1)
	v_mfma_f32_32x32x16_bf16 v[212:227], v[78:81], v[46:49], v[212:227]
	v_max_f32_e32 v108, 0, v18
	v_max_f32_e32 v109, 0, v19
	v_pk_fma_f32 v[50:51], v[200:201], v[108:109], v[50:51]
	v_max_f32_e32 v210, 0, v20
	v_max_f32_e32 v211, 0, v21
	v_pk_fma_f32 v[50:51], v[202:203], v[210:211], v[50:51]
	v_add_f32_e32 v50, v50, v51
	v_ashrrev_i32_e32 v51, 31, v50
	s_waitcnt lgkmcnt(0)
	v_mfma_f32_32x32x16_bf16 v[212:227], v[82:85], v[196:199], v[212:227]
	v_or_b32_e32 v51, 0x80000000, v51
	s_cmpk_gt_i32 s11, 360
	s_cselect_b64 vcc, -1, 0
	v_xor_b32_e32 v50, v51, v50
	v_cndmask_b32_e32 v50, v123, v50, vcc
	global_store_dword v243, v50, s[8:9] offset:2048
	s_add_u32 s8, s8, 0x1000
	s_addc_u32 s9, s9, 0
	v_mfma_f32_32x32x16_bf16 v[6:21], v[86:89], v[38:41], 0
	s_add_i32 m0, s10, 32768
	s_nop 0
	global_load_lds_dwordx4 v102, s[6:7]
	s_add_i32 m0, s10, 33792
	s_nop 0
	global_load_lds_dwordx4 v110, s[6:7]
	s_add_i32 m0, s10, 34816
	s_nop 0
	global_load_lds_dwordx4 v112, s[6:7]
	s_add_i32 m0, s10, 35840
	s_nop 0
	global_load_lds_dwordx4 v193, s[6:7]
	s_add_u32 s6, s6, 0x8000
	s_addc_u32 s7, s7, 0
	v_max_f32_e32 v108, 0, v212
	v_max_f32_e32 v109, 0, v213
	v_pk_mul_f32 v[0:1], v[22:23], v[108:109]
	v_max_f32_e32 v210, 0, v214
	v_max_f32_e32 v211, 0, v215
	v_pk_fma_f32 v[0:1], v[24:25], v[210:211], v[0:1]
	v_max_f32_e32 v108, 0, v216
	v_max_f32_e32 v109, 0, v217
	v_pk_fma_f32 v[0:1], v[26:27], v[108:109], v[0:1]
	v_mfma_f32_32x32x16_bf16 v[6:21], v[90:93], v[42:45], v[6:21]
	v_max_f32_e32 v210, 0, v218
	v_max_f32_e32 v211, 0, v219
	v_pk_fma_f32 v[0:1], v[28:29], v[210:211], v[0:1]
	v_max_f32_e32 v108, 0, v220
	v_max_f32_e32 v109, 0, v221
	v_pk_fma_f32 v[0:1], v[30:31], v[108:109], v[0:1]
	v_max_f32_e32 v210, 0, v222
	v_max_f32_e32 v211, 0, v223
	v_pk_fma_f32 v[0:1], v[32:33], v[210:211], v[0:1]
	v_mfma_f32_32x32x16_bf16 v[6:21], v[94:97], v[46:49], v[6:21]
	v_max_f32_e32 v108, 0, v224
	v_max_f32_e32 v109, 0, v225
	v_pk_fma_f32 v[0:1], v[34:35], v[108:109], v[0:1]
	v_max_f32_e32 v210, 0, v226
	v_max_f32_e32 v211, 0, v227
	v_pk_fma_f32 v[0:1], v[36:37], v[210:211], v[0:1]
	v_add_f32_e32 v0, v0, v1
	v_ashrrev_i32_e32 v1, 31, v0
	v_mfma_f32_32x32x16_bf16 v[6:21], v[98:101], v[196:199], v[6:21]
	s_waitcnt vmcnt(10)
	v_add_u32_e32 v228, 0x10000, v5
	ds_read_b128 v[38:41], v228 offset:43264
	v_add_u32_e32 v228, 0x10000, v52
	ds_read_b128 v[42:45], v228 offset:43264
	v_add_u32_e32 v228, 0x10000, v55
	ds_read_b128 v[46:49], v228 offset:43264
	v_add_u32_e32 v228, 0x10000, v56
	ds_read_b128 v[196:199], v228 offset:43264
	v_or_b32_e32 v1, 0x80000000, v1
	s_cmpk_gt_i32 s11, 368
	s_cselect_b64 vcc, -1, 0
	v_xor_b32_e32 v0, v1, v0
	v_cndmask_b32_e32 v179, v123, v0, vcc
	s_nop 3
	s_waitcnt lgkmcnt(3)
	v_mfma_f32_32x32x16_bf16 v[212:227], v[70:73], v[38:41], 0
	v_max_f32_e32 v108, 0, v6
	v_max_f32_e32 v109, 0, v7
	v_pk_mul_f32 v[50:51], v[244:245], v[108:109]
	v_max_f32_e32 v210, 0, v8
	v_max_f32_e32 v211, 0, v9
	v_pk_fma_f32 v[50:51], v[246:247], v[210:211], v[50:51]
	v_max_f32_e32 v108, 0, v10
	v_max_f32_e32 v109, 0, v11
	v_pk_fma_f32 v[50:51], v[248:249], v[108:109], v[50:51]
	s_waitcnt lgkmcnt(2)
	v_mfma_f32_32x32x16_bf16 v[212:227], v[74:77], v[42:45], v[212:227]
	v_max_f32_e32 v210, 0, v12
	v_max_f32_e32 v211, 0, v13
	v_pk_fma_f32 v[50:51], v[250:251], v[210:211], v[50:51]
	v_max_f32_e32 v108, 0, v14
	v_max_f32_e32 v109, 0, v15
	v_pk_fma_f32 v[50:51], v[252:253], v[108:109], v[50:51]
	v_max_f32_e32 v210, 0, v16
	v_max_f32_e32 v211, 0, v17
	v_pk_fma_f32 v[50:51], v[254:255], v[210:211], v[50:51]
	s_waitcnt lgkmcnt(1)
	v_mfma_f32_32x32x16_bf16 v[212:227], v[78:81], v[46:49], v[212:227]
	v_max_f32_e32 v108, 0, v18
	v_max_f32_e32 v109, 0, v19
	v_pk_fma_f32 v[50:51], v[200:201], v[108:109], v[50:51]
	v_max_f32_e32 v210, 0, v20
	v_max_f32_e32 v211, 0, v21
	v_pk_fma_f32 v[50:51], v[202:203], v[210:211], v[50:51]
	v_add_f32_e32 v50, v50, v51
	v_ashrrev_i32_e32 v51, 31, v50
	s_waitcnt lgkmcnt(0)
	v_mfma_f32_32x32x16_bf16 v[212:227], v[82:85], v[196:199], v[212:227]
	v_or_b32_e32 v51, 0x80000000, v51
	s_cmpk_gt_i32 s11, 368
	s_cselect_b64 vcc, -1, 0
	v_xor_b32_e32 v50, v51, v50
	v_cndmask_b32_e32 v50, v123, v50, vcc
	global_store_dword v243, v50, s[8:9]
	v_mfma_f32_32x32x16_bf16 v[6:21], v[86:89], v[38:41], 0
	s_add_i32 m0, s10, 65536
	s_nop 0
	global_load_lds_dwordx4 v102, s[6:7]
	s_add_i32 m0, s10, 66560
	s_nop 0
	global_load_lds_dwordx4 v110, s[6:7]
	s_add_i32 m0, s10, 67584
	s_nop 0
	global_load_lds_dwordx4 v112, s[6:7]
	s_add_i32 m0, s10, 68608
	s_nop 0
	global_load_lds_dwordx4 v193, s[6:7]
	s_add_u32 s6, s6, 0x8000
	s_addc_u32 s7, s7, 0
	v_max_f32_e32 v108, 0, v212
	v_max_f32_e32 v109, 0, v213
	v_pk_mul_f32 v[0:1], v[22:23], v[108:109]
	v_max_f32_e32 v210, 0, v214
	v_max_f32_e32 v211, 0, v215
	v_pk_fma_f32 v[0:1], v[24:25], v[210:211], v[0:1]
	v_max_f32_e32 v108, 0, v216
	v_max_f32_e32 v109, 0, v217
	v_pk_fma_f32 v[0:1], v[26:27], v[108:109], v[0:1]
	v_mfma_f32_32x32x16_bf16 v[6:21], v[90:93], v[42:45], v[6:21]
	v_max_f32_e32 v210, 0, v218
	v_max_f32_e32 v211, 0, v219
	v_pk_fma_f32 v[0:1], v[28:29], v[210:211], v[0:1]
	v_max_f32_e32 v108, 0, v220
	v_max_f32_e32 v109, 0, v221
	v_pk_fma_f32 v[0:1], v[30:31], v[108:109], v[0:1]
	v_max_f32_e32 v210, 0, v222
	v_max_f32_e32 v211, 0, v223
	v_pk_fma_f32 v[0:1], v[32:33], v[210:211], v[0:1]
	v_mfma_f32_32x32x16_bf16 v[6:21], v[94:97], v[46:49], v[6:21]
	v_max_f32_e32 v108, 0, v224
	v_max_f32_e32 v109, 0, v225
	v_pk_fma_f32 v[0:1], v[34:35], v[108:109], v[0:1]
	v_max_f32_e32 v210, 0, v226
	v_max_f32_e32 v211, 0, v227
	v_pk_fma_f32 v[0:1], v[36:37], v[210:211], v[0:1]
	v_add_f32_e32 v0, v0, v1
	v_ashrrev_i32_e32 v1, 31, v0
	v_mfma_f32_32x32x16_bf16 v[6:21], v[98:101], v[196:199], v[6:21]
	s_waitcnt vmcnt(10)
	ds_read_b128 v[38:41], v5 offset:10496
	ds_read_b128 v[42:45], v52 offset:10496
	ds_read_b128 v[46:49], v55 offset:10496
	ds_read_b128 v[196:199], v56 offset:10496
	v_or_b32_e32 v1, 0x80000000, v1
	s_cmpk_gt_i32 s11, 376
	s_cselect_b64 vcc, -1, 0
	v_xor_b32_e32 v0, v1, v0
	v_cndmask_b32_e32 v168, v123, v0, vcc
	s_nop 3
	v_max_f32_e32 v108, 0, v6
	v_max_f32_e32 v109, 0, v7
	v_pk_mul_f32 v[50:51], v[244:245], v[108:109]
	v_max_f32_e32 v210, 0, v8
	v_max_f32_e32 v211, 0, v9
	v_pk_fma_f32 v[50:51], v[246:247], v[210:211], v[50:51]
	v_max_f32_e32 v108, 0, v10
	v_max_f32_e32 v109, 0, v11
	v_pk_fma_f32 v[50:51], v[248:249], v[108:109], v[50:51]
	v_max_f32_e32 v210, 0, v12
	v_max_f32_e32 v211, 0, v13
	v_pk_fma_f32 v[50:51], v[250:251], v[210:211], v[50:51]
	v_max_f32_e32 v108, 0, v14
	v_max_f32_e32 v109, 0, v15
	v_pk_fma_f32 v[50:51], v[252:253], v[108:109], v[50:51]
	v_max_f32_e32 v210, 0, v16
	v_max_f32_e32 v211, 0, v17
	v_pk_fma_f32 v[50:51], v[254:255], v[210:211], v[50:51]
	v_max_f32_e32 v108, 0, v18
	v_max_f32_e32 v109, 0, v19
	v_pk_fma_f32 v[50:51], v[200:201], v[108:109], v[50:51]
	v_max_f32_e32 v210, 0, v20
	v_max_f32_e32 v211, 0, v21
	v_pk_fma_f32 v[50:51], v[202:203], v[210:211], v[50:51]
	v_add_f32_e32 v50, v50, v51
	v_ashrrev_i32_e32 v51, 31, v50
	v_or_b32_e32 v51, 0x80000000, v51
	s_cmpk_gt_i32 s11, 376
	s_cselect_b64 vcc, -1, 0
	v_xor_b32_e32 v50, v51, v50
	v_cndmask_b32_e32 v50, v123, v50, vcc
	global_store_dword v243, v50, s[8:9] offset:2048
	s_add_u32 s8, s8, 0x1000
	s_addc_u32 s9, s9, 0
	s_cmpk_gt_i32 s81, 48
	s_cbranch_scc0 .Lix_fill_6
	s_waitcnt lgkmcnt(3)
	v_mfma_f32_32x32x16_bf16 v[212:227], v[70:73], v[38:41], 0
	s_add_i32 m0, s10, 98304
	s_nop 0
	global_load_lds_dwordx4 v102, s[6:7]
	s_waitcnt lgkmcnt(2)
	v_mfma_f32_32x32x16_bf16 v[212:227], v[74:77], v[42:45], v[212:227]
	s_add_i32 m0, s10, 99328
	s_nop 0
	global_load_lds_dwordx4 v110, s[6:7]
	s_waitcnt lgkmcnt(1)
	v_mfma_f32_32x32x16_bf16 v[212:227], v[78:81], v[46:49], v[212:227]
	s_add_i32 m0, s10, 100352
	s_nop 0
	global_load_lds_dwordx4 v112, s[6:7]
	s_waitcnt lgkmcnt(0)
	v_mfma_f32_32x32x16_bf16 v[212:227], v[82:85], v[196:199], v[212:227]
	s_add_i32 m0, s10, 101376
	s_nop 0
	global_load_lds_dwordx4 v193, s[6:7]
	s_add_u32 s6, s6, 0x8000
	s_addc_u32 s7, s7, 0
	v_mfma_f32_32x32x16_bf16 v[6:21], v[86:89], v[38:41], 0
	s_nop 7
	s_nop 2
	v_max_f32_e32 v108, 0, v212
	v_max_f32_e32 v109, 0, v213
	v_pk_mul_f32 v[0:1], v[22:23], v[108:109]
	v_max_f32_e32 v210, 0, v214
	v_max_f32_e32 v211, 0, v215
	v_pk_fma_f32 v[0:1], v[24:25], v[210:211], v[0:1]
	v_max_f32_e32 v108, 0, v216
	v_max_f32_e32 v109, 0, v217
	v_pk_fma_f32 v[0:1], v[26:27], v[108:109], v[0:1]
	v_mfma_f32_32x32x16_bf16 v[6:21], v[90:93], v[42:45], v[6:21]
	v_max_f32_e32 v210, 0, v218
	v_max_f32_e32 v211, 0, v219
	v_pk_fma_f32 v[0:1], v[28:29], v[210:211], v[0:1]
	v_max_f32_e32 v108, 0, v220
	v_max_f32_e32 v109, 0, v221
	v_pk_fma_f32 v[0:1], v[30:31], v[108:109], v[0:1]
	v_max_f32_e32 v210, 0, v222
	v_max_f32_e32 v211, 0, v223
	v_pk_fma_f32 v[0:1], v[32:33], v[210:211], v[0:1]
	v_mfma_f32_32x32x16_bf16 v[6:21], v[94:97], v[46:49], v[6:21]
	v_max_f32_e32 v108, 0, v224
	v_max_f32_e32 v109, 0, v225
	v_pk_fma_f32 v[0:1], v[34:35], v[108:109], v[0:1]
	v_max_f32_e32 v210, 0, v226
	v_max_f32_e32 v211, 0, v227
	v_pk_fma_f32 v[0:1], v[36:37], v[210:211], v[0:1]
	v_add_f32_e32 v0, v0, v1
	v_ashrrev_i32_e32 v1, 31, v0
	v_mfma_f32_32x32x16_bf16 v[6:21], v[98:101], v[196:199], v[6:21]
	s_waitcnt vmcnt(10)
	ds_read_b128 v[38:41], v5 offset:43264
	ds_read_b128 v[42:45], v52 offset:43264
	ds_read_b128 v[46:49], v55 offset:43264
	ds_read_b128 v[196:199], v56 offset:43264
	v_or_b32_e32 v1, 0x80000000, v1
	s_cmpk_gt_i32 s11, 384
	s_cselect_b64 vcc, -1, 0
	v_xor_b32_e32 v0, v1, v0
	v_cndmask_b32_e32 v182, v123, v0, vcc
	s_nop 3
	s_waitcnt lgkmcnt(3)
	v_mfma_f32_32x32x16_bf16 v[212:227], v[70:73], v[38:41], 0
	v_max_f32_e32 v108, 0, v6
	v_max_f32_e32 v109, 0, v7
	v_pk_mul_f32 v[50:51], v[244:245], v[108:109]
	v_max_f32_e32 v210, 0, v8
	v_max_f32_e32 v211, 0, v9
	v_pk_fma_f32 v[50:51], v[246:247], v[210:211], v[50:51]
	v_max_f32_e32 v108, 0, v10
	v_max_f32_e32 v109, 0, v11
	v_pk_fma_f32 v[50:51], v[248:249], v[108:109], v[50:51]
	s_waitcnt lgkmcnt(2)
	v_mfma_f32_32x32x16_bf16 v[212:227], v[74:77], v[42:45], v[212:227]
	v_max_f32_e32 v210, 0, v12
	v_max_f32_e32 v211, 0, v13
	v_pk_fma_f32 v[50:51], v[250:251], v[210:211], v[50:51]
	v_max_f32_e32 v108, 0, v14
	v_max_f32_e32 v109, 0, v15
	v_pk_fma_f32 v[50:51], v[252:253], v[108:109], v[50:51]
	v_max_f32_e32 v210, 0, v16
	v_max_f32_e32 v211, 0, v17
	v_pk_fma_f32 v[50:51], v[254:255], v[210:211], v[50:51]
	s_waitcnt lgkmcnt(1)
	v_mfma_f32_32x32x16_bf16 v[212:227], v[78:81], v[46:49], v[212:227]
	v_max_f32_e32 v108, 0, v18
	v_max_f32_e32 v109, 0, v19
	v_pk_fma_f32 v[50:51], v[200:201], v[108:109], v[50:51]
	v_max_f32_e32 v210, 0, v20
	v_max_f32_e32 v211, 0, v21
	v_pk_fma_f32 v[50:51], v[202:203], v[210:211], v[50:51]
	v_add_f32_e32 v50, v50, v51
	v_ashrrev_i32_e32 v51, 31, v50
	s_waitcnt lgkmcnt(0)
	v_mfma_f32_32x32x16_bf16 v[212:227], v[82:85], v[196:199], v[212:227]
	v_or_b32_e32 v51, 0x80000000, v51
	s_cmpk_gt_i32 s11, 384
	s_cselect_b64 vcc, -1, 0
	v_xor_b32_e32 v50, v51, v50
	v_cndmask_b32_e32 v50, v123, v50, vcc
	global_store_dword v243, v50, s[8:9]
	v_mfma_f32_32x32x16_bf16 v[6:21], v[86:89], v[38:41], 0
	s_add_i32 m0, s10, 0
	s_nop 0
	global_load_lds_dwordx4 v102, s[6:7]
	s_add_i32 m0, s10, 1024
	s_nop 0
	global_load_lds_dwordx4 v110, s[6:7]
	s_add_i32 m0, s10, 2048
	s_nop 0
	global_load_lds_dwordx4 v112, s[6:7]
	s_add_i32 m0, s10, 3072
	s_nop 0
	global_load_lds_dwordx4 v193, s[6:7]
	s_add_u32 s6, s6, 0x8000
	s_addc_u32 s7, s7, 0
	v_max_f32_e32 v108, 0, v212
	v_max_f32_e32 v109, 0, v213
	v_pk_mul_f32 v[0:1], v[22:23], v[108:109]
	v_max_f32_e32 v210, 0, v214
	v_max_f32_e32 v211, 0, v215
	v_pk_fma_f32 v[0:1], v[24:25], v[210:211], v[0:1]
	v_max_f32_e32 v108, 0, v216
	v_max_f32_e32 v109, 0, v217
	v_pk_fma_f32 v[0:1], v[26:27], v[108:109], v[0:1]
	v_mfma_f32_32x32x16_bf16 v[6:21], v[90:93], v[42:45], v[6:21]
	v_max_f32_e32 v210, 0, v218
	v_max_f32_e32 v211, 0, v219
	v_pk_fma_f32 v[0:1], v[28:29], v[210:211], v[0:1]
	v_max_f32_e32 v108, 0, v220
	v_max_f32_e32 v109, 0, v221
	v_pk_fma_f32 v[0:1], v[30:31], v[108:109], v[0:1]
	v_max_f32_e32 v210, 0, v222
	v_max_f32_e32 v211, 0, v223
	v_pk_fma_f32 v[0:1], v[32:33], v[210:211], v[0:1]
	v_mfma_f32_32x32x16_bf16 v[6:21], v[94:97], v[46:49], v[6:21]
	v_max_f32_e32 v108, 0, v224
	v_max_f32_e32 v109, 0, v225
	v_pk_fma_f32 v[0:1], v[34:35], v[108:109], v[0:1]
	v_max_f32_e32 v210, 0, v226
	v_max_f32_e32 v211, 0, v227
	v_pk_fma_f32 v[0:1], v[36:37], v[210:211], v[0:1]
	v_add_f32_e32 v0, v0, v1
	v_ashrrev_i32_e32 v1, 31, v0
	v_mfma_f32_32x32x16_bf16 v[6:21], v[98:101], v[196:199], v[6:21]
	s_waitcnt vmcnt(10)
	v_add_u32_e32 v228, 0x10000, v5
	ds_read_b128 v[38:41], v228 offset:10496
	v_add_u32_e32 v228, 0x10000, v52
	ds_read_b128 v[42:45], v228 offset:10496
	v_add_u32_e32 v228, 0x10000, v55
	ds_read_b128 v[46:49], v228 offset:10496
	v_add_u32_e32 v228, 0x10000, v56
	ds_read_b128 v[196:199], v228 offset:10496
	v_or_b32_e32 v1, 0x80000000, v1
	s_cmpk_gt_i32 s11, 392
	s_cselect_b64 vcc, -1, 0
	v_xor_b32_e32 v0, v1, v0
	v_cndmask_b32_e32 v181, v123, v0, vcc
	s_nop 3
	s_waitcnt lgkmcnt(3)
	v_mfma_f32_32x32x16_bf16 v[212:227], v[70:73], v[38:41], 0
	v_max_f32_e32 v108, 0, v6
	v_max_f32_e32 v109, 0, v7
	v_pk_mul_f32 v[50:51], v[244:245], v[108:109]
	v_max_f32_e32 v210, 0, v8
	v_max_f32_e32 v211, 0, v9
	v_pk_fma_f32 v[50:51], v[246:247], v[210:211], v[50:51]
	v_max_f32_e32 v108, 0, v10
	v_max_f32_e32 v109, 0, v11
	v_pk_fma_f32 v[50:51], v[248:249], v[108:109], v[50:51]
	s_waitcnt lgkmcnt(2)
	v_mfma_f32_32x32x16_bf16 v[212:227], v[74:77], v[42:45], v[212:227]
	v_max_f32_e32 v210, 0, v12
	v_max_f32_e32 v211, 0, v13
	v_pk_fma_f32 v[50:51], v[250:251], v[210:211], v[50:51]
	v_max_f32_e32 v108, 0, v14
	v_max_f32_e32 v109, 0, v15
	v_pk_fma_f32 v[50:51], v[252:253], v[108:109], v[50:51]
	v_max_f32_e32 v210, 0, v16
	v_max_f32_e32 v211, 0, v17
	v_pk_fma_f32 v[50:51], v[254:255], v[210:211], v[50:51]
	s_waitcnt lgkmcnt(1)
	v_mfma_f32_32x32x16_bf16 v[212:227], v[78:81], v[46:49], v[212:227]
	v_max_f32_e32 v108, 0, v18
	v_max_f32_e32 v109, 0, v19
	v_pk_fma_f32 v[50:51], v[200:201], v[108:109], v[50:51]
	v_max_f32_e32 v210, 0, v20
	v_max_f32_e32 v211, 0, v21
	v_pk_fma_f32 v[50:51], v[202:203], v[210:211], v[50:51]
	v_add_f32_e32 v50, v50, v51
	v_ashrrev_i32_e32 v51, 31, v50
	s_waitcnt lgkmcnt(0)
	v_mfma_f32_32x32x16_bf16 v[212:227], v[82:85], v[196:199], v[212:227]
	v_or_b32_e32 v51, 0x80000000, v51
	s_cmpk_gt_i32 s11, 392
	s_cselect_b64 vcc, -1, 0
	v_xor_b32_e32 v50, v51, v50
	v_cndmask_b32_e32 v50, v123, v50, vcc
	global_store_dword v243, v50, s[8:9] offset:2048
	s_add_u32 s8, s8, 0x1000
	s_addc_u32 s9, s9, 0
	v_mfma_f32_32x32x16_bf16 v[6:21], v[86:89], v[38:41], 0
	s_add_i32 m0, s10, 32768
	s_nop 0
	global_load_lds_dwordx4 v102, s[6:7]
	s_add_i32 m0, s10, 33792
	s_nop 0
	global_load_lds_dwordx4 v110, s[6:7]
	s_add_i32 m0, s10, 34816
	s_nop 0
	global_load_lds_dwordx4 v112, s[6:7]
	s_add_i32 m0, s10, 35840
	s_nop 0
	global_load_lds_dwordx4 v193, s[6:7]
	s_add_u32 s6, s6, 0x8000
	s_addc_u32 s7, s7, 0
	v_max_f32_e32 v108, 0, v212
	v_max_f32_e32 v109, 0, v213
	v_pk_mul_f32 v[0:1], v[22:23], v[108:109]
	v_max_f32_e32 v210, 0, v214
	v_max_f32_e32 v211, 0, v215
	v_pk_fma_f32 v[0:1], v[24:25], v[210:211], v[0:1]
	v_max_f32_e32 v108, 0, v216
	v_max_f32_e32 v109, 0, v217
	v_pk_fma_f32 v[0:1], v[26:27], v[108:109], v[0:1]
	v_mfma_f32_32x32x16_bf16 v[6:21], v[90:93], v[42:45], v[6:21]
	v_max_f32_e32 v210, 0, v218
	v_max_f32_e32 v211, 0, v219
	v_pk_fma_f32 v[0:1], v[28:29], v[210:211], v[0:1]
	v_max_f32_e32 v108, 0, v220
	v_max_f32_e32 v109, 0, v221
	v_pk_fma_f32 v[0:1], v[30:31], v[108:109], v[0:1]
	v_max_f32_e32 v210, 0, v222
	v_max_f32_e32 v211, 0, v223
	v_pk_fma_f32 v[0:1], v[32:33], v[210:211], v[0:1]
	v_mfma_f32_32x32x16_bf16 v[6:21], v[94:97], v[46:49], v[6:21]
	v_max_f32_e32 v108, 0, v224
	v_max_f32_e32 v109, 0, v225
	v_pk_fma_f32 v[0:1], v[34:35], v[108:109], v[0:1]
	v_max_f32_e32 v210, 0, v226
	v_max_f32_e32 v211, 0, v227
	v_pk_fma_f32 v[0:1], v[36:37], v[210:211], v[0:1]
	v_add_f32_e32 v0, v0, v1
	v_ashrrev_i32_e32 v1, 31, v0
	v_mfma_f32_32x32x16_bf16 v[6:21], v[98:101], v[196:199], v[6:21]
	s_waitcnt vmcnt(10)
	v_add_u32_e32 v228, 0x10000, v5
	ds_read_b128 v[38:41], v228 offset:43264
	v_add_u32_e32 v228, 0x10000, v52
	ds_read_b128 v[42:45], v228 offset:43264
	v_add_u32_e32 v228, 0x10000, v55
	ds_read_b128 v[46:49], v228 offset:43264
	v_add_u32_e32 v228, 0x10000, v56
	ds_read_b128 v[196:199], v228 offset:43264
	v_or_b32_e32 v1, 0x80000000, v1
	s_cmpk_gt_i32 s11, 400
	s_cselect_b64 vcc, -1, 0
	v_xor_b32_e32 v0, v1, v0
	v_cndmask_b32_e32 v184, v123, v0, vcc
	s_nop 3
	s_waitcnt lgkmcnt(3)
	v_mfma_f32_32x32x16_bf16 v[212:227], v[70:73], v[38:41], 0
	v_max_f32_e32 v108, 0, v6
	v_max_f32_e32 v109, 0, v7
	v_pk_mul_f32 v[50:51], v[244:245], v[108:109]
	v_max_f32_e32 v210, 0, v8
	v_max_f32_e32 v211, 0, v9
	v_pk_fma_f32 v[50:51], v[246:247], v[210:211], v[50:51]
	v_max_f32_e32 v108, 0, v10
	v_max_f32_e32 v109, 0, v11
	v_pk_fma_f32 v[50:51], v[248:249], v[108:109], v[50:51]
	s_waitcnt lgkmcnt(2)
	v_mfma_f32_32x32x16_bf16 v[212:227], v[74:77], v[42:45], v[212:227]
	v_max_f32_e32 v210, 0, v12
	v_max_f32_e32 v211, 0, v13
	v_pk_fma_f32 v[50:51], v[250:251], v[210:211], v[50:51]
	v_max_f32_e32 v108, 0, v14
	v_max_f32_e32 v109, 0, v15
	v_pk_fma_f32 v[50:51], v[252:253], v[108:109], v[50:51]
	v_max_f32_e32 v210, 0, v16
	v_max_f32_e32 v211, 0, v17
	v_pk_fma_f32 v[50:51], v[254:255], v[210:211], v[50:51]
	s_waitcnt lgkmcnt(1)
	v_mfma_f32_32x32x16_bf16 v[212:227], v[78:81], v[46:49], v[212:227]
	v_max_f32_e32 v108, 0, v18
	v_max_f32_e32 v109, 0, v19
	v_pk_fma_f32 v[50:51], v[200:201], v[108:109], v[50:51]
	v_max_f32_e32 v210, 0, v20
	v_max_f32_e32 v211, 0, v21
	v_pk_fma_f32 v[50:51], v[202:203], v[210:211], v[50:51]
	v_add_f32_e32 v50, v50, v51
	v_ashrrev_i32_e32 v51, 31, v50
	s_waitcnt lgkmcnt(0)
	v_mfma_f32_32x32x16_bf16 v[212:227], v[82:85], v[196:199], v[212:227]
	v_or_b32_e32 v51, 0x80000000, v51
	s_cmpk_gt_i32 s11, 400
	s_cselect_b64 vcc, -1, 0
	v_xor_b32_e32 v50, v51, v50
	v_cndmask_b32_e32 v50, v123, v50, vcc
	global_store_dword v243, v50, s[8:9]
	v_mfma_f32_32x32x16_bf16 v[6:21], v[86:89], v[38:41], 0
	s_add_i32 m0, s10, 65536
	s_nop 0
	global_load_lds_dwordx4 v102, s[6:7]
	s_add_i32 m0, s10, 66560
	s_nop 0
	global_load_lds_dwordx4 v110, s[6:7]
	s_add_i32 m0, s10, 67584
	s_nop 0
	global_load_lds_dwordx4 v112, s[6:7]
	s_add_i32 m0, s10, 68608
	s_nop 0
	global_load_lds_dwordx4 v193, s[6:7]
	s_add_u32 s6, s6, 0x8000
	s_addc_u32 s7, s7, 0
	v_max_f32_e32 v108, 0, v212
	v_max_f32_e32 v109, 0, v213
	v_pk_mul_f32 v[0:1], v[22:23], v[108:109]
	v_max_f32_e32 v210, 0, v214
	v_max_f32_e32 v211, 0, v215
	v_pk_fma_f32 v[0:1], v[24:25], v[210:211], v[0:1]
	v_max_f32_e32 v108, 0, v216
	v_max_f32_e32 v109, 0, v217
	v_pk_fma_f32 v[0:1], v[26:27], v[108:109], v[0:1]
	v_mfma_f32_32x32x16_bf16 v[6:21], v[90:93], v[42:45], v[6:21]
	v_max_f32_e32 v210, 0, v218
	v_max_f32_e32 v211, 0, v219
	v_pk_fma_f32 v[0:1], v[28:29], v[210:211], v[0:1]
	v_max_f32_e32 v108, 0, v220
	v_max_f32_e32 v109, 0, v221
	v_pk_fma_f32 v[0:1], v[30:31], v[108:109], v[0:1]
	v_max_f32_e32 v210, 0, v222
	v_max_f32_e32 v211, 0, v223
	v_pk_fma_f32 v[0:1], v[32:33], v[210:211], v[0:1]
	v_mfma_f32_32x32x16_bf16 v[6:21], v[94:97], v[46:49], v[6:21]
	v_max_f32_e32 v108, 0, v224
	v_max_f32_e32 v109, 0, v225
	v_pk_fma_f32 v[0:1], v[34:35], v[108:109], v[0:1]
	v_max_f32_e32 v210, 0, v226
	v_max_f32_e32 v211, 0, v227
	v_pk_fma_f32 v[0:1], v[36:37], v[210:211], v[0:1]
	v_add_f32_e32 v0, v0, v1
	v_ashrrev_i32_e32 v1, 31, v0
	v_mfma_f32_32x32x16_bf16 v[6:21], v[98:101], v[196:199], v[6:21]
	s_waitcnt vmcnt(10)
	ds_read_b128 v[38:41], v5 offset:10496
	ds_read_b128 v[42:45], v52 offset:10496
	ds_read_b128 v[46:49], v55 offset:10496
	ds_read_b128 v[196:199], v56 offset:10496
	v_or_b32_e32 v1, 0x80000000, v1
	s_cmpk_gt_i32 s11, 408
	s_cselect_b64 vcc, -1, 0
	v_xor_b32_e32 v0, v1, v0
	v_cndmask_b32_e32 v183, v123, v0, vcc
	s_nop 3
	s_waitcnt lgkmcnt(3)
	v_mfma_f32_32x32x16_bf16 v[212:227], v[70:73], v[38:41], 0
	v_max_f32_e32 v108, 0, v6
	v_max_f32_e32 v109, 0, v7
	v_pk_mul_f32 v[50:51], v[244:245], v[108:109]
	v_max_f32_e32 v210, 0, v8
	v_max_f32_e32 v211, 0, v9
	v_pk_fma_f32 v[50:51], v[246:247], v[210:211], v[50:51]
	v_max_f32_e32 v108, 0, v10
	v_max_f32_e32 v109, 0, v11
	v_pk_fma_f32 v[50:51], v[248:249], v[108:109], v[50:51]
	s_waitcnt lgkmcnt(2)
	v_mfma_f32_32x32x16_bf16 v[212:227], v[74:77], v[42:45], v[212:227]
	v_max_f32_e32 v210, 0, v12
	v_max_f32_e32 v211, 0, v13
	v_pk_fma_f32 v[50:51], v[250:251], v[210:211], v[50:51]
	v_max_f32_e32 v108, 0, v14
	v_max_f32_e32 v109, 0, v15
	v_pk_fma_f32 v[50:51], v[252:253], v[108:109], v[50:51]
	v_max_f32_e32 v210, 0, v16
	v_max_f32_e32 v211, 0, v17
	v_pk_fma_f32 v[50:51], v[254:255], v[210:211], v[50:51]
	s_waitcnt lgkmcnt(1)
	v_mfma_f32_32x32x16_bf16 v[212:227], v[78:81], v[46:49], v[212:227]
	v_max_f32_e32 v108, 0, v18
	v_max_f32_e32 v109, 0, v19
	v_pk_fma_f32 v[50:51], v[200:201], v[108:109], v[50:51]
	v_max_f32_e32 v210, 0, v20
	v_max_f32_e32 v211, 0, v21
	v_pk_fma_f32 v[50:51], v[202:203], v[210:211], v[50:51]
	v_add_f32_e32 v50, v50, v51
	v_ashrrev_i32_e32 v51, 31, v50
	s_waitcnt lgkmcnt(0)
	v_mfma_f32_32x32x16_bf16 v[212:227], v[82:85], v[196:199], v[212:227]
	v_or_b32_e32 v51, 0x80000000, v51
	s_cmpk_gt_i32 s11, 408
	s_cselect_b64 vcc, -1, 0
	v_xor_b32_e32 v50, v51, v50
	v_cndmask_b32_e32 v50, v123, v50, vcc
	global_store_dword v243, v50, s[8:9] offset:2048
	s_add_u32 s8, s8, 0x1000
	s_addc_u32 s9, s9, 0
	v_mfma_f32_32x32x16_bf16 v[6:21], v[86:89], v[38:41], 0
	s_add_i32 m0, s10, 98304
	s_nop 0
	global_load_lds_dwordx4 v102, s[6:7]
	s_add_i32 m0, s10, 99328
	s_nop 0
	global_load_lds_dwordx4 v110, s[6:7]
	s_add_i32 m0, s10, 100352
	s_nop 0
	global_load_lds_dwordx4 v112, s[6:7]
	s_add_i32 m0, s10, 101376
	s_nop 0
	global_load_lds_dwordx4 v193, s[6:7]
	s_add_u32 s6, s6, 0x8000
	s_addc_u32 s7, s7, 0
	v_max_f32_e32 v108, 0, v212
	v_max_f32_e32 v109, 0, v213
	v_pk_mul_f32 v[0:1], v[22:23], v[108:109]
	v_max_f32_e32 v210, 0, v214
	v_max_f32_e32 v211, 0, v215
	v_pk_fma_f32 v[0:1], v[24:25], v[210:211], v[0:1]
	v_max_f32_e32 v108, 0, v216
	v_max_f32_e32 v109, 0, v217
	v_pk_fma_f32 v[0:1], v[26:27], v[108:109], v[0:1]
	v_mfma_f32_32x32x16_bf16 v[6:21], v[90:93], v[42:45], v[6:21]
	v_max_f32_e32 v210, 0, v218
	v_max_f32_e32 v211, 0, v219
	v_pk_fma_f32 v[0:1], v[28:29], v[210:211], v[0:1]
	v_max_f32_e32 v108, 0, v220
	v_max_f32_e32 v109, 0, v221
	v_pk_fma_f32 v[0:1], v[30:31], v[108:109], v[0:1]
	v_max_f32_e32 v210, 0, v222
	v_max_f32_e32 v211, 0, v223
	v_pk_fma_f32 v[0:1], v[32:33], v[210:211], v[0:1]
	v_mfma_f32_32x32x16_bf16 v[6:21], v[94:97], v[46:49], v[6:21]
	v_max_f32_e32 v108, 0, v224
	v_max_f32_e32 v109, 0, v225
	v_pk_fma_f32 v[0:1], v[34:35], v[108:109], v[0:1]
	v_max_f32_e32 v210, 0, v226
	v_max_f32_e32 v211, 0, v227
	v_pk_fma_f32 v[0:1], v[36:37], v[210:211], v[0:1]
	v_add_f32_e32 v0, v0, v1
	v_ashrrev_i32_e32 v1, 31, v0
	v_mfma_f32_32x32x16_bf16 v[6:21], v[98:101], v[196:199], v[6:21]
	s_waitcnt vmcnt(10)
	ds_read_b128 v[38:41], v5 offset:43264
	ds_read_b128 v[42:45], v52 offset:43264
	ds_read_b128 v[46:49], v55 offset:43264
	ds_read_b128 v[196:199], v56 offset:43264
	v_or_b32_e32 v1, 0x80000000, v1
	s_cmpk_gt_i32 s11, 416
	s_cselect_b64 vcc, -1, 0
	v_xor_b32_e32 v0, v1, v0
	v_cndmask_b32_e32 v187, v123, v0, vcc
	s_nop 3
	s_waitcnt lgkmcnt(3)
	v_mfma_f32_32x32x16_bf16 v[212:227], v[70:73], v[38:41], 0
	v_max_f32_e32 v108, 0, v6
	v_max_f32_e32 v109, 0, v7
	v_pk_mul_f32 v[50:51], v[244:245], v[108:109]
	v_max_f32_e32 v210, 0, v8
	v_max_f32_e32 v211, 0, v9
	v_pk_fma_f32 v[50:51], v[246:247], v[210:211], v[50:51]
	v_max_f32_e32 v108, 0, v10
	v_max_f32_e32 v109, 0, v11
	v_pk_fma_f32 v[50:51], v[248:249], v[108:109], v[50:51]
	s_waitcnt lgkmcnt(2)
	v_mfma_f32_32x32x16_bf16 v[212:227], v[74:77], v[42:45], v[212:227]
	v_max_f32_e32 v210, 0, v12
	v_max_f32_e32 v211, 0, v13
	v_pk_fma_f32 v[50:51], v[250:251], v[210:211], v[50:51]
	v_max_f32_e32 v108, 0, v14
	v_max_f32_e32 v109, 0, v15
	v_pk_fma_f32 v[50:51], v[252:253], v[108:109], v[50:51]
	v_max_f32_e32 v210, 0, v16
	v_max_f32_e32 v211, 0, v17
	v_pk_fma_f32 v[50:51], v[254:255], v[210:211], v[50:51]
	s_waitcnt lgkmcnt(1)
	v_mfma_f32_32x32x16_bf16 v[212:227], v[78:81], v[46:49], v[212:227]
	v_max_f32_e32 v108, 0, v18
	v_max_f32_e32 v109, 0, v19
	v_pk_fma_f32 v[50:51], v[200:201], v[108:109], v[50:51]
	v_max_f32_e32 v210, 0, v20
	v_max_f32_e32 v211, 0, v21
	v_pk_fma_f32 v[50:51], v[202:203], v[210:211], v[50:51]
	v_add_f32_e32 v50, v50, v51
	v_ashrrev_i32_e32 v51, 31, v50
	s_waitcnt lgkmcnt(0)
	v_mfma_f32_32x32x16_bf16 v[212:227], v[82:85], v[196:199], v[212:227]
	v_or_b32_e32 v51, 0x80000000, v51
	s_cmpk_gt_i32 s11, 416
	s_cselect_b64 vcc, -1, 0
	v_xor_b32_e32 v50, v51, v50
	v_cndmask_b32_e32 v50, v123, v50, vcc
	global_store_dword v243, v50, s[8:9]
	v_mfma_f32_32x32x16_bf16 v[6:21], v[86:89], v[38:41], 0
	s_add_i32 m0, s10, 0
	s_nop 0
	global_load_lds_dwordx4 v102, s[6:7]
	s_add_i32 m0, s10, 1024
	s_nop 0
	global_load_lds_dwordx4 v110, s[6:7]
	s_add_i32 m0, s10, 2048
	s_nop 0
	global_load_lds_dwordx4 v112, s[6:7]
	s_add_i32 m0, s10, 3072
	s_nop 0
	global_load_lds_dwordx4 v193, s[6:7]
	s_add_u32 s6, s6, 0x8000
	s_addc_u32 s7, s7, 0
	v_max_f32_e32 v108, 0, v212
	v_max_f32_e32 v109, 0, v213
	v_pk_mul_f32 v[0:1], v[22:23], v[108:109]
	v_max_f32_e32 v210, 0, v214
	v_max_f32_e32 v211, 0, v215
	v_pk_fma_f32 v[0:1], v[24:25], v[210:211], v[0:1]
	v_max_f32_e32 v108, 0, v216
	v_max_f32_e32 v109, 0, v217
	v_pk_fma_f32 v[0:1], v[26:27], v[108:109], v[0:1]
	v_mfma_f32_32x32x16_bf16 v[6:21], v[90:93], v[42:45], v[6:21]
	v_max_f32_e32 v210, 0, v218
	v_max_f32_e32 v211, 0, v219
	v_pk_fma_f32 v[0:1], v[28:29], v[210:211], v[0:1]
	v_max_f32_e32 v108, 0, v220
	v_max_f32_e32 v109, 0, v221
	v_pk_fma_f32 v[0:1], v[30:31], v[108:109], v[0:1]
	v_max_f32_e32 v210, 0, v222
	v_max_f32_e32 v211, 0, v223
	v_pk_fma_f32 v[0:1], v[32:33], v[210:211], v[0:1]
	v_mfma_f32_32x32x16_bf16 v[6:21], v[94:97], v[46:49], v[6:21]
	v_max_f32_e32 v108, 0, v224
	v_max_f32_e32 v109, 0, v225
	v_pk_fma_f32 v[0:1], v[34:35], v[108:109], v[0:1]
	v_max_f32_e32 v210, 0, v226
	v_max_f32_e32 v211, 0, v227
	v_pk_fma_f32 v[0:1], v[36:37], v[210:211], v[0:1]
	v_add_f32_e32 v0, v0, v1
	v_ashrrev_i32_e32 v1, 31, v0
	v_mfma_f32_32x32x16_bf16 v[6:21], v[98:101], v[196:199], v[6:21]
	s_waitcnt vmcnt(10)
	v_add_u32_e32 v228, 0x10000, v5
	ds_read_b128 v[38:41], v228 offset:10496
	v_add_u32_e32 v228, 0x10000, v52
	ds_read_b128 v[42:45], v228 offset:10496
	v_add_u32_e32 v228, 0x10000, v55
	ds_read_b128 v[46:49], v228 offset:10496
	v_add_u32_e32 v228, 0x10000, v56
	ds_read_b128 v[196:199], v228 offset:10496
	v_or_b32_e32 v1, 0x80000000, v1
	s_cmpk_gt_i32 s11, 424
	s_cselect_b64 vcc, -1, 0
	v_xor_b32_e32 v0, v1, v0
	v_cndmask_b32_e32 v186, v123, v0, vcc
	s_nop 3
	s_waitcnt lgkmcnt(3)
	v_mfma_f32_32x32x16_bf16 v[212:227], v[70:73], v[38:41], 0
	v_max_f32_e32 v108, 0, v6
	v_max_f32_e32 v109, 0, v7
	v_pk_mul_f32 v[50:51], v[244:245], v[108:109]
	v_max_f32_e32 v210, 0, v8
	v_max_f32_e32 v211, 0, v9
	v_pk_fma_f32 v[50:51], v[246:247], v[210:211], v[50:51]
	v_max_f32_e32 v108, 0, v10
	v_max_f32_e32 v109, 0, v11
	v_pk_fma_f32 v[50:51], v[248:249], v[108:109], v[50:51]
	s_waitcnt lgkmcnt(2)
	v_mfma_f32_32x32x16_bf16 v[212:227], v[74:77], v[42:45], v[212:227]
	v_max_f32_e32 v210, 0, v12
	v_max_f32_e32 v211, 0, v13
	v_pk_fma_f32 v[50:51], v[250:251], v[210:211], v[50:51]
	v_max_f32_e32 v108, 0, v14
	v_max_f32_e32 v109, 0, v15
	v_pk_fma_f32 v[50:51], v[252:253], v[108:109], v[50:51]
	v_max_f32_e32 v210, 0, v16
	v_max_f32_e32 v211, 0, v17
	v_pk_fma_f32 v[50:51], v[254:255], v[210:211], v[50:51]
	s_waitcnt lgkmcnt(1)
	v_mfma_f32_32x32x16_bf16 v[212:227], v[78:81], v[46:49], v[212:227]
	v_max_f32_e32 v108, 0, v18
	v_max_f32_e32 v109, 0, v19
	v_pk_fma_f32 v[50:51], v[200:201], v[108:109], v[50:51]
	v_max_f32_e32 v210, 0, v20
	v_max_f32_e32 v211, 0, v21
	v_pk_fma_f32 v[50:51], v[202:203], v[210:211], v[50:51]
	v_add_f32_e32 v50, v50, v51
	v_ashrrev_i32_e32 v51, 31, v50
	s_waitcnt lgkmcnt(0)
	v_mfma_f32_32x32x16_bf16 v[212:227], v[82:85], v[196:199], v[212:227]
	v_or_b32_e32 v51, 0x80000000, v51
	s_cmpk_gt_i32 s11, 424
	s_cselect_b64 vcc, -1, 0
	v_xor_b32_e32 v50, v51, v50
	v_cndmask_b32_e32 v50, v123, v50, vcc
	global_store_dword v243, v50, s[8:9] offset:2048
	s_add_u32 s8, s8, 0x1000
	s_addc_u32 s9, s9, 0
	v_mfma_f32_32x32x16_bf16 v[6:21], v[86:89], v[38:41], 0
	s_add_i32 m0, s10, 32768
	s_nop 0
	global_load_lds_dwordx4 v102, s[6:7]
	s_add_i32 m0, s10, 33792
	s_nop 0
	global_load_lds_dwordx4 v110, s[6:7]
	s_add_i32 m0, s10, 34816
	s_nop 0
	global_load_lds_dwordx4 v112, s[6:7]
	s_add_i32 m0, s10, 35840
	s_nop 0
	global_load_lds_dwordx4 v193, s[6:7]
	s_add_u32 s6, s6, 0x8000
	s_addc_u32 s7, s7, 0
	v_max_f32_e32 v108, 0, v212
	v_max_f32_e32 v109, 0, v213
	v_pk_mul_f32 v[0:1], v[22:23], v[108:109]
	v_max_f32_e32 v210, 0, v214
	v_max_f32_e32 v211, 0, v215
	v_pk_fma_f32 v[0:1], v[24:25], v[210:211], v[0:1]
	v_max_f32_e32 v108, 0, v216
	v_max_f32_e32 v109, 0, v217
	v_pk_fma_f32 v[0:1], v[26:27], v[108:109], v[0:1]
	v_mfma_f32_32x32x16_bf16 v[6:21], v[90:93], v[42:45], v[6:21]
	v_max_f32_e32 v210, 0, v218
	v_max_f32_e32 v211, 0, v219
	v_pk_fma_f32 v[0:1], v[28:29], v[210:211], v[0:1]
	v_max_f32_e32 v108, 0, v220
	v_max_f32_e32 v109, 0, v221
	v_pk_fma_f32 v[0:1], v[30:31], v[108:109], v[0:1]
	v_max_f32_e32 v210, 0, v222
	v_max_f32_e32 v211, 0, v223
	v_pk_fma_f32 v[0:1], v[32:33], v[210:211], v[0:1]
	v_mfma_f32_32x32x16_bf16 v[6:21], v[94:97], v[46:49], v[6:21]
	v_max_f32_e32 v108, 0, v224
	v_max_f32_e32 v109, 0, v225
	v_pk_fma_f32 v[0:1], v[34:35], v[108:109], v[0:1]
	v_max_f32_e32 v210, 0, v226
	v_max_f32_e32 v211, 0, v227
	v_pk_fma_f32 v[0:1], v[36:37], v[210:211], v[0:1]
	v_add_f32_e32 v0, v0, v1
	v_ashrrev_i32_e32 v1, 31, v0
	v_mfma_f32_32x32x16_bf16 v[6:21], v[98:101], v[196:199], v[6:21]
	s_waitcnt vmcnt(10)
	v_add_u32_e32 v228, 0x10000, v5
	ds_read_b128 v[38:41], v228 offset:43264
	v_add_u32_e32 v228, 0x10000, v52
	ds_read_b128 v[42:45], v228 offset:43264
	v_add_u32_e32 v228, 0x10000, v55
	ds_read_b128 v[46:49], v228 offset:43264
	v_add_u32_e32 v228, 0x10000, v56
	ds_read_b128 v[196:199], v228 offset:43264
	v_or_b32_e32 v1, 0x80000000, v1
	s_cmpk_gt_i32 s11, 432
	s_cselect_b64 vcc, -1, 0
	v_xor_b32_e32 v0, v1, v0
	v_cndmask_b32_e32 v189, v123, v0, vcc
	s_nop 3
	s_waitcnt lgkmcnt(3)
	v_mfma_f32_32x32x16_bf16 v[212:227], v[70:73], v[38:41], 0
	v_max_f32_e32 v108, 0, v6
	v_max_f32_e32 v109, 0, v7
	v_pk_mul_f32 v[50:51], v[244:245], v[108:109]
	v_max_f32_e32 v210, 0, v8
	v_max_f32_e32 v211, 0, v9
	v_pk_fma_f32 v[50:51], v[246:247], v[210:211], v[50:51]
	v_max_f32_e32 v108, 0, v10
	v_max_f32_e32 v109, 0, v11
	v_pk_fma_f32 v[50:51], v[248:249], v[108:109], v[50:51]
	s_waitcnt lgkmcnt(2)
	v_mfma_f32_32x32x16_bf16 v[212:227], v[74:77], v[42:45], v[212:227]
	v_max_f32_e32 v210, 0, v12
	v_max_f32_e32 v211, 0, v13
	v_pk_fma_f32 v[50:51], v[250:251], v[210:211], v[50:51]
	v_max_f32_e32 v108, 0, v14
	v_max_f32_e32 v109, 0, v15
	v_pk_fma_f32 v[50:51], v[252:253], v[108:109], v[50:51]
	v_max_f32_e32 v210, 0, v16
	v_max_f32_e32 v211, 0, v17
	v_pk_fma_f32 v[50:51], v[254:255], v[210:211], v[50:51]
	s_waitcnt lgkmcnt(1)
	v_mfma_f32_32x32x16_bf16 v[212:227], v[78:81], v[46:49], v[212:227]
	v_max_f32_e32 v108, 0, v18
	v_max_f32_e32 v109, 0, v19
	v_pk_fma_f32 v[50:51], v[200:201], v[108:109], v[50:51]
	v_max_f32_e32 v210, 0, v20
	v_max_f32_e32 v211, 0, v21
	v_pk_fma_f32 v[50:51], v[202:203], v[210:211], v[50:51]
	v_add_f32_e32 v50, v50, v51
	v_ashrrev_i32_e32 v51, 31, v50
	s_waitcnt lgkmcnt(0)
	v_mfma_f32_32x32x16_bf16 v[212:227], v[82:85], v[196:199], v[212:227]
	v_or_b32_e32 v51, 0x80000000, v51
	s_cmpk_gt_i32 s11, 432
	s_cselect_b64 vcc, -1, 0
	v_xor_b32_e32 v50, v51, v50
	v_cndmask_b32_e32 v50, v123, v50, vcc
	global_store_dword v243, v50, s[8:9]
	v_mfma_f32_32x32x16_bf16 v[6:21], v[86:89], v[38:41], 0
	s_add_i32 m0, s10, 65536
	s_nop 0
	global_load_lds_dwordx4 v102, s[6:7]
	s_add_i32 m0, s10, 66560
	s_nop 0
	global_load_lds_dwordx4 v110, s[6:7]
	s_add_i32 m0, s10, 67584
	s_nop 0
	global_load_lds_dwordx4 v112, s[6:7]
	s_add_i32 m0, s10, 68608
	s_nop 0
	global_load_lds_dwordx4 v193, s[6:7]
	s_add_u32 s6, s6, 0x8000
	s_addc_u32 s7, s7, 0
	v_max_f32_e32 v108, 0, v212
	v_max_f32_e32 v109, 0, v213
	v_pk_mul_f32 v[0:1], v[22:23], v[108:109]
	v_max_f32_e32 v210, 0, v214
	v_max_f32_e32 v211, 0, v215
	v_pk_fma_f32 v[0:1], v[24:25], v[210:211], v[0:1]
	v_max_f32_e32 v108, 0, v216
	v_max_f32_e32 v109, 0, v217
	v_pk_fma_f32 v[0:1], v[26:27], v[108:109], v[0:1]
	v_mfma_f32_32x32x16_bf16 v[6:21], v[90:93], v[42:45], v[6:21]
	v_max_f32_e32 v210, 0, v218
	v_max_f32_e32 v211, 0, v219
	v_pk_fma_f32 v[0:1], v[28:29], v[210:211], v[0:1]
	v_max_f32_e32 v108, 0, v220
	v_max_f32_e32 v109, 0, v221
	v_pk_fma_f32 v[0:1], v[30:31], v[108:109], v[0:1]
	v_max_f32_e32 v210, 0, v222
	v_max_f32_e32 v211, 0, v223
	v_pk_fma_f32 v[0:1], v[32:33], v[210:211], v[0:1]
	v_mfma_f32_32x32x16_bf16 v[6:21], v[94:97], v[46:49], v[6:21]
	v_max_f32_e32 v108, 0, v224
	v_max_f32_e32 v109, 0, v225
	v_pk_fma_f32 v[0:1], v[34:35], v[108:109], v[0:1]
	v_max_f32_e32 v210, 0, v226
	v_max_f32_e32 v211, 0, v227
	v_pk_fma_f32 v[0:1], v[36:37], v[210:211], v[0:1]
	v_add_f32_e32 v0, v0, v1
	v_ashrrev_i32_e32 v1, 31, v0
	v_mfma_f32_32x32x16_bf16 v[6:21], v[98:101], v[196:199], v[6:21]
	s_waitcnt vmcnt(10)
	ds_read_b128 v[38:41], v5 offset:10496
	ds_read_b128 v[42:45], v52 offset:10496
	ds_read_b128 v[46:49], v55 offset:10496
	ds_read_b128 v[196:199], v56 offset:10496
	v_or_b32_e32 v1, 0x80000000, v1
	s_cmpk_gt_i32 s11, 440
	s_cselect_b64 vcc, -1, 0
	v_xor_b32_e32 v0, v1, v0
	v_cndmask_b32_e32 v188, v123, v0, vcc
	s_nop 3
	v_max_f32_e32 v108, 0, v6
	v_max_f32_e32 v109, 0, v7
	v_pk_mul_f32 v[50:51], v[244:245], v[108:109]
	v_max_f32_e32 v210, 0, v8
	v_max_f32_e32 v211, 0, v9
	v_pk_fma_f32 v[50:51], v[246:247], v[210:211], v[50:51]
	v_max_f32_e32 v108, 0, v10
	v_max_f32_e32 v109, 0, v11
	v_pk_fma_f32 v[50:51], v[248:249], v[108:109], v[50:51]
	v_max_f32_e32 v210, 0, v12
	v_max_f32_e32 v211, 0, v13
	v_pk_fma_f32 v[50:51], v[250:251], v[210:211], v[50:51]
	v_max_f32_e32 v108, 0, v14
	v_max_f32_e32 v109, 0, v15
	v_pk_fma_f32 v[50:51], v[252:253], v[108:109], v[50:51]
	v_max_f32_e32 v210, 0, v16
	v_max_f32_e32 v211, 0, v17
	v_pk_fma_f32 v[50:51], v[254:255], v[210:211], v[50:51]
	v_max_f32_e32 v108, 0, v18
	v_max_f32_e32 v109, 0, v19
	v_pk_fma_f32 v[50:51], v[200:201], v[108:109], v[50:51]
	v_max_f32_e32 v210, 0, v20
	v_max_f32_e32 v211, 0, v21
	v_pk_fma_f32 v[50:51], v[202:203], v[210:211], v[50:51]
	v_add_f32_e32 v50, v50, v51
	v_ashrrev_i32_e32 v51, 31, v50
	v_or_b32_e32 v51, 0x80000000, v51
	s_cmpk_gt_i32 s11, 440
	s_cselect_b64 vcc, -1, 0
	v_xor_b32_e32 v50, v51, v50
	v_cndmask_b32_e32 v50, v123, v50, vcc
	global_store_dword v243, v50, s[8:9] offset:2048
	s_add_u32 s8, s8, 0x1000
	s_addc_u32 s9, s9, 0
	s_cmpk_gt_i32 s81, 56
	s_cbranch_scc0 .Lix_fill_7
	s_waitcnt lgkmcnt(3)
	v_mfma_f32_32x32x16_bf16 v[212:227], v[70:73], v[38:41], 0
	s_add_i32 m0, s10, 98304
	s_nop 0
	global_load_lds_dwordx4 v102, s[6:7]
	s_waitcnt lgkmcnt(2)
	v_mfma_f32_32x32x16_bf16 v[212:227], v[74:77], v[42:45], v[212:227]
	s_add_i32 m0, s10, 99328
	s_nop 0
	global_load_lds_dwordx4 v110, s[6:7]
	s_waitcnt lgkmcnt(1)
	v_mfma_f32_32x32x16_bf16 v[212:227], v[78:81], v[46:49], v[212:227]
	s_add_i32 m0, s10, 100352
	s_nop 0
	global_load_lds_dwordx4 v112, s[6:7]
	s_waitcnt lgkmcnt(0)
	v_mfma_f32_32x32x16_bf16 v[212:227], v[82:85], v[196:199], v[212:227]
	s_add_i32 m0, s10, 101376
	s_nop 0
	global_load_lds_dwordx4 v193, s[6:7]
	s_add_u32 s6, s6, 0x8000
	s_addc_u32 s7, s7, 0
	v_mfma_f32_32x32x16_bf16 v[6:21], v[86:89], v[38:41], 0
	s_nop 7
	s_nop 2
	v_max_f32_e32 v108, 0, v212
	v_max_f32_e32 v109, 0, v213
	v_pk_mul_f32 v[0:1], v[22:23], v[108:109]
	v_max_f32_e32 v210, 0, v214
	v_max_f32_e32 v211, 0, v215
	v_pk_fma_f32 v[0:1], v[24:25], v[210:211], v[0:1]
	v_max_f32_e32 v108, 0, v216
	v_max_f32_e32 v109, 0, v217
	v_pk_fma_f32 v[0:1], v[26:27], v[108:109], v[0:1]
	v_mfma_f32_32x32x16_bf16 v[6:21], v[90:93], v[42:45], v[6:21]
	v_max_f32_e32 v210, 0, v218
	v_max_f32_e32 v211, 0, v219
	v_pk_fma_f32 v[0:1], v[28:29], v[210:211], v[0:1]
	v_max_f32_e32 v108, 0, v220
	v_max_f32_e32 v109, 0, v221
	v_pk_fma_f32 v[0:1], v[30:31], v[108:109], v[0:1]
	v_max_f32_e32 v210, 0, v222
	v_max_f32_e32 v211, 0, v223
	v_pk_fma_f32 v[0:1], v[32:33], v[210:211], v[0:1]
	v_mfma_f32_32x32x16_bf16 v[6:21], v[94:97], v[46:49], v[6:21]
	v_max_f32_e32 v108, 0, v224
	v_max_f32_e32 v109, 0, v225
	v_pk_fma_f32 v[0:1], v[34:35], v[108:109], v[0:1]
	v_max_f32_e32 v210, 0, v226
	v_max_f32_e32 v211, 0, v227
	v_pk_fma_f32 v[0:1], v[36:37], v[210:211], v[0:1]
	v_add_f32_e32 v0, v0, v1
	v_ashrrev_i32_e32 v1, 31, v0
	v_mfma_f32_32x32x16_bf16 v[6:21], v[98:101], v[196:199], v[6:21]
	s_waitcnt vmcnt(10)
	ds_read_b128 v[38:41], v5 offset:43264
	ds_read_b128 v[42:45], v52 offset:43264
	ds_read_b128 v[46:49], v55 offset:43264
	ds_read_b128 v[196:199], v56 offset:43264
	v_or_b32_e32 v1, 0x80000000, v1
	s_cmpk_gt_i32 s11, 448
	s_cselect_b64 vcc, -1, 0
	v_xor_b32_e32 v0, v1, v0
	v_cndmask_b32_e32 v190, v123, v0, vcc
	s_nop 3
	s_waitcnt lgkmcnt(3)
	v_mfma_f32_32x32x16_bf16 v[212:227], v[70:73], v[38:41], 0
	v_max_f32_e32 v108, 0, v6
	v_max_f32_e32 v109, 0, v7
	v_pk_mul_f32 v[50:51], v[244:245], v[108:109]
	v_max_f32_e32 v210, 0, v8
	v_max_f32_e32 v211, 0, v9
	v_pk_fma_f32 v[50:51], v[246:247], v[210:211], v[50:51]
	v_max_f32_e32 v108, 0, v10
	v_max_f32_e32 v109, 0, v11
	v_pk_fma_f32 v[50:51], v[248:249], v[108:109], v[50:51]
	s_waitcnt lgkmcnt(2)
	v_mfma_f32_32x32x16_bf16 v[212:227], v[74:77], v[42:45], v[212:227]
	v_max_f32_e32 v210, 0, v12
	v_max_f32_e32 v211, 0, v13
	v_pk_fma_f32 v[50:51], v[250:251], v[210:211], v[50:51]
	v_max_f32_e32 v108, 0, v14
	v_max_f32_e32 v109, 0, v15
	v_pk_fma_f32 v[50:51], v[252:253], v[108:109], v[50:51]
	v_max_f32_e32 v210, 0, v16
	v_max_f32_e32 v211, 0, v17
	v_pk_fma_f32 v[50:51], v[254:255], v[210:211], v[50:51]
	s_waitcnt lgkmcnt(1)
	v_mfma_f32_32x32x16_bf16 v[212:227], v[78:81], v[46:49], v[212:227]
	v_max_f32_e32 v108, 0, v18
	v_max_f32_e32 v109, 0, v19
	v_pk_fma_f32 v[50:51], v[200:201], v[108:109], v[50:51]
	v_max_f32_e32 v210, 0, v20
	v_max_f32_e32 v211, 0, v21
	v_pk_fma_f32 v[50:51], v[202:203], v[210:211], v[50:51]
	v_add_f32_e32 v50, v50, v51
	v_ashrrev_i32_e32 v51, 31, v50
	s_waitcnt lgkmcnt(0)
	v_mfma_f32_32x32x16_bf16 v[212:227], v[82:85], v[196:199], v[212:227]
	v_or_b32_e32 v51, 0x80000000, v51
	s_cmpk_gt_i32 s11, 448
	s_cselect_b64 vcc, -1, 0
	v_xor_b32_e32 v50, v51, v50
	v_cndmask_b32_e32 v50, v123, v50, vcc
	global_store_dword v243, v50, s[8:9]
	v_mfma_f32_32x32x16_bf16 v[6:21], v[86:89], v[38:41], 0
	s_add_i32 m0, s10, 0
	s_nop 0
	global_load_lds_dwordx4 v102, s[6:7]
	s_add_i32 m0, s10, 1024
	s_nop 0
	global_load_lds_dwordx4 v110, s[6:7]
	s_add_i32 m0, s10, 2048
	s_nop 0
	global_load_lds_dwordx4 v112, s[6:7]
	s_add_i32 m0, s10, 3072
	s_nop 0
	global_load_lds_dwordx4 v193, s[6:7]
	s_add_u32 s6, s6, 0x8000
	s_addc_u32 s7, s7, 0
	v_max_f32_e32 v108, 0, v212
	v_max_f32_e32 v109, 0, v213
	v_pk_mul_f32 v[0:1], v[22:23], v[108:109]
	v_max_f32_e32 v210, 0, v214
	v_max_f32_e32 v211, 0, v215
	v_pk_fma_f32 v[0:1], v[24:25], v[210:211], v[0:1]
	v_max_f32_e32 v108, 0, v216
	v_max_f32_e32 v109, 0, v217
	v_pk_fma_f32 v[0:1], v[26:27], v[108:109], v[0:1]
	v_mfma_f32_32x32x16_bf16 v[6:21], v[90:93], v[42:45], v[6:21]
	v_max_f32_e32 v210, 0, v218
	v_max_f32_e32 v211, 0, v219
	v_pk_fma_f32 v[0:1], v[28:29], v[210:211], v[0:1]
	v_max_f32_e32 v108, 0, v220
	v_max_f32_e32 v109, 0, v221
	v_pk_fma_f32 v[0:1], v[30:31], v[108:109], v[0:1]
	v_max_f32_e32 v210, 0, v222
	v_max_f32_e32 v211, 0, v223
	v_pk_fma_f32 v[0:1], v[32:33], v[210:211], v[0:1]
	v_mfma_f32_32x32x16_bf16 v[6:21], v[94:97], v[46:49], v[6:21]
	v_max_f32_e32 v108, 0, v224
	v_max_f32_e32 v109, 0, v225
	v_pk_fma_f32 v[0:1], v[34:35], v[108:109], v[0:1]
	v_max_f32_e32 v210, 0, v226
	v_max_f32_e32 v211, 0, v227
	v_pk_fma_f32 v[0:1], v[36:37], v[210:211], v[0:1]
	v_add_f32_e32 v0, v0, v1
	v_ashrrev_i32_e32 v1, 31, v0
	v_mfma_f32_32x32x16_bf16 v[6:21], v[98:101], v[196:199], v[6:21]
	s_waitcnt vmcnt(10)
	v_add_u32_e32 v228, 0x10000, v5
	ds_read_b128 v[38:41], v228 offset:10496
	v_add_u32_e32 v228, 0x10000, v52
	ds_read_b128 v[42:45], v228 offset:10496
	v_add_u32_e32 v228, 0x10000, v55
	ds_read_b128 v[46:49], v228 offset:10496
	v_add_u32_e32 v228, 0x10000, v56
	ds_read_b128 v[196:199], v228 offset:10496
	v_or_b32_e32 v1, 0x80000000, v1
	s_cmpk_gt_i32 s11, 456
	s_cselect_b64 vcc, -1, 0
	v_xor_b32_e32 v0, v1, v0
	v_cndmask_b32_e32 v53, v123, v0, vcc
	s_nop 3
	s_waitcnt lgkmcnt(3)
	v_mfma_f32_32x32x16_bf16 v[212:227], v[70:73], v[38:41], 0
	v_max_f32_e32 v108, 0, v6
	v_max_f32_e32 v109, 0, v7
	v_pk_mul_f32 v[50:51], v[244:245], v[108:109]
	v_max_f32_e32 v210, 0, v8
	v_max_f32_e32 v211, 0, v9
	v_pk_fma_f32 v[50:51], v[246:247], v[210:211], v[50:51]
	v_max_f32_e32 v108, 0, v10
	v_max_f32_e32 v109, 0, v11
	v_pk_fma_f32 v[50:51], v[248:249], v[108:109], v[50:51]
	s_waitcnt lgkmcnt(2)
	v_mfma_f32_32x32x16_bf16 v[212:227], v[74:77], v[42:45], v[212:227]
	v_max_f32_e32 v210, 0, v12
	v_max_f32_e32 v211, 0, v13
	v_pk_fma_f32 v[50:51], v[250:251], v[210:211], v[50:51]
	v_max_f32_e32 v108, 0, v14
	v_max_f32_e32 v109, 0, v15
	v_pk_fma_f32 v[50:51], v[252:253], v[108:109], v[50:51]
	v_max_f32_e32 v210, 0, v16
	v_max_f32_e32 v211, 0, v17
	v_pk_fma_f32 v[50:51], v[254:255], v[210:211], v[50:51]
	s_waitcnt lgkmcnt(1)
	v_mfma_f32_32x32x16_bf16 v[212:227], v[78:81], v[46:49], v[212:227]
	v_max_f32_e32 v108, 0, v18
	v_max_f32_e32 v109, 0, v19
	v_pk_fma_f32 v[50:51], v[200:201], v[108:109], v[50:51]
	v_max_f32_e32 v210, 0, v20
	v_max_f32_e32 v211, 0, v21
	v_pk_fma_f32 v[50:51], v[202:203], v[210:211], v[50:51]
	v_add_f32_e32 v50, v50, v51
	v_ashrrev_i32_e32 v51, 31, v50
	s_waitcnt lgkmcnt(0)
	v_mfma_f32_32x32x16_bf16 v[212:227], v[82:85], v[196:199], v[212:227]
	v_or_b32_e32 v51, 0x80000000, v51
	s_cmpk_gt_i32 s11, 456
	s_cselect_b64 vcc, -1, 0
	v_xor_b32_e32 v50, v51, v50
	v_cndmask_b32_e32 v50, v123, v50, vcc
	global_store_dword v243, v50, s[8:9] offset:2048
	s_add_u32 s8, s8, 0x1000
	s_addc_u32 s9, s9, 0
	v_mfma_f32_32x32x16_bf16 v[6:21], v[86:89], v[38:41], 0
	s_add_i32 m0, s10, 32768
	s_nop 0
	global_load_lds_dwordx4 v102, s[6:7]
	s_add_i32 m0, s10, 33792
	s_nop 0
	global_load_lds_dwordx4 v110, s[6:7]
	s_add_i32 m0, s10, 34816
	s_nop 0
	global_load_lds_dwordx4 v112, s[6:7]
	s_add_i32 m0, s10, 35840
	s_nop 0
	global_load_lds_dwordx4 v193, s[6:7]
	s_add_u32 s6, s6, 0x8000
	s_addc_u32 s7, s7, 0
	v_max_f32_e32 v108, 0, v212
	v_max_f32_e32 v109, 0, v213
	v_pk_mul_f32 v[0:1], v[22:23], v[108:109]
	v_max_f32_e32 v210, 0, v214
	v_max_f32_e32 v211, 0, v215
	v_pk_fma_f32 v[0:1], v[24:25], v[210:211], v[0:1]
	v_max_f32_e32 v108, 0, v216
	v_max_f32_e32 v109, 0, v217
	v_pk_fma_f32 v[0:1], v[26:27], v[108:109], v[0:1]
	v_mfma_f32_32x32x16_bf16 v[6:21], v[90:93], v[42:45], v[6:21]
	v_max_f32_e32 v210, 0, v218
	v_max_f32_e32 v211, 0, v219
	v_pk_fma_f32 v[0:1], v[28:29], v[210:211], v[0:1]
	v_max_f32_e32 v108, 0, v220
	v_max_f32_e32 v109, 0, v221
	v_pk_fma_f32 v[0:1], v[30:31], v[108:109], v[0:1]
	v_max_f32_e32 v210, 0, v222
	v_max_f32_e32 v211, 0, v223
	v_pk_fma_f32 v[0:1], v[32:33], v[210:211], v[0:1]
	v_mfma_f32_32x32x16_bf16 v[6:21], v[94:97], v[46:49], v[6:21]
	v_max_f32_e32 v108, 0, v224
	v_max_f32_e32 v109, 0, v225
	v_pk_fma_f32 v[0:1], v[34:35], v[108:109], v[0:1]
	v_max_f32_e32 v210, 0, v226
	v_max_f32_e32 v211, 0, v227
	v_pk_fma_f32 v[0:1], v[36:37], v[210:211], v[0:1]
	v_add_f32_e32 v0, v0, v1
	v_ashrrev_i32_e32 v1, 31, v0
	v_mfma_f32_32x32x16_bf16 v[6:21], v[98:101], v[196:199], v[6:21]
	s_waitcnt vmcnt(10)
	v_add_u32_e32 v228, 0x10000, v5
	ds_read_b128 v[38:41], v228 offset:43264
	v_add_u32_e32 v228, 0x10000, v52
	ds_read_b128 v[42:45], v228 offset:43264
	v_add_u32_e32 v228, 0x10000, v55
	ds_read_b128 v[46:49], v228 offset:43264
	v_add_u32_e32 v228, 0x10000, v56
	ds_read_b128 v[196:199], v228 offset:43264
	v_or_b32_e32 v1, 0x80000000, v1
	s_cmpk_gt_i32 s11, 464
	s_cselect_b64 vcc, -1, 0
	v_xor_b32_e32 v0, v1, v0
	v_cndmask_b32_e32 v192, v123, v0, vcc
	s_nop 3
	s_waitcnt lgkmcnt(3)
	v_mfma_f32_32x32x16_bf16 v[212:227], v[70:73], v[38:41], 0
	v_max_f32_e32 v108, 0, v6
	v_max_f32_e32 v109, 0, v7
	v_pk_mul_f32 v[50:51], v[244:245], v[108:109]
	v_max_f32_e32 v210, 0, v8
	v_max_f32_e32 v211, 0, v9
	v_pk_fma_f32 v[50:51], v[246:247], v[210:211], v[50:51]
	v_max_f32_e32 v108, 0, v10
	v_max_f32_e32 v109, 0, v11
	v_pk_fma_f32 v[50:51], v[248:249], v[108:109], v[50:51]
	s_waitcnt lgkmcnt(2)
	v_mfma_f32_32x32x16_bf16 v[212:227], v[74:77], v[42:45], v[212:227]
	v_max_f32_e32 v210, 0, v12
	v_max_f32_e32 v211, 0, v13
	v_pk_fma_f32 v[50:51], v[250:251], v[210:211], v[50:51]
	v_max_f32_e32 v108, 0, v14
	v_max_f32_e32 v109, 0, v15
	v_pk_fma_f32 v[50:51], v[252:253], v[108:109], v[50:51]
	v_max_f32_e32 v210, 0, v16
	v_max_f32_e32 v211, 0, v17
	v_pk_fma_f32 v[50:51], v[254:255], v[210:211], v[50:51]
	s_waitcnt lgkmcnt(1)
	v_mfma_f32_32x32x16_bf16 v[212:227], v[78:81], v[46:49], v[212:227]
	v_max_f32_e32 v108, 0, v18
	v_max_f32_e32 v109, 0, v19
	v_pk_fma_f32 v[50:51], v[200:201], v[108:109], v[50:51]
	v_max_f32_e32 v210, 0, v20
	v_max_f32_e32 v211, 0, v21
	v_pk_fma_f32 v[50:51], v[202:203], v[210:211], v[50:51]
	v_add_f32_e32 v50, v50, v51
	v_ashrrev_i32_e32 v51, 31, v50
	s_waitcnt lgkmcnt(0)
	v_mfma_f32_32x32x16_bf16 v[212:227], v[82:85], v[196:199], v[212:227]
	v_or_b32_e32 v51, 0x80000000, v51
	s_cmpk_gt_i32 s11, 464
	s_cselect_b64 vcc, -1, 0
	v_xor_b32_e32 v50, v51, v50
	v_cndmask_b32_e32 v50, v123, v50, vcc
	global_store_dword v243, v50, s[8:9]
	v_mfma_f32_32x32x16_bf16 v[6:21], v[86:89], v[38:41], 0
	s_add_i32 m0, s10, 65536
	s_nop 0
	global_load_lds_dwordx4 v102, s[6:7]
	s_add_i32 m0, s10, 66560
	s_nop 0
	global_load_lds_dwordx4 v110, s[6:7]
	s_add_i32 m0, s10, 67584
	s_nop 0
	global_load_lds_dwordx4 v112, s[6:7]
	s_add_i32 m0, s10, 68608
	s_nop 0
	global_load_lds_dwordx4 v193, s[6:7]
	s_add_u32 s6, s6, 0x8000
	s_addc_u32 s7, s7, 0
	v_max_f32_e32 v108, 0, v212
	v_max_f32_e32 v109, 0, v213
	v_pk_mul_f32 v[0:1], v[22:23], v[108:109]
	v_max_f32_e32 v210, 0, v214
	v_max_f32_e32 v211, 0, v215
	v_pk_fma_f32 v[0:1], v[24:25], v[210:211], v[0:1]
	v_max_f32_e32 v108, 0, v216
	v_max_f32_e32 v109, 0, v217
	v_pk_fma_f32 v[0:1], v[26:27], v[108:109], v[0:1]
	v_mfma_f32_32x32x16_bf16 v[6:21], v[90:93], v[42:45], v[6:21]
	v_max_f32_e32 v210, 0, v218
	v_max_f32_e32 v211, 0, v219
	v_pk_fma_f32 v[0:1], v[28:29], v[210:211], v[0:1]
	v_max_f32_e32 v108, 0, v220
	v_max_f32_e32 v109, 0, v221
	v_pk_fma_f32 v[0:1], v[30:31], v[108:109], v[0:1]
	v_max_f32_e32 v210, 0, v222
	v_max_f32_e32 v211, 0, v223
	v_pk_fma_f32 v[0:1], v[32:33], v[210:211], v[0:1]
	v_mfma_f32_32x32x16_bf16 v[6:21], v[94:97], v[46:49], v[6:21]
	v_max_f32_e32 v108, 0, v224
	v_max_f32_e32 v109, 0, v225
	v_pk_fma_f32 v[0:1], v[34:35], v[108:109], v[0:1]
	v_max_f32_e32 v210, 0, v226
	v_max_f32_e32 v211, 0, v227
	v_pk_fma_f32 v[0:1], v[36:37], v[210:211], v[0:1]
	v_add_f32_e32 v0, v0, v1
	v_ashrrev_i32_e32 v1, 31, v0
	v_mfma_f32_32x32x16_bf16 v[6:21], v[98:101], v[196:199], v[6:21]
	s_waitcnt vmcnt(10)
	ds_read_b128 v[38:41], v5 offset:10496
	ds_read_b128 v[42:45], v52 offset:10496
	ds_read_b128 v[46:49], v55 offset:10496
	ds_read_b128 v[196:199], v56 offset:10496
	v_or_b32_e32 v1, 0x80000000, v1
	s_cmpk_gt_i32 s11, 472
	s_cselect_b64 vcc, -1, 0
	v_xor_b32_e32 v0, v1, v0
	v_cndmask_b32_e32 v191, v123, v0, vcc
	s_nop 3
	s_waitcnt lgkmcnt(3)
	v_mfma_f32_32x32x16_bf16 v[212:227], v[70:73], v[38:41], 0
	v_max_f32_e32 v108, 0, v6
	v_max_f32_e32 v109, 0, v7
	v_pk_mul_f32 v[50:51], v[244:245], v[108:109]
	v_max_f32_e32 v210, 0, v8
	v_max_f32_e32 v211, 0, v9
	v_pk_fma_f32 v[50:51], v[246:247], v[210:211], v[50:51]
	v_max_f32_e32 v108, 0, v10
	v_max_f32_e32 v109, 0, v11
	v_pk_fma_f32 v[50:51], v[248:249], v[108:109], v[50:51]
	s_waitcnt lgkmcnt(2)
	v_mfma_f32_32x32x16_bf16 v[212:227], v[74:77], v[42:45], v[212:227]
	v_max_f32_e32 v210, 0, v12
	v_max_f32_e32 v211, 0, v13
	v_pk_fma_f32 v[50:51], v[250:251], v[210:211], v[50:51]
	v_max_f32_e32 v108, 0, v14
	v_max_f32_e32 v109, 0, v15
	v_pk_fma_f32 v[50:51], v[252:253], v[108:109], v[50:51]
	v_max_f32_e32 v210, 0, v16
	v_max_f32_e32 v211, 0, v17
	v_pk_fma_f32 v[50:51], v[254:255], v[210:211], v[50:51]
	s_waitcnt lgkmcnt(1)
	v_mfma_f32_32x32x16_bf16 v[212:227], v[78:81], v[46:49], v[212:227]
	v_max_f32_e32 v108, 0, v18
	v_max_f32_e32 v109, 0, v19
	v_pk_fma_f32 v[50:51], v[200:201], v[108:109], v[50:51]
	v_max_f32_e32 v210, 0, v20
	v_max_f32_e32 v211, 0, v21
	v_pk_fma_f32 v[50:51], v[202:203], v[210:211], v[50:51]
	v_add_f32_e32 v50, v50, v51
	v_ashrrev_i32_e32 v51, 31, v50
	s_waitcnt lgkmcnt(0)
	v_mfma_f32_32x32x16_bf16 v[212:227], v[82:85], v[196:199], v[212:227]
	v_or_b32_e32 v51, 0x80000000, v51
	s_cmpk_gt_i32 s11, 472
	s_cselect_b64 vcc, -1, 0
	v_xor_b32_e32 v50, v51, v50
	v_cndmask_b32_e32 v50, v123, v50, vcc
	global_store_dword v243, v50, s[8:9] offset:2048
	s_add_u32 s8, s8, 0x1000
	s_addc_u32 s9, s9, 0
	v_mfma_f32_32x32x16_bf16 v[6:21], v[86:89], v[38:41], 0
	s_add_i32 m0, s10, 98304
	s_nop 0
	global_load_lds_dwordx4 v102, s[6:7]
	s_add_i32 m0, s10, 99328
	s_nop 0
	global_load_lds_dwordx4 v110, s[6:7]
	s_add_i32 m0, s10, 100352
	s_nop 0
	global_load_lds_dwordx4 v112, s[6:7]
	s_add_i32 m0, s10, 101376
	s_nop 0
	global_load_lds_dwordx4 v193, s[6:7]
	s_add_u32 s6, s6, 0x8000
	s_addc_u32 s7, s7, 0
	v_max_f32_e32 v108, 0, v212
	v_max_f32_e32 v109, 0, v213
	v_pk_mul_f32 v[0:1], v[22:23], v[108:109]
	v_max_f32_e32 v210, 0, v214
	v_max_f32_e32 v211, 0, v215
	v_pk_fma_f32 v[0:1], v[24:25], v[210:211], v[0:1]
	v_max_f32_e32 v108, 0, v216
	v_max_f32_e32 v109, 0, v217
	v_pk_fma_f32 v[0:1], v[26:27], v[108:109], v[0:1]
	v_mfma_f32_32x32x16_bf16 v[6:21], v[90:93], v[42:45], v[6:21]
	v_max_f32_e32 v210, 0, v218
	v_max_f32_e32 v211, 0, v219
	v_pk_fma_f32 v[0:1], v[28:29], v[210:211], v[0:1]
	v_max_f32_e32 v108, 0, v220
	v_max_f32_e32 v109, 0, v221
	v_pk_fma_f32 v[0:1], v[30:31], v[108:109], v[0:1]
	v_max_f32_e32 v210, 0, v222
	v_max_f32_e32 v211, 0, v223
	v_pk_fma_f32 v[0:1], v[32:33], v[210:211], v[0:1]
	v_mfma_f32_32x32x16_bf16 v[6:21], v[94:97], v[46:49], v[6:21]
	v_max_f32_e32 v108, 0, v224
	v_max_f32_e32 v109, 0, v225
	v_pk_fma_f32 v[0:1], v[34:35], v[108:109], v[0:1]
	v_max_f32_e32 v210, 0, v226
	v_max_f32_e32 v211, 0, v227
	v_pk_fma_f32 v[0:1], v[36:37], v[210:211], v[0:1]
	v_add_f32_e32 v0, v0, v1
	v_ashrrev_i32_e32 v1, 31, v0
	v_mfma_f32_32x32x16_bf16 v[6:21], v[98:101], v[196:199], v[6:21]
	s_waitcnt vmcnt(10)
	ds_read_b128 v[38:41], v5 offset:43264
	ds_read_b128 v[42:45], v52 offset:43264
	ds_read_b128 v[46:49], v55 offset:43264
	ds_read_b128 v[196:199], v56 offset:43264
	v_or_b32_e32 v1, 0x80000000, v1
	s_cmpk_gt_i32 s11, 480
	s_cselect_b64 vcc, -1, 0
	v_xor_b32_e32 v0, v1, v0
	v_cndmask_b32_e32 v3, v123, v0, vcc
	s_nop 3
	s_waitcnt lgkmcnt(3)
	v_mfma_f32_32x32x16_bf16 v[212:227], v[70:73], v[38:41], 0
	v_max_f32_e32 v108, 0, v6
	v_max_f32_e32 v109, 0, v7
	v_pk_mul_f32 v[50:51], v[244:245], v[108:109]
	v_max_f32_e32 v210, 0, v8
	v_max_f32_e32 v211, 0, v9
	v_pk_fma_f32 v[50:51], v[246:247], v[210:211], v[50:51]
	v_max_f32_e32 v108, 0, v10
	v_max_f32_e32 v109, 0, v11
	v_pk_fma_f32 v[50:51], v[248:249], v[108:109], v[50:51]
	s_waitcnt lgkmcnt(2)
	v_mfma_f32_32x32x16_bf16 v[212:227], v[74:77], v[42:45], v[212:227]
	v_max_f32_e32 v210, 0, v12
	v_max_f32_e32 v211, 0, v13
	v_pk_fma_f32 v[50:51], v[250:251], v[210:211], v[50:51]
	v_max_f32_e32 v108, 0, v14
	v_max_f32_e32 v109, 0, v15
	v_pk_fma_f32 v[50:51], v[252:253], v[108:109], v[50:51]
	v_max_f32_e32 v210, 0, v16
	v_max_f32_e32 v211, 0, v17
	v_pk_fma_f32 v[50:51], v[254:255], v[210:211], v[50:51]
	s_waitcnt lgkmcnt(1)
	v_mfma_f32_32x32x16_bf16 v[212:227], v[78:81], v[46:49], v[212:227]
	v_max_f32_e32 v108, 0, v18
	v_max_f32_e32 v109, 0, v19
	v_pk_fma_f32 v[50:51], v[200:201], v[108:109], v[50:51]
	v_max_f32_e32 v210, 0, v20
	v_max_f32_e32 v211, 0, v21
	v_pk_fma_f32 v[50:51], v[202:203], v[210:211], v[50:51]
	v_add_f32_e32 v50, v50, v51
	v_ashrrev_i32_e32 v51, 31, v50
	s_waitcnt lgkmcnt(0)
	v_mfma_f32_32x32x16_bf16 v[212:227], v[82:85], v[196:199], v[212:227]
	v_or_b32_e32 v51, 0x80000000, v51
	s_cmpk_gt_i32 s11, 480
	s_cselect_b64 vcc, -1, 0
	v_xor_b32_e32 v50, v51, v50
	v_cndmask_b32_e32 v50, v123, v50, vcc
	global_store_dword v243, v50, s[8:9]
	v_mfma_f32_32x32x16_bf16 v[6:21], v[86:89], v[38:41], 0
	s_add_i32 m0, s10, 0
	s_nop 0
	global_load_lds_dwordx4 v102, s[6:7]
	s_add_i32 m0, s10, 1024
	s_nop 0
	global_load_lds_dwordx4 v110, s[6:7]
	s_add_i32 m0, s10, 2048
	s_nop 0
	global_load_lds_dwordx4 v112, s[6:7]
	s_add_i32 m0, s10, 3072
	s_nop 0
	global_load_lds_dwordx4 v193, s[6:7]
	s_add_u32 s6, s6, 0x8000
	s_addc_u32 s7, s7, 0
	v_max_f32_e32 v108, 0, v212
	v_max_f32_e32 v109, 0, v213
	v_pk_mul_f32 v[0:1], v[22:23], v[108:109]
	v_max_f32_e32 v210, 0, v214
	v_max_f32_e32 v211, 0, v215
	v_pk_fma_f32 v[0:1], v[24:25], v[210:211], v[0:1]
	v_max_f32_e32 v108, 0, v216
	v_max_f32_e32 v109, 0, v217
	v_pk_fma_f32 v[0:1], v[26:27], v[108:109], v[0:1]
	v_mfma_f32_32x32x16_bf16 v[6:21], v[90:93], v[42:45], v[6:21]
	v_max_f32_e32 v210, 0, v218
	v_max_f32_e32 v211, 0, v219
	v_pk_fma_f32 v[0:1], v[28:29], v[210:211], v[0:1]
	v_max_f32_e32 v108, 0, v220
	v_max_f32_e32 v109, 0, v221
	v_pk_fma_f32 v[0:1], v[30:31], v[108:109], v[0:1]
	v_max_f32_e32 v210, 0, v222
	v_max_f32_e32 v211, 0, v223
	v_pk_fma_f32 v[0:1], v[32:33], v[210:211], v[0:1]
	v_mfma_f32_32x32x16_bf16 v[6:21], v[94:97], v[46:49], v[6:21]
	v_max_f32_e32 v108, 0, v224
	v_max_f32_e32 v109, 0, v225
	v_pk_fma_f32 v[0:1], v[34:35], v[108:109], v[0:1]
	v_max_f32_e32 v210, 0, v226
	v_max_f32_e32 v211, 0, v227
	v_pk_fma_f32 v[0:1], v[36:37], v[210:211], v[0:1]
	v_add_f32_e32 v0, v0, v1
	v_ashrrev_i32_e32 v1, 31, v0
	v_mfma_f32_32x32x16_bf16 v[6:21], v[98:101], v[196:199], v[6:21]
	s_waitcnt vmcnt(10)
	v_add_u32_e32 v228, 0x10000, v5
	ds_read_b128 v[38:41], v228 offset:10496
	v_add_u32_e32 v228, 0x10000, v52
	ds_read_b128 v[42:45], v228 offset:10496
	v_add_u32_e32 v228, 0x10000, v55
	ds_read_b128 v[46:49], v228 offset:10496
	v_add_u32_e32 v228, 0x10000, v56
	ds_read_b128 v[196:199], v228 offset:10496
	v_or_b32_e32 v1, 0x80000000, v1
	s_cmpk_gt_i32 s11, 488
	s_cselect_b64 vcc, -1, 0
	v_xor_b32_e32 v0, v1, v0
	v_cndmask_b32_e32 v2, v123, v0, vcc
	s_nop 3
	s_waitcnt lgkmcnt(3)
	v_mfma_f32_32x32x16_bf16 v[212:227], v[70:73], v[38:41], 0
	v_max_f32_e32 v108, 0, v6
	v_max_f32_e32 v109, 0, v7
	v_pk_mul_f32 v[50:51], v[244:245], v[108:109]
	v_max_f32_e32 v210, 0, v8
	v_max_f32_e32 v211, 0, v9
	v_pk_fma_f32 v[50:51], v[246:247], v[210:211], v[50:51]
	v_max_f32_e32 v108, 0, v10
	v_max_f32_e32 v109, 0, v11
	v_pk_fma_f32 v[50:51], v[248:249], v[108:109], v[50:51]
	s_waitcnt lgkmcnt(2)
	v_mfma_f32_32x32x16_bf16 v[212:227], v[74:77], v[42:45], v[212:227]
	v_max_f32_e32 v210, 0, v12
	v_max_f32_e32 v211, 0, v13
	v_pk_fma_f32 v[50:51], v[250:251], v[210:211], v[50:51]
	v_max_f32_e32 v108, 0, v14
	v_max_f32_e32 v109, 0, v15
	v_pk_fma_f32 v[50:51], v[252:253], v[108:109], v[50:51]
	v_max_f32_e32 v210, 0, v16
	v_max_f32_e32 v211, 0, v17
	v_pk_fma_f32 v[50:51], v[254:255], v[210:211], v[50:51]
	s_waitcnt lgkmcnt(1)
	v_mfma_f32_32x32x16_bf16 v[212:227], v[78:81], v[46:49], v[212:227]
	v_max_f32_e32 v108, 0, v18
	v_max_f32_e32 v109, 0, v19
	v_pk_fma_f32 v[50:51], v[200:201], v[108:109], v[50:51]
	v_max_f32_e32 v210, 0, v20
	v_max_f32_e32 v211, 0, v21
	v_pk_fma_f32 v[50:51], v[202:203], v[210:211], v[50:51]
	v_add_f32_e32 v50, v50, v51
	v_ashrrev_i32_e32 v51, 31, v50
	s_waitcnt lgkmcnt(0)
	v_mfma_f32_32x32x16_bf16 v[212:227], v[82:85], v[196:199], v[212:227]
	v_or_b32_e32 v51, 0x80000000, v51
	s_cmpk_gt_i32 s11, 488
	s_cselect_b64 vcc, -1, 0
	v_xor_b32_e32 v50, v51, v50
	v_cndmask_b32_e32 v50, v123, v50, vcc
	global_store_dword v243, v50, s[8:9] offset:2048
	s_add_u32 s8, s8, 0x1000
	s_addc_u32 s9, s9, 0
	v_mfma_f32_32x32x16_bf16 v[6:21], v[86:89], v[38:41], 0
	s_add_i32 m0, s10, 32768
	s_nop 0
	global_load_lds_dwordx4 v102, s[6:7]
	s_add_i32 m0, s10, 33792
	s_nop 0
	global_load_lds_dwordx4 v110, s[6:7]
	s_add_i32 m0, s10, 34816
	s_nop 0
	global_load_lds_dwordx4 v112, s[6:7]
	s_add_i32 m0, s10, 35840
	s_nop 0
	global_load_lds_dwordx4 v193, s[6:7]
	s_add_u32 s6, s6, 0x8000
	s_addc_u32 s7, s7, 0
	v_max_f32_e32 v108, 0, v212
	v_max_f32_e32 v109, 0, v213
	v_pk_mul_f32 v[0:1], v[22:23], v[108:109]
	v_max_f32_e32 v210, 0, v214
	v_max_f32_e32 v211, 0, v215
	v_pk_fma_f32 v[0:1], v[24:25], v[210:211], v[0:1]
	v_max_f32_e32 v108, 0, v216
	v_max_f32_e32 v109, 0, v217
	v_pk_fma_f32 v[0:1], v[26:27], v[108:109], v[0:1]
	v_mfma_f32_32x32x16_bf16 v[6:21], v[90:93], v[42:45], v[6:21]
	v_max_f32_e32 v210, 0, v218
	v_max_f32_e32 v211, 0, v219
	v_pk_fma_f32 v[0:1], v[28:29], v[210:211], v[0:1]
	v_max_f32_e32 v108, 0, v220
	v_max_f32_e32 v109, 0, v221
	v_pk_fma_f32 v[0:1], v[30:31], v[108:109], v[0:1]
	v_max_f32_e32 v210, 0, v222
	v_max_f32_e32 v211, 0, v223
	v_pk_fma_f32 v[0:1], v[32:33], v[210:211], v[0:1]
	v_mfma_f32_32x32x16_bf16 v[6:21], v[94:97], v[46:49], v[6:21]
	v_max_f32_e32 v108, 0, v224
	v_max_f32_e32 v109, 0, v225
	v_pk_fma_f32 v[0:1], v[34:35], v[108:109], v[0:1]
	v_max_f32_e32 v210, 0, v226
	v_max_f32_e32 v211, 0, v227
	v_pk_fma_f32 v[0:1], v[36:37], v[210:211], v[0:1]
	v_add_f32_e32 v0, v0, v1
	v_ashrrev_i32_e32 v1, 31, v0
	v_mfma_f32_32x32x16_bf16 v[6:21], v[98:101], v[196:199], v[6:21]
	s_waitcnt vmcnt(10)
	v_add_u32_e32 v228, 0x10000, v5
	ds_read_b128 v[38:41], v228 offset:43264
	v_add_u32_e32 v228, 0x10000, v52
	ds_read_b128 v[42:45], v228 offset:43264
	v_add_u32_e32 v228, 0x10000, v55
	ds_read_b128 v[46:49], v228 offset:43264
	v_add_u32_e32 v228, 0x10000, v56
	ds_read_b128 v[196:199], v228 offset:43264
	v_or_b32_e32 v1, 0x80000000, v1
	s_cmpk_gt_i32 s11, 496
	s_cselect_b64 vcc, -1, 0
	v_xor_b32_e32 v0, v1, v0
	v_cndmask_b32_e32 v4, v123, v0, vcc
	s_nop 3
	s_waitcnt lgkmcnt(3)
	v_mfma_f32_32x32x16_bf16 v[212:227], v[70:73], v[38:41], 0
	v_max_f32_e32 v108, 0, v6
	v_max_f32_e32 v109, 0, v7
	v_pk_mul_f32 v[50:51], v[244:245], v[108:109]
	v_max_f32_e32 v210, 0, v8
	v_max_f32_e32 v211, 0, v9
	v_pk_fma_f32 v[50:51], v[246:247], v[210:211], v[50:51]
	v_max_f32_e32 v108, 0, v10
	v_max_f32_e32 v109, 0, v11
	v_pk_fma_f32 v[50:51], v[248:249], v[108:109], v[50:51]
	s_waitcnt lgkmcnt(2)
	v_mfma_f32_32x32x16_bf16 v[212:227], v[74:77], v[42:45], v[212:227]
	v_max_f32_e32 v210, 0, v12
	v_max_f32_e32 v211, 0, v13
	v_pk_fma_f32 v[50:51], v[250:251], v[210:211], v[50:51]
	v_max_f32_e32 v108, 0, v14
	v_max_f32_e32 v109, 0, v15
	v_pk_fma_f32 v[50:51], v[252:253], v[108:109], v[50:51]
	v_max_f32_e32 v210, 0, v16
	v_max_f32_e32 v211, 0, v17
	v_pk_fma_f32 v[50:51], v[254:255], v[210:211], v[50:51]
	s_waitcnt lgkmcnt(1)
	v_mfma_f32_32x32x16_bf16 v[212:227], v[78:81], v[46:49], v[212:227]
	v_max_f32_e32 v108, 0, v18
	v_max_f32_e32 v109, 0, v19
	v_pk_fma_f32 v[50:51], v[200:201], v[108:109], v[50:51]
	v_max_f32_e32 v210, 0, v20
	v_max_f32_e32 v211, 0, v21
	v_pk_fma_f32 v[50:51], v[202:203], v[210:211], v[50:51]
	v_add_f32_e32 v50, v50, v51
	v_ashrrev_i32_e32 v51, 31, v50
	s_waitcnt lgkmcnt(0)
	v_mfma_f32_32x32x16_bf16 v[212:227], v[82:85], v[196:199], v[212:227]
	v_or_b32_e32 v51, 0x80000000, v51
	s_cmpk_gt_i32 s11, 496
	s_cselect_b64 vcc, -1, 0
	v_xor_b32_e32 v50, v51, v50
	v_cndmask_b32_e32 v50, v123, v50, vcc
	global_store_dword v243, v50, s[8:9]
	v_mfma_f32_32x32x16_bf16 v[6:21], v[86:89], v[38:41], 0
	s_add_i32 m0, s10, 65536
	s_nop 0
	global_load_lds_dwordx4 v102, s[6:7]
	s_add_i32 m0, s10, 66560
	s_nop 0
	global_load_lds_dwordx4 v110, s[6:7]
	s_add_i32 m0, s10, 67584
	s_nop 0
	global_load_lds_dwordx4 v112, s[6:7]
	s_add_i32 m0, s10, 68608
	s_nop 0
	global_load_lds_dwordx4 v193, s[6:7]
	s_add_u32 s6, s6, 0x8000
	s_addc_u32 s7, s7, 0
	v_max_f32_e32 v108, 0, v212
	v_max_f32_e32 v109, 0, v213
	v_pk_mul_f32 v[0:1], v[22:23], v[108:109]
	v_max_f32_e32 v210, 0, v214
	v_max_f32_e32 v211, 0, v215
	v_pk_fma_f32 v[0:1], v[24:25], v[210:211], v[0:1]
	v_max_f32_e32 v108, 0, v216
	v_max_f32_e32 v109, 0, v217
	v_pk_fma_f32 v[0:1], v[26:27], v[108:109], v[0:1]
	v_mfma_f32_32x32x16_bf16 v[6:21], v[90:93], v[42:45], v[6:21]
	v_max_f32_e32 v210, 0, v218
	v_max_f32_e32 v211, 0, v219
	v_pk_fma_f32 v[0:1], v[28:29], v[210:211], v[0:1]
	v_max_f32_e32 v108, 0, v220
	v_max_f32_e32 v109, 0, v221
	v_pk_fma_f32 v[0:1], v[30:31], v[108:109], v[0:1]
	v_max_f32_e32 v210, 0, v222
	v_max_f32_e32 v211, 0, v223
	v_pk_fma_f32 v[0:1], v[32:33], v[210:211], v[0:1]
	v_mfma_f32_32x32x16_bf16 v[6:21], v[94:97], v[46:49], v[6:21]
	v_max_f32_e32 v108, 0, v224
	v_max_f32_e32 v109, 0, v225
	v_pk_fma_f32 v[0:1], v[34:35], v[108:109], v[0:1]
	v_max_f32_e32 v210, 0, v226
	v_max_f32_e32 v211, 0, v227
	v_pk_fma_f32 v[0:1], v[36:37], v[210:211], v[0:1]
	v_add_f32_e32 v0, v0, v1
	v_ashrrev_i32_e32 v1, 31, v0
	v_mfma_f32_32x32x16_bf16 v[6:21], v[98:101], v[196:199], v[6:21]
	s_waitcnt vmcnt(10)
	ds_read_b128 v[38:41], v5 offset:10496
	ds_read_b128 v[42:45], v52 offset:10496
	ds_read_b128 v[46:49], v55 offset:10496
	ds_read_b128 v[196:199], v56 offset:10496
	v_or_b32_e32 v1, 0x80000000, v1
	s_cmpk_gt_i32 s11, 504
	s_cselect_b64 vcc, -1, 0
	v_xor_b32_e32 v0, v1, v0
	v_cndmask_b32_e32 v185, v123, v0, vcc
	s_nop 3
	v_max_f32_e32 v108, 0, v6
	v_max_f32_e32 v109, 0, v7
	v_pk_mul_f32 v[50:51], v[244:245], v[108:109]
	v_max_f32_e32 v210, 0, v8
	v_max_f32_e32 v211, 0, v9
	v_pk_fma_f32 v[50:51], v[246:247], v[210:211], v[50:51]
	v_max_f32_e32 v108, 0, v10
	v_max_f32_e32 v109, 0, v11
	v_pk_fma_f32 v[50:51], v[248:249], v[108:109], v[50:51]
	v_max_f32_e32 v210, 0, v12
	v_max_f32_e32 v211, 0, v13
	v_pk_fma_f32 v[50:51], v[250:251], v[210:211], v[50:51]
	v_max_f32_e32 v108, 0, v14
	v_max_f32_e32 v109, 0, v15
	v_pk_fma_f32 v[50:51], v[252:253], v[108:109], v[50:51]
	v_max_f32_e32 v210, 0, v16
	v_max_f32_e32 v211, 0, v17
	v_pk_fma_f32 v[50:51], v[254:255], v[210:211], v[50:51]
	v_max_f32_e32 v108, 0, v18
	v_max_f32_e32 v109, 0, v19
	v_pk_fma_f32 v[50:51], v[200:201], v[108:109], v[50:51]
	v_max_f32_e32 v210, 0, v20
	v_max_f32_e32 v211, 0, v21
	v_pk_fma_f32 v[50:51], v[202:203], v[210:211], v[50:51]
	v_add_f32_e32 v50, v50, v51
	v_ashrrev_i32_e32 v51, 31, v50
	v_or_b32_e32 v51, 0x80000000, v51
	s_cmpk_gt_i32 s11, 504
	s_cselect_b64 vcc, -1, 0
	v_xor_b32_e32 v50, v51, v50
	v_cndmask_b32_e32 v50, v123, v50, vcc
	global_store_dword v243, v50, s[8:9] offset:2048
	s_add_u32 s8, s8, 0x1000
	s_addc_u32 s9, s9, 0
	s_branch .Lix_done
.Ltramp_fwd:
	s_branch .Ltc_entry
.Ltramp_ret2:
	s_branch .Ldef_2_ret
.Ltramp_ret3:
	s_branch .Ldef_3_ret
.Lix_fill_1:
	v_mov_b32_e32 v142, v123
	v_mov_b32_e32 v141, v123
	v_mov_b32_e32 v144, v123
	v_mov_b32_e32 v143, v123
	v_mov_b32_e32 v146, v123
	v_mov_b32_e32 v145, v123
	v_mov_b32_e32 v147, v123
	v_mov_b32_e32 v136, v123

.LBB0_1630:
	s_waitcnt vmcnt(0)
	s_barrier
	s_cmpk_lg_i32 s22, 0x100
	s_cbranch_scc1 .Ldef_2_skip
	s_cmpk_lt_u32 s2, 16
	s_cbranch_scc1 .Ldef_2_skip
	v_readlane_b32 s4, v242, 0
	v_readlane_b32 s5, v242, 1
	s_sub_u32 s4, s4, 0xe0
	s_subb_u32 s5, s5, 0
	s_load_dwordx2 s[50:51], s[4:5], 0xb8
	s_waitcnt lgkmcnt(0)
	s_mov_b32 s100, s2
	s_mov_b32 s101, s22
	s_sub_i32 s2, s2, 16
	s_addk_i32 s2, 7040
	s_movk_i32 s22, 240
	s_movk_i32 s98, 11135
	s_mov_b32 s99, 2
	s_branch .Ltramp_fwd
.Ldef_2_ret:
	s_mov_b32 s2, s100
	s_mov_b32 s22, s101
	s_mov_b32 s99, 0
.Ldef_2_skip:
.LBB0_1631:
	s_cmp_gt_i32 s31, 4
	s_cselect_b64 s[4:5], -1, 0
	s_and_b64 s[0:1], s[0:1], s[4:5]
	s_andn2_b64 vcc, exec, s[0:1]
	s_cbranch_vccnz .LBB0_1685
	s_getreg_b32 s3, hwreg(HW_REG_XCC_ID, 0, 4)
	s_waitcnt vmcnt(0)
	s_waitcnt vmcnt(0) lgkmcnt(0)
	s_barrier
	s_mov_b64 s[0:1], exec
	v_readlane_b32 s6, v242, 2
	v_readlane_b32 s7, v242, 3
	s_and_b64 s[6:7], s[0:1], s[6:7]
	s_mov_b64 exec, s[6:7]
	s_cbranch_execz .LBB0_1684
	s_add_i32 s6, 0, 0x23fc0
	v_mov_b32_e32 v0, s6
	s_waitcnt vmcnt(0) expcnt(0) lgkmcnt(0)
	ds_read_b32 v2, v0
	s_add_i32 s6, 0, 0x23fc4
	v_mov_b32_e32 v0, s6
	ds_read_b32 v0, v0
	s_and_b32 s3, s3, 15
	s_waitcnt lgkmcnt(1)
	v_cmp_ne_u32_e32 vcc, 0, v2
	s_cbranch_vccnz .LBB0_1648
	v_readlane_b32 s6, v242, 0
	v_readlane_b32 s7, v242, 1
	s_load_dwordx2 s[10:11], s[6:7], 0x4
	s_add_u32 s6, s28, 0x1d418200
	s_addc_u32 s7, s29, 0
	s_add_u32 s8, s28, 0x1d418400
	s_addc_u32 s9, s29, 0
	s_waitcnt lgkmcnt(0)
	s_mul_i32 s23, s10, s22
	s_add_u32 s10, s28, 0x1d418500
	s_mul_i32 s23, s23, s11
	s_addc_u32 s11, s29, 0
	s_add_u32 s12, s28, 0x1d418600
	s_addc_u32 s13, s29, 0
	s_add_u32 s14, s28, 0x1d418700
	s_addc_u32 s15, s29, 0
	s_add_u32 s16, s28, 0x1d418800
	s_addc_u32 s17, s29, 0
	s_add_u32 s18, s28, 0x1d418900
	s_addc_u32 s19, s29, 0
	s_add_u32 s20, s28, 0x1d418a00
	s_addc_u32 s21, s29, 0
	s_add_u32 s24, s28, 0x1d418b00
	s_addc_u32 s25, s29, 0
	s_add_u32 s34, s28, 0x1d418c00
	s_addc_u32 s35, s29, 0
	s_add_u32 s36, s28, 0x1d418d00
	s_addc_u32 s37, s29, 0
	s_add_u32 s38, s28, 0x1d418e00
	s_addc_u32 s39, s29, 0
	s_add_u32 s40, s28, 0x1d418f00
	s_addc_u32 s41, s29, 0
	s_add_u32 s42, s28, 0x1d419000
	s_addc_u32 s43, s29, 0
	s_add_u32 s44, s28, 0x1d419100
	s_addc_u32 s45, s29, 0
	s_add_u32 s46, s28, 0x1d419200
	s_addc_u32 s47, s29, 0
	s_add_u32 s50, s28, 0x1d419300
	s_addc_u32 s51, s29, 0
	s_mov_b32 s33, 1
	v_mov_b32_e32 v16, 0
	s_branch .LBB0_1636

.LBB0_1735:
	s_waitcnt vmcnt(0)
	s_barrier
	s_cmpk_lg_i32 s22, 0x100
	s_cbranch_scc1 .Ldef_3_skip
	s_cmpk_lt_u32 s2, 16
	s_cbranch_scc1 .Ldef_3_skip
	v_readlane_b32 s4, v242, 0
	v_readlane_b32 s5, v242, 1
	s_sub_u32 s4, s4, 0xe0
	s_subb_u32 s5, s5, 0
	v_writelane_b32 v255, s24, 6
	v_writelane_b32 v255, s25, 7
	s_load_dwordx2 s[24:25], s[4:5], 0xc0
	s_waitcnt lgkmcnt(0)
	s_mov_b32 s100, s2
	s_mov_b32 s101, s22
	s_sub_i32 s2, s2, 16
	s_addk_i32 s2, 11136
	s_movk_i32 s22, 240
	s_movk_i32 s98, 15231
	s_mov_b32 s99, 3
	s_branch .Ltramp_fwd
.Ldef_3_ret:
	s_mov_b32 s2, s100
	s_mov_b32 s22, s101
	s_mov_b32 s99, 0
	s_nop 0
	v_readlane_b32 s24, v255, 6
	v_readlane_b32 s25, v255, 7
.Ldef_3_skip:
.LBB0_1736:
	s_cmp_gt_i32 s31, 5
	s_cselect_b64 s[4:5], -1, 0
	s_and_b64 s[0:1], s[0:1], s[4:5]
	s_andn2_b64 vcc, exec, s[0:1]
	s_cbranch_vccnz .LBB0_1790
	s_getreg_b32 s3, hwreg(HW_REG_XCC_ID, 0, 4)
	s_waitcnt vmcnt(0)
	s_waitcnt vmcnt(0) lgkmcnt(0)
	s_barrier
	s_mov_b64 s[0:1], exec
	v_readlane_b32 s6, v242, 2
	v_readlane_b32 s7, v242, 3
	s_and_b64 s[6:7], s[0:1], s[6:7]
	s_mov_b64 exec, s[6:7]
	s_cbranch_execz .LBB0_1789
	s_add_i32 s6, 0, 0x23fc0
	v_mov_b32_e32 v0, s6
	s_waitcnt vmcnt(0) expcnt(0) lgkmcnt(0)
	ds_read_b32 v2, v0
	s_add_i32 s6, 0, 0x23fc4
	v_mov_b32_e32 v0, s6
	ds_read_b32 v0, v0
	s_and_b32 s3, s3, 15
	s_waitcnt lgkmcnt(1)
	v_cmp_ne_u32_e32 vcc, 0, v2
	s_cbranch_vccnz .LBB0_1753
	v_readlane_b32 s6, v242, 0
	v_readlane_b32 s7, v242, 1
	s_load_dwordx2 s[10:11], s[6:7], 0x4
	s_add_u32 s6, s28, 0x1d418200
	s_addc_u32 s7, s29, 0
	s_add_u32 s8, s28, 0x1d418400
	s_addc_u32 s9, s29, 0
	s_waitcnt lgkmcnt(0)
	s_mul_i32 s23, s10, s22
	s_add_u32 s10, s28, 0x1d418500
	s_mul_i32 s23, s23, s11
	s_addc_u32 s11, s29, 0
	s_add_u32 s12, s28, 0x1d418600
	s_addc_u32 s13, s29, 0
	s_add_u32 s14, s28, 0x1d418700
	s_addc_u32 s15, s29, 0
	s_add_u32 s16, s28, 0x1d418800
	s_addc_u32 s17, s29, 0
	s_add_u32 s18, s28, 0x1d418900
	s_addc_u32 s19, s29, 0
	s_add_u32 s20, s28, 0x1d418a00
	s_addc_u32 s21, s29, 0
	s_add_u32 s24, s28, 0x1d418b00
	s_addc_u32 s25, s29, 0
	s_add_u32 s34, s28, 0x1d418c00
	s_addc_u32 s35, s29, 0
	s_add_u32 s36, s28, 0x1d418d00
	s_addc_u32 s37, s29, 0
	s_add_u32 s38, s28, 0x1d418e00
	s_addc_u32 s39, s29, 0
	s_add_u32 s40, s28, 0x1d418f00
	s_addc_u32 s41, s29, 0
	s_add_u32 s42, s28, 0x1d419000
	s_addc_u32 s43, s29, 0
	s_add_u32 s44, s28, 0x1d419100
	s_addc_u32 s45, s29, 0
	s_add_u32 s46, s28, 0x1d419200
	s_addc_u32 s47, s29, 0
	s_add_u32 s50, s28, 0x1d419300
	s_addc_u32 s51, s29, 0
	s_mov_b32 s33, 1
	v_mov_b32_e32 v16, 0
	s_branch .LBB0_1741

	.amdhsa_kernel _Z8mega_fwd6Params
		.amdhsa_group_segment_fixed_size 0
		.amdhsa_private_segment_fixed_size 0
		.amdhsa_kernarg_size 480
		.amdhsa_user_sgpr_count 2
		.amdhsa_user_sgpr_dispatch_ptr 0
		.amdhsa_user_sgpr_queue_ptr 0
		.amdhsa_user_sgpr_kernarg_segment_ptr 1
		.amdhsa_user_sgpr_dispatch_id 0
		.amdhsa_user_sgpr_kernarg_preload_length 0
		.amdhsa_user_sgpr_kernarg_preload_offset 0
		.amdhsa_user_sgpr_private_segment_size 0
		.amdhsa_uses_dynamic_stack 0
		.amdhsa_enable_private_segment 0
		.amdhsa_system_sgpr_workgroup_id_x 1
		.amdhsa_system_sgpr_workgroup_id_y 0
		.amdhsa_system_sgpr_workgroup_id_z 0
		.amdhsa_system_sgpr_workgroup_info 0
		.amdhsa_system_vgpr_workitem_id 2
		.amdhsa_next_free_vgpr 256
		.amdhsa_next_free_sgpr 102
		.amdhsa_accum_offset 256
		.amdhsa_reserve_vcc 1
		.amdhsa_float_round_mode_32 0
		.amdhsa_float_round_mode_16_64 0
		.amdhsa_float_denorm_mode_32 3
		.amdhsa_float_denorm_mode_16_64 3
		.amdhsa_dx10_clamp 1
		.amdhsa_ieee_mode 1
		.amdhsa_fp16_overflow 0
		.amdhsa_tg_split 0
		.amdhsa_exception_fp_ieee_invalid_op 0
		.amdhsa_exception_fp_denorm_src 0
		.amdhsa_exception_fp_ieee_div_zero 0
		.amdhsa_exception_fp_ieee_overflow 0
		.amdhsa_exception_fp_ieee_underflow 0
		.amdhsa_exception_fp_ieee_inexact 0
		.amdhsa_exception_int_div_zero 0
	.end_amdhsa_kernel

amdhsa.kernels:
  - .agpr_count:     0
    .args:
      - .offset:         0
        .size:           224
        .value_kind:     by_value
      - .offset:         224
        .size:           4
        .value_kind:     hidden_block_count_x
      - .offset:         228
        .size:           4
        .value_kind:     hidden_block_count_y
      - .offset:         232
        .size:           4
        .value_kind:     hidden_block_count_z
      - .offset:         236
        .size:           2
        .value_kind:     hidden_group_size_x
      - .offset:         238
        .size:           2
        .value_kind:     hidden_group_size_y
      - .offset:         240
        .size:           2
        .value_kind:     hidden_group_size_z
      - .offset:         242
        .size:           2
        .value_kind:     hidden_remainder_x
      - .offset:         244
        .size:           2
        .value_kind:     hidden_remainder_y
      - .offset:         246
        .size:           2
        .value_kind:     hidden_remainder_z
      - .offset:         264
        .size:           8
        .value_kind:     hidden_global_offset_x
      - .offset:         272
        .size:           8
        .value_kind:     hidden_global_offset_y
      - .offset:         280
        .size:           8
        .value_kind:     hidden_global_offset_z
      - .offset:         288
        .size:           2
        .value_kind:     hidden_grid_dims
      - .offset:         312
        .size:           8
        .value_kind:     hidden_multigrid_sync_arg
      - .offset:         344
        .size:           4
        .value_kind:     hidden_dynamic_lds_size
    .group_segment_fixed_size: 0
    .kernarg_segment_align: 8
    .kernarg_segment_size: 480
    .language:       OpenCL C
    .language_version:
      - 2
      - 0
    .max_flat_workgroup_size: 512
    .name:           _Z8mega_fwd6Params
    .private_segment_fixed_size: 0
    .sgpr_count:     108
    .sgpr_spill_count: 52
    .symbol:         _Z8mega_fwd6Params.kd
    .uniform_work_group_size: 1
    .uses_dynamic_stack: false
    .vgpr_count:     256
    .vgpr_spill_count: 0
    .wavefront_size: 64
